# filter_gen: a3 stored transposed by filter_mlp, coalesced dword loads with rolling 64-load prefetch, 4x unrolled; natten V via ds_read_b64_tr_b16
# speedup vs baseline: 1.0206x; 1.0186x over previous
; __device__ void ph_filter_mlp(const Params& P, int j, float* __restrict__ a3) {
;     ...
;         a = sinf(fq * acc);
;         acc = b3[lane];
;         for (int i = 0; i < 64; ++i) acc += __shfl(a, i) * w3[i * 64 + lane];
;         a = sinf(fq * acc);
;         a3[pos * 64 + lane] = a;
.LBB0_44:
	s_or_b64 exec, exec, s[10:11]
	v_mul_f32_e32 v19, v18, v18
	v_fmamk_f32 v20, v19, 0xb94c1982, v227
	v_fmaak_f32 v20, v19, v20, 0xbe2aaa9d
	v_mul_f32_e32 v20, v19, v20
	v_fmac_f32_e32 v18, v18, v20
	v_fmamk_f32 v20, v19, 0x37d75334, v228
	v_fmaak_f32 v20, v19, v20, 0x3d2aabf7
	v_fmaak_f32 v20, v19, v20, 0xbf000004
	v_fma_f32 v19, v19, v20, 1.0
	v_and_b32_e32 v20, 1, v17
	v_lshlrev_b32_e32 v17, 30, v17
	v_cmp_eq_u32_e32 vcc, 0, v20
	v_and_b32_e32 v17, 0x80000000, v17
	v_xor_b32_e32 v7, v7, v6
	v_cndmask_b32_e32 v18, v19, v18, vcc
	v_xor_b32_e32 v7, v7, v17
	v_xor_b32_e32 v7, v7, v18
	v_cmp_class_f32_e64 vcc, v6, s14
	v_lshl_or_b32 v6, v9, 12, v8
	v_readlane_b32 s0, v252, 50
	v_add_u32_e32 v8, s12, v8
	v_cndmask_b32_e32 v17, v243, v7, vcc
	v_ashrrev_i32_e32 v7, 31, v6
	v_readlane_b32 s1, v252, 51
	v_cmp_lt_i32_e32 vcc, s9, v8
	s_or_b64 s[52:53], vcc, s[52:53]
	v_lshl_add_u64 v[6:7], v[6:7], 2, s[0:1]
	global_store_dword v[6:7], v17, off
	s_andn2_b64 exec, exec, s[52:53]
	s_cbranch_execz .LBB0_81

; __device__ void ph_filter_gen(const Params& P, int j, const float* __restrict__ a3, float* __restrict__ kf, float* sl) {
;     ...
;         if (tid < 256) { const int jj = tid >> 2, q = tid & 3; sw[tid] = w4[(size_t)jj * 4096 + q * 1024 + c]; }
;         __syncthreads();
;         const float delta = fabsf(min_decay + (float)c * ((max_decay - min_decay) / 1023.0f));
;         float hv[8][4]; float n0 = 0.f, n1 = 0.f;
; #pragma unroll
;         for (int i = 0; i < 8; ++i) { const int t = tid + NT * i; const float4* ar = (const float4*)(a3 + (size_t)t * 64);
;             float a0 = 0.f, a1 = 0.f, a2 = 0.f, a3v = 0.f;
; #pragma unroll 4
;             for (int jq = 0; jq < 16; ++jq) { const float4 av = ar[jq]; const float ae[4] = {av.x, av.y, av.z, av.w};
; #pragma unroll
;                 for (int e = 0; e < 4; ++e) { const float4 wv = *(const float4*)(sw + (jq * 4 + e) * 4); a0 += ae[e] * wv.x; a1 += ae[e] * wv.y; a2 += ae[e] * wv.z; a3v += ae[e] * wv.w; } }
.LBB0_220:
	s_or_b64 exec, exec, s[10:11]
	v_mov_b32_e32 v38, 0
	s_mov_b32 s0, 0
	s_mov_b64 s[14:15], 0
	v_mov_b32_e32 v39, v38
	v_mov_b32_e32 v36, v38
	v_mov_b32_e32 v37, v38
	s_waitcnt lgkmcnt(0)
	s_barrier
	v_mov_b32_e32 v113, v68
	s_add_u32 s100, s78, 0x1e800000
	s_addc_u32 s101, s79, 0
	global_load_dword v116, v113, s[100:101]
	s_add_u32 s100, s100, 0x4000
	s_addc_u32 s101, s101, 0
	global_load_dword v117, v113, s[100:101]
	s_add_u32 s100, s100, 0x4000
	s_addc_u32 s101, s101, 0
	global_load_dword v118, v113, s[100:101]
	s_add_u32 s100, s100, 0x4000
	s_addc_u32 s101, s101, 0
	global_load_dword v119, v113, s[100:101]
	s_add_u32 s100, s100, 0x4000
	s_addc_u32 s101, s101, 0
	global_load_dword v120, v113, s[100:101]
	s_add_u32 s100, s100, 0x4000
	s_addc_u32 s101, s101, 0
	global_load_dword v121, v113, s[100:101]
	s_add_u32 s100, s100, 0x4000
	s_addc_u32 s101, s101, 0
	global_load_dword v122, v113, s[100:101]
	s_add_u32 s100, s100, 0x4000
	s_addc_u32 s101, s101, 0
	global_load_dword v123, v113, s[100:101]
	s_add_u32 s100, s100, 0x4000
	s_addc_u32 s101, s101, 0
	global_load_dword v124, v113, s[100:101]
	s_add_u32 s100, s100, 0x4000
	s_addc_u32 s101, s101, 0
	global_load_dword v125, v113, s[100:101]
	s_add_u32 s100, s100, 0x4000
	s_addc_u32 s101, s101, 0
	global_load_dword v126, v113, s[100:101]
	s_add_u32 s100, s100, 0x4000
	s_addc_u32 s101, s101, 0
	global_load_dword v127, v113, s[100:101]
	s_add_u32 s100, s100, 0x4000
	s_addc_u32 s101, s101, 0
	global_load_dword v128, v113, s[100:101]
	s_add_u32 s100, s100, 0x4000
	s_addc_u32 s101, s101, 0
	global_load_dword v129, v113, s[100:101]
	s_add_u32 s100, s100, 0x4000
	s_addc_u32 s101, s101, 0
	global_load_dword v130, v113, s[100:101]
	s_add_u32 s100, s100, 0x4000
	s_addc_u32 s101, s101, 0
	global_load_dword v131, v113, s[100:101]
	s_add_u32 s100, s78, 0x1e840000
	s_addc_u32 s101, s79, 0
	global_load_dword v132, v113, s[100:101]
	s_add_u32 s100, s100, 0x4000
	s_addc_u32 s101, s101, 0
	global_load_dword v133, v113, s[100:101]
	s_add_u32 s100, s100, 0x4000
	s_addc_u32 s101, s101, 0
	global_load_dword v134, v113, s[100:101]
	s_add_u32 s100, s100, 0x4000
	s_addc_u32 s101, s101, 0
	global_load_dword v135, v113, s[100:101]
	s_add_u32 s100, s100, 0x4000
	s_addc_u32 s101, s101, 0
	global_load_dword v136, v113, s[100:101]
	s_add_u32 s100, s100, 0x4000
	s_addc_u32 s101, s101, 0
	global_load_dword v137, v113, s[100:101]
	s_add_u32 s100, s100, 0x4000
	s_addc_u32 s101, s101, 0
	global_load_dword v138, v113, s[100:101]
	s_add_u32 s100, s100, 0x4000
	s_addc_u32 s101, s101, 0
	global_load_dword v139, v113, s[100:101]
	s_add_u32 s100, s100, 0x4000
	s_addc_u32 s101, s101, 0
	global_load_dword v140, v113, s[100:101]
	s_add_u32 s100, s100, 0x4000
	s_addc_u32 s101, s101, 0
	global_load_dword v141, v113, s[100:101]
	s_add_u32 s100, s100, 0x4000
	s_addc_u32 s101, s101, 0
	global_load_dword v142, v113, s[100:101]
	s_add_u32 s100, s100, 0x4000
	s_addc_u32 s101, s101, 0
	global_load_dword v143, v113, s[100:101]
	s_add_u32 s100, s100, 0x4000
	s_addc_u32 s101, s101, 0
	global_load_dword v144, v113, s[100:101]
	s_add_u32 s100, s100, 0x4000
	s_addc_u32 s101, s101, 0
	global_load_dword v145, v113, s[100:101]
	s_add_u32 s100, s100, 0x4000
	s_addc_u32 s101, s101, 0
	global_load_dword v146, v113, s[100:101]
	s_add_u32 s100, s100, 0x4000
	s_addc_u32 s101, s101, 0
	global_load_dword v147, v113, s[100:101]
	s_add_u32 s100, s78, 0x1e880000
	s_addc_u32 s101, s79, 0
	global_load_dword v148, v113, s[100:101]
	s_add_u32 s100, s100, 0x4000
	s_addc_u32 s101, s101, 0
	global_load_dword v149, v113, s[100:101]
	s_add_u32 s100, s100, 0x4000
	s_addc_u32 s101, s101, 0
	global_load_dword v150, v113, s[100:101]
	s_add_u32 s100, s100, 0x4000
	s_addc_u32 s101, s101, 0
	global_load_dword v151, v113, s[100:101]
	s_add_u32 s100, s100, 0x4000
	s_addc_u32 s101, s101, 0
	global_load_dword v152, v113, s[100:101]
	s_add_u32 s100, s100, 0x4000
	s_addc_u32 s101, s101, 0
	global_load_dword v153, v113, s[100:101]
	s_add_u32 s100, s100, 0x4000
	s_addc_u32 s101, s101, 0
	global_load_dword v154, v113, s[100:101]
	s_add_u32 s100, s100, 0x4000
	s_addc_u32 s101, s101, 0
	global_load_dword v155, v113, s[100:101]
	s_add_u32 s100, s100, 0x4000
	s_addc_u32 s101, s101, 0
	global_load_dword v156, v113, s[100:101]
	s_add_u32 s100, s100, 0x4000
	s_addc_u32 s101, s101, 0
	global_load_dword v157, v113, s[100:101]
	s_add_u32 s100, s100, 0x4000
	s_addc_u32 s101, s101, 0
	global_load_dword v158, v113, s[100:101]
	s_add_u32 s100, s100, 0x4000
	s_addc_u32 s101, s101, 0
	global_load_dword v159, v113, s[100:101]
	s_add_u32 s100, s100, 0x4000
	s_addc_u32 s101, s101, 0
	global_load_dword v160, v113, s[100:101]
	s_add_u32 s100, s100, 0x4000
	s_addc_u32 s101, s101, 0
	global_load_dword v161, v113, s[100:101]
	s_add_u32 s100, s100, 0x4000
	s_addc_u32 s101, s101, 0
	global_load_dword v162, v113, s[100:101]
	s_add_u32 s100, s100, 0x4000
	s_addc_u32 s101, s101, 0
	global_load_dword v163, v113, s[100:101]
	s_add_u32 s100, s78, 0x1e8c0000
	s_addc_u32 s101, s79, 0
	global_load_dword v164, v113, s[100:101]
	s_add_u32 s100, s100, 0x4000
	s_addc_u32 s101, s101, 0
	global_load_dword v165, v113, s[100:101]
	s_add_u32 s100, s100, 0x4000
	s_addc_u32 s101, s101, 0
	global_load_dword v166, v113, s[100:101]
	s_add_u32 s100, s100, 0x4000
	s_addc_u32 s101, s101, 0
	global_load_dword v167, v113, s[100:101]
	s_add_u32 s100, s100, 0x4000
	s_addc_u32 s101, s101, 0
	global_load_dword v168, v113, s[100:101]
	s_add_u32 s100, s100, 0x4000
	s_addc_u32 s101, s101, 0
	global_load_dword v169, v113, s[100:101]
	s_add_u32 s100, s100, 0x4000
	s_addc_u32 s101, s101, 0
	global_load_dword v170, v113, s[100:101]
	s_add_u32 s100, s100, 0x4000
	s_addc_u32 s101, s101, 0
	global_load_dword v171, v113, s[100:101]
	s_add_u32 s100, s100, 0x4000
	s_addc_u32 s101, s101, 0
	global_load_dword v172, v113, s[100:101]
	s_add_u32 s100, s100, 0x4000
	s_addc_u32 s101, s101, 0
	global_load_dword v173, v113, s[100:101]
	s_add_u32 s100, s100, 0x4000
	s_addc_u32 s101, s101, 0
	global_load_dword v174, v113, s[100:101]
	s_add_u32 s100, s100, 0x4000
	s_addc_u32 s101, s101, 0
	global_load_dword v175, v113, s[100:101]
	s_add_u32 s100, s100, 0x4000
	s_addc_u32 s101, s101, 0
	global_load_dword v176, v113, s[100:101]
	s_add_u32 s100, s100, 0x4000
	s_addc_u32 s101, s101, 0
	global_load_dword v177, v113, s[100:101]
	s_add_u32 s100, s100, 0x4000
	s_addc_u32 s101, s101, 0
	global_load_dword v178, v113, s[100:101]
	s_add_u32 s100, s100, 0x4000
	s_addc_u32 s101, s101, 0
	global_load_dword v179, v113, s[100:101]
; __device__ void ph_filter_gen(const Params& P, int j, const float* __restrict__ a3, float* __restrict__ kf, float* sl) {
;     ...
;         for (int i = 0; i < 8; ++i) { const int t = tid + NT * i; const float4* ar = (const float4*)(a3 + (size_t)t * 64);
;             float a0 = 0.f, a1 = 0.f, a2 = 0.f, a3v = 0.f;
; #pragma unroll 4
;             for (int jq = 0; jq < 16; ++jq) { const float4 av = ar[jq]; const float ae[4] = {av.x, av.y, av.z, av.w};
; #pragma unroll
;                 for (int e = 0; e < 4; ++e) { const float4 wv = *(const float4*)(sw + (jq * 4 + e) * 4); a0 += ae[e] * wv.x; a1 += ae[e] * wv.y; a2 += ae[e] * wv.z; a3v += ae[e] * wv.w; } }
;             const float dec = expf(-((float)t / (float)(SEQ - 1)) * delta);
;             hv[i][0] = a0 * dec; hv[i][1] = a1 * dec; hv[i][2] = a2 * dec; hv[i][3] = a3v * dec;
.LBB0_221:
	v_add_u32_e32 v113, 0x800, v68
	s_waitcnt vmcnt(48)
	v_mov_b32_e32 v82, 0
	ds_read_b128 v[56:59], v82
	ds_read_b128 v[60:63], v82 offset:16
	ds_read_b128 v[64:67], v82 offset:32
	ds_read_b128 v[78:81], v82 offset:48
	s_waitcnt lgkmcnt(3)
	v_pk_fma_f32 v[38:39], v[116:117], v[56:57], v[38:39] op_sel_hi:[0,1,1]
	v_pk_fma_f32 v[36:37], v[116:117], v[58:59], v[36:37] op_sel_hi:[0,1,1]
	s_waitcnt lgkmcnt(2)
	v_pk_fma_f32 v[38:39], v[116:117], v[60:61], v[38:39] op_sel:[1,0,0]
	v_pk_fma_f32 v[36:37], v[116:117], v[62:63], v[36:37] op_sel:[1,0,0]
	s_waitcnt lgkmcnt(1)
	v_pk_fma_f32 v[38:39], v[118:119], v[64:65], v[38:39] op_sel_hi:[0,1,1]
	v_mov_b32_e32 v56, v119
	v_pk_fma_f32 v[36:37], v[118:119], v[66:67], v[36:37] op_sel_hi:[0,1,1]
	s_waitcnt lgkmcnt(0)
	v_pk_fma_f32 v[60:61], v[56:57], v[78:79], v[38:39] op_sel_hi:[0,1,1]
	v_pk_fma_f32 v[64:65], v[56:57], v[80:81], v[36:37] op_sel_hi:[0,1,1]
	ds_read_b128 v[36:39], v82 offset:64
	ds_read_b128 v[40:43], v82 offset:80
	ds_read_b128 v[56:59], v82 offset:96
	s_waitcnt lgkmcnt(2)
	v_pk_fma_f32 v[36:37], v[120:121], v[36:37], v[60:61] op_sel_hi:[0,1,1]
	ds_read_b128 v[60:63], v82 offset:112
	s_waitcnt lgkmcnt(2)
	v_pk_fma_f32 v[36:37], v[120:121], v[40:41], v[36:37] op_sel:[1,0,0]
	v_mov_b32_e32 v40, v123
	s_waitcnt lgkmcnt(1)
	v_pk_fma_f32 v[36:37], v[122:123], v[56:57], v[36:37] op_sel_hi:[0,1,1]
	s_waitcnt lgkmcnt(0)
	v_pk_fma_f32 v[56:57], v[40:41], v[60:61], v[36:37] op_sel_hi:[0,1,1]
	v_pk_fma_f32 v[36:37], v[120:121], v[38:39], v[64:65] op_sel_hi:[0,1,1]
	v_pk_fma_f32 v[36:37], v[120:121], v[42:43], v[36:37] op_sel:[1,0,0]
	s_nop 0
	v_pk_fma_f32 v[36:37], v[122:123], v[58:59], v[36:37] op_sel_hi:[0,1,1]
	v_pk_fma_f32 v[60:61], v[40:41], v[62:63], v[36:37] op_sel_hi:[0,1,1]
	ds_read_b128 v[36:39], v82 offset:128
	ds_read_b128 v[40:43], v82 offset:144
	ds_read_b128 v[52:55], v82 offset:160
	s_waitcnt lgkmcnt(2)
	v_pk_fma_f32 v[36:37], v[124:125], v[36:37], v[56:57] op_sel_hi:[0,1,1]
	ds_read_b128 v[56:59], v82 offset:176
	v_pk_fma_f32 v[38:39], v[124:125], v[38:39], v[60:61] op_sel_hi:[0,1,1]
	s_waitcnt lgkmcnt(2)
	v_pk_fma_f32 v[36:37], v[124:125], v[40:41], v[36:37] op_sel:[1,0,0]
	v_pk_fma_f32 v[38:39], v[124:125], v[42:43], v[38:39] op_sel:[1,0,0]
	s_waitcnt lgkmcnt(1)
	v_pk_fma_f32 v[36:37], v[126:127], v[52:53], v[36:37] op_sel_hi:[0,1,1]
	v_mov_b32_e32 v40, v127
	v_pk_fma_f32 v[38:39], v[126:127], v[54:55], v[38:39] op_sel_hi:[0,1,1]
	s_waitcnt lgkmcnt(0)
	v_pk_fma_f32 v[36:37], v[40:41], v[56:57], v[36:37] op_sel_hi:[0,1,1]
	v_pk_fma_f32 v[42:43], v[40:41], v[58:59], v[38:39] op_sel_hi:[0,1,1]
	ds_read_b128 v[38:41], v82 offset:192
	ds_read_b128 v[48:51], v82 offset:208
	ds_read_b128 v[52:55], v82 offset:224
	ds_read_b128 v[56:59], v82 offset:240
	s_waitcnt lgkmcnt(3)
	v_pk_fma_f32 v[36:37], v[128:129], v[38:39], v[36:37] op_sel_hi:[0,1,1]
	s_waitcnt lgkmcnt(2)
	v_pk_fma_f32 v[36:37], v[128:129], v[48:49], v[36:37] op_sel:[1,0,0]
	v_mov_b32_e32 v48, v131
	s_waitcnt lgkmcnt(1)
	v_pk_fma_f32 v[36:37], v[130:131], v[52:53], v[36:37] op_sel_hi:[0,1,1]
	s_waitcnt lgkmcnt(0)
	v_pk_fma_f32 v[38:39], v[48:49], v[56:57], v[36:37] op_sel_hi:[0,1,1]
	v_pk_fma_f32 v[36:37], v[128:129], v[40:41], v[42:43] op_sel_hi:[0,1,1]
	v_pk_fma_f32 v[36:37], v[128:129], v[50:51], v[36:37] op_sel:[1,0,0]
	s_nop 0
	v_pk_fma_f32 v[36:37], v[130:131], v[54:55], v[36:37] op_sel_hi:[0,1,1]
	v_pk_fma_f32 v[36:37], v[48:49], v[58:59], v[36:37] op_sel_hi:[0,1,1]
	s_add_u32 s100, s78, 0x1e800000
	s_addc_u32 s101, s79, 0
	global_load_dword v116, v113, s[100:101]
	s_add_u32 s100, s100, 0x4000
	s_addc_u32 s101, s101, 0
	global_load_dword v117, v113, s[100:101]
	s_add_u32 s100, s100, 0x4000
	s_addc_u32 s101, s101, 0
	global_load_dword v118, v113, s[100:101]
	s_add_u32 s100, s100, 0x4000
	s_addc_u32 s101, s101, 0
	global_load_dword v119, v113, s[100:101]
	s_add_u32 s100, s100, 0x4000
	s_addc_u32 s101, s101, 0
	global_load_dword v120, v113, s[100:101]
	s_add_u32 s100, s100, 0x4000
	s_addc_u32 s101, s101, 0
	global_load_dword v121, v113, s[100:101]
	s_add_u32 s100, s100, 0x4000
	s_addc_u32 s101, s101, 0
	global_load_dword v122, v113, s[100:101]
	s_add_u32 s100, s100, 0x4000
	s_addc_u32 s101, s101, 0
	global_load_dword v123, v113, s[100:101]
	s_add_u32 s100, s100, 0x4000
	s_addc_u32 s101, s101, 0
	global_load_dword v124, v113, s[100:101]
	s_add_u32 s100, s100, 0x4000
	s_addc_u32 s101, s101, 0
	global_load_dword v125, v113, s[100:101]
	s_add_u32 s100, s100, 0x4000
	s_addc_u32 s101, s101, 0
	global_load_dword v126, v113, s[100:101]
	s_add_u32 s100, s100, 0x4000
	s_addc_u32 s101, s101, 0
	global_load_dword v127, v113, s[100:101]
	s_add_u32 s100, s100, 0x4000
	s_addc_u32 s101, s101, 0
	global_load_dword v128, v113, s[100:101]
	s_add_u32 s100, s100, 0x4000
	s_addc_u32 s101, s101, 0
	global_load_dword v129, v113, s[100:101]
	s_add_u32 s100, s100, 0x4000
	s_addc_u32 s101, s101, 0
	global_load_dword v130, v113, s[100:101]
	s_add_u32 s100, s100, 0x4000
	s_addc_u32 s101, s101, 0
	global_load_dword v131, v113, s[100:101]
	s_waitcnt vmcnt(48)
	v_mov_b32_e32 v82, 0x100
	ds_read_b128 v[56:59], v82
	ds_read_b128 v[60:63], v82 offset:16
	ds_read_b128 v[64:67], v82 offset:32
	ds_read_b128 v[78:81], v82 offset:48
	s_waitcnt lgkmcnt(3)
	v_pk_fma_f32 v[38:39], v[132:133], v[56:57], v[38:39] op_sel_hi:[0,1,1]
	v_pk_fma_f32 v[36:37], v[132:133], v[58:59], v[36:37] op_sel_hi:[0,1,1]
	s_waitcnt lgkmcnt(2)
	v_pk_fma_f32 v[38:39], v[132:133], v[60:61], v[38:39] op_sel:[1,0,0]
	v_pk_fma_f32 v[36:37], v[132:133], v[62:63], v[36:37] op_sel:[1,0,0]
	s_waitcnt lgkmcnt(1)
; __device__ void ph_filter_gen(const Params& P, int j, const float* __restrict__ a3, float* __restrict__ kf, float* sl) {
;     ...
;         for (int i = 0; i < 8; ++i) { const int t = tid + NT * i; const float4* ar = (const float4*)(a3 + (size_t)t * 64);
;             float a0 = 0.f, a1 = 0.f, a2 = 0.f, a3v = 0.f;
; #pragma unroll 4
;             for (int jq = 0; jq < 16; ++jq) { const float4 av = ar[jq]; const float ae[4] = {av.x, av.y, av.z, av.w};
; #pragma unroll
;                 for (int e = 0; e < 4; ++e) { const float4 wv = *(const float4*)(sw + (jq * 4 + e) * 4); a0 += ae[e] * wv.x; a1 += ae[e] * wv.y; a2 += ae[e] * wv.z; a3v += ae[e] * wv.w; } }
;             const float dec = expf(-((float)t / (float)(SEQ - 1)) * delta);
;             hv[i][0] = a0 * dec; hv[i][1] = a1 * dec; hv[i][2] = a2 * dec; hv[i][3] = a3v * dec;
	v_pk_fma_f32 v[38:39], v[134:135], v[64:65], v[38:39] op_sel_hi:[0,1,1]
	v_mov_b32_e32 v56, v135
	v_pk_fma_f32 v[36:37], v[134:135], v[66:67], v[36:37] op_sel_hi:[0,1,1]
	s_waitcnt lgkmcnt(0)
	v_pk_fma_f32 v[60:61], v[56:57], v[78:79], v[38:39] op_sel_hi:[0,1,1]
	v_pk_fma_f32 v[64:65], v[56:57], v[80:81], v[36:37] op_sel_hi:[0,1,1]
	ds_read_b128 v[36:39], v82 offset:64
	ds_read_b128 v[40:43], v82 offset:80
	ds_read_b128 v[56:59], v82 offset:96
	s_waitcnt lgkmcnt(2)
	v_pk_fma_f32 v[36:37], v[136:137], v[36:37], v[60:61] op_sel_hi:[0,1,1]
	ds_read_b128 v[60:63], v82 offset:112
	s_waitcnt lgkmcnt(2)
	v_pk_fma_f32 v[36:37], v[136:137], v[40:41], v[36:37] op_sel:[1,0,0]
	v_mov_b32_e32 v40, v139
	s_waitcnt lgkmcnt(1)
	v_pk_fma_f32 v[36:37], v[138:139], v[56:57], v[36:37] op_sel_hi:[0,1,1]
	s_waitcnt lgkmcnt(0)
	v_pk_fma_f32 v[56:57], v[40:41], v[60:61], v[36:37] op_sel_hi:[0,1,1]
	v_pk_fma_f32 v[36:37], v[136:137], v[38:39], v[64:65] op_sel_hi:[0,1,1]
	v_pk_fma_f32 v[36:37], v[136:137], v[42:43], v[36:37] op_sel:[1,0,0]
	s_nop 0
	v_pk_fma_f32 v[36:37], v[138:139], v[58:59], v[36:37] op_sel_hi:[0,1,1]
	v_pk_fma_f32 v[60:61], v[40:41], v[62:63], v[36:37] op_sel_hi:[0,1,1]
	ds_read_b128 v[36:39], v82 offset:128
	ds_read_b128 v[40:43], v82 offset:144
	ds_read_b128 v[52:55], v82 offset:160
	s_waitcnt lgkmcnt(2)
	v_pk_fma_f32 v[36:37], v[140:141], v[36:37], v[56:57] op_sel_hi:[0,1,1]
	ds_read_b128 v[56:59], v82 offset:176
	v_pk_fma_f32 v[38:39], v[140:141], v[38:39], v[60:61] op_sel_hi:[0,1,1]
	s_waitcnt lgkmcnt(2)
	v_pk_fma_f32 v[36:37], v[140:141], v[40:41], v[36:37] op_sel:[1,0,0]
	v_pk_fma_f32 v[38:39], v[140:141], v[42:43], v[38:39] op_sel:[1,0,0]
	s_waitcnt lgkmcnt(1)
	v_pk_fma_f32 v[36:37], v[142:143], v[52:53], v[36:37] op_sel_hi:[0,1,1]
	v_mov_b32_e32 v40, v143
	v_pk_fma_f32 v[38:39], v[142:143], v[54:55], v[38:39] op_sel_hi:[0,1,1]
	s_waitcnt lgkmcnt(0)
	v_pk_fma_f32 v[36:37], v[40:41], v[56:57], v[36:37] op_sel_hi:[0,1,1]
	v_pk_fma_f32 v[42:43], v[40:41], v[58:59], v[38:39] op_sel_hi:[0,1,1]
	ds_read_b128 v[38:41], v82 offset:192
	ds_read_b128 v[48:51], v82 offset:208
	ds_read_b128 v[52:55], v82 offset:224
	ds_read_b128 v[56:59], v82 offset:240
	s_waitcnt lgkmcnt(3)
	v_pk_fma_f32 v[36:37], v[144:145], v[38:39], v[36:37] op_sel_hi:[0,1,1]
	s_waitcnt lgkmcnt(2)
	v_pk_fma_f32 v[36:37], v[144:145], v[48:49], v[36:37] op_sel:[1,0,0]
	v_mov_b32_e32 v48, v147
	s_waitcnt lgkmcnt(1)
	v_pk_fma_f32 v[36:37], v[146:147], v[52:53], v[36:37] op_sel_hi:[0,1,1]
	s_waitcnt lgkmcnt(0)
	v_pk_fma_f32 v[38:39], v[48:49], v[56:57], v[36:37] op_sel_hi:[0,1,1]
	v_pk_fma_f32 v[36:37], v[144:145], v[40:41], v[42:43] op_sel_hi:[0,1,1]
	v_pk_fma_f32 v[36:37], v[144:145], v[50:51], v[36:37] op_sel:[1,0,0]
	s_nop 0
	v_pk_fma_f32 v[36:37], v[146:147], v[54:55], v[36:37] op_sel_hi:[0,1,1]
	v_pk_fma_f32 v[36:37], v[48:49], v[58:59], v[36:37] op_sel_hi:[0,1,1]
	s_add_u32 s100, s78, 0x1e840000
	s_addc_u32 s101, s79, 0
	global_load_dword v132, v113, s[100:101]
	s_add_u32 s100, s100, 0x4000
	s_addc_u32 s101, s101, 0
	global_load_dword v133, v113, s[100:101]
	s_add_u32 s100, s100, 0x4000
	s_addc_u32 s101, s101, 0
	global_load_dword v134, v113, s[100:101]
	s_add_u32 s100, s100, 0x4000
	s_addc_u32 s101, s101, 0
	global_load_dword v135, v113, s[100:101]
	s_add_u32 s100, s100, 0x4000
	s_addc_u32 s101, s101, 0
	global_load_dword v136, v113, s[100:101]
	s_add_u32 s100, s100, 0x4000
	s_addc_u32 s101, s101, 0
	global_load_dword v137, v113, s[100:101]
	s_add_u32 s100, s100, 0x4000
	s_addc_u32 s101, s101, 0
	global_load_dword v138, v113, s[100:101]
	s_add_u32 s100, s100, 0x4000
	s_addc_u32 s101, s101, 0
	global_load_dword v139, v113, s[100:101]
	s_add_u32 s100, s100, 0x4000
	s_addc_u32 s101, s101, 0
	global_load_dword v140, v113, s[100:101]
	s_add_u32 s100, s100, 0x4000
	s_addc_u32 s101, s101, 0
	global_load_dword v141, v113, s[100:101]
	s_add_u32 s100, s100, 0x4000
	s_addc_u32 s101, s101, 0
	global_load_dword v142, v113, s[100:101]
	s_add_u32 s100, s100, 0x4000
	s_addc_u32 s101, s101, 0
	global_load_dword v143, v113, s[100:101]
	s_add_u32 s100, s100, 0x4000
	s_addc_u32 s101, s101, 0
	global_load_dword v144, v113, s[100:101]
	s_add_u32 s100, s100, 0x4000
	s_addc_u32 s101, s101, 0
	global_load_dword v145, v113, s[100:101]
	s_add_u32 s100, s100, 0x4000
	s_addc_u32 s101, s101, 0
	global_load_dword v146, v113, s[100:101]
	s_add_u32 s100, s100, 0x4000
	s_addc_u32 s101, s101, 0
	global_load_dword v147, v113, s[100:101]
	s_waitcnt vmcnt(48)
	v_mov_b32_e32 v82, 0x200
	ds_read_b128 v[56:59], v82
	ds_read_b128 v[60:63], v82 offset:16
	ds_read_b128 v[64:67], v82 offset:32
	ds_read_b128 v[78:81], v82 offset:48
	s_waitcnt lgkmcnt(3)
	v_pk_fma_f32 v[38:39], v[148:149], v[56:57], v[38:39] op_sel_hi:[0,1,1]
	v_pk_fma_f32 v[36:37], v[148:149], v[58:59], v[36:37] op_sel_hi:[0,1,1]
	s_waitcnt lgkmcnt(2)
	v_pk_fma_f32 v[38:39], v[148:149], v[60:61], v[38:39] op_sel:[1,0,0]
	v_pk_fma_f32 v[36:37], v[148:149], v[62:63], v[36:37] op_sel:[1,0,0]
	s_waitcnt lgkmcnt(1)
	v_pk_fma_f32 v[38:39], v[150:151], v[64:65], v[38:39] op_sel_hi:[0,1,1]
	v_mov_b32_e32 v56, v151
	v_pk_fma_f32 v[36:37], v[150:151], v[66:67], v[36:37] op_sel_hi:[0,1,1]
	s_waitcnt lgkmcnt(0)
	v_pk_fma_f32 v[60:61], v[56:57], v[78:79], v[38:39] op_sel_hi:[0,1,1]
	v_pk_fma_f32 v[64:65], v[56:57], v[80:81], v[36:37] op_sel_hi:[0,1,1]
	ds_read_b128 v[36:39], v82 offset:64
	ds_read_b128 v[40:43], v82 offset:80
	ds_read_b128 v[56:59], v82 offset:96
	s_waitcnt lgkmcnt(2)
	v_pk_fma_f32 v[36:37], v[152:153], v[36:37], v[60:61] op_sel_hi:[0,1,1]
	ds_read_b128 v[60:63], v82 offset:112
	s_waitcnt lgkmcnt(2)
; __device__ void ph_filter_gen(const Params& P, int j, const float* __restrict__ a3, float* __restrict__ kf, float* sl) {
;     ...
;         for (int i = 0; i < 8; ++i) { const int t = tid + NT * i; const float4* ar = (const float4*)(a3 + (size_t)t * 64);
;             float a0 = 0.f, a1 = 0.f, a2 = 0.f, a3v = 0.f;
; #pragma unroll 4
;             for (int jq = 0; jq < 16; ++jq) { const float4 av = ar[jq]; const float ae[4] = {av.x, av.y, av.z, av.w};
; #pragma unroll
;                 for (int e = 0; e < 4; ++e) { const float4 wv = *(const float4*)(sw + (jq * 4 + e) * 4); a0 += ae[e] * wv.x; a1 += ae[e] * wv.y; a2 += ae[e] * wv.z; a3v += ae[e] * wv.w; } }
;             const float dec = expf(-((float)t / (float)(SEQ - 1)) * delta);
;             hv[i][0] = a0 * dec; hv[i][1] = a1 * dec; hv[i][2] = a2 * dec; hv[i][3] = a3v * dec;
	v_pk_fma_f32 v[36:37], v[152:153], v[40:41], v[36:37] op_sel:[1,0,0]
	v_mov_b32_e32 v40, v155
	s_waitcnt lgkmcnt(1)
	v_pk_fma_f32 v[36:37], v[154:155], v[56:57], v[36:37] op_sel_hi:[0,1,1]
	s_waitcnt lgkmcnt(0)
	v_pk_fma_f32 v[56:57], v[40:41], v[60:61], v[36:37] op_sel_hi:[0,1,1]
	v_pk_fma_f32 v[36:37], v[152:153], v[38:39], v[64:65] op_sel_hi:[0,1,1]
	v_pk_fma_f32 v[36:37], v[152:153], v[42:43], v[36:37] op_sel:[1,0,0]
	s_nop 0
	v_pk_fma_f32 v[36:37], v[154:155], v[58:59], v[36:37] op_sel_hi:[0,1,1]
	v_pk_fma_f32 v[60:61], v[40:41], v[62:63], v[36:37] op_sel_hi:[0,1,1]
	ds_read_b128 v[36:39], v82 offset:128
	ds_read_b128 v[40:43], v82 offset:144
	ds_read_b128 v[52:55], v82 offset:160
	s_waitcnt lgkmcnt(2)
	v_pk_fma_f32 v[36:37], v[156:157], v[36:37], v[56:57] op_sel_hi:[0,1,1]
	ds_read_b128 v[56:59], v82 offset:176
	v_pk_fma_f32 v[38:39], v[156:157], v[38:39], v[60:61] op_sel_hi:[0,1,1]
	s_waitcnt lgkmcnt(2)
	v_pk_fma_f32 v[36:37], v[156:157], v[40:41], v[36:37] op_sel:[1,0,0]
	v_pk_fma_f32 v[38:39], v[156:157], v[42:43], v[38:39] op_sel:[1,0,0]
	s_waitcnt lgkmcnt(1)
	v_pk_fma_f32 v[36:37], v[158:159], v[52:53], v[36:37] op_sel_hi:[0,1,1]
	v_mov_b32_e32 v40, v159
	v_pk_fma_f32 v[38:39], v[158:159], v[54:55], v[38:39] op_sel_hi:[0,1,1]
	s_waitcnt lgkmcnt(0)
	v_pk_fma_f32 v[36:37], v[40:41], v[56:57], v[36:37] op_sel_hi:[0,1,1]
	v_pk_fma_f32 v[42:43], v[40:41], v[58:59], v[38:39] op_sel_hi:[0,1,1]
	ds_read_b128 v[38:41], v82 offset:192
	ds_read_b128 v[48:51], v82 offset:208
	ds_read_b128 v[52:55], v82 offset:224
	ds_read_b128 v[56:59], v82 offset:240
	s_waitcnt lgkmcnt(3)
	v_pk_fma_f32 v[36:37], v[160:161], v[38:39], v[36:37] op_sel_hi:[0,1,1]
	s_waitcnt lgkmcnt(2)
	v_pk_fma_f32 v[36:37], v[160:161], v[48:49], v[36:37] op_sel:[1,0,0]
	v_mov_b32_e32 v48, v163
	s_waitcnt lgkmcnt(1)
	v_pk_fma_f32 v[36:37], v[162:163], v[52:53], v[36:37] op_sel_hi:[0,1,1]
	s_waitcnt lgkmcnt(0)
	v_pk_fma_f32 v[38:39], v[48:49], v[56:57], v[36:37] op_sel_hi:[0,1,1]
	v_pk_fma_f32 v[36:37], v[160:161], v[40:41], v[42:43] op_sel_hi:[0,1,1]
	v_pk_fma_f32 v[36:37], v[160:161], v[50:51], v[36:37] op_sel:[1,0,0]
	s_nop 0
	v_pk_fma_f32 v[36:37], v[162:163], v[54:55], v[36:37] op_sel_hi:[0,1,1]
	v_pk_fma_f32 v[36:37], v[48:49], v[58:59], v[36:37] op_sel_hi:[0,1,1]
	s_add_u32 s100, s78, 0x1e880000
	s_addc_u32 s101, s79, 0
	global_load_dword v148, v113, s[100:101]
	s_add_u32 s100, s100, 0x4000
	s_addc_u32 s101, s101, 0
	global_load_dword v149, v113, s[100:101]
	s_add_u32 s100, s100, 0x4000
	s_addc_u32 s101, s101, 0
	global_load_dword v150, v113, s[100:101]
	s_add_u32 s100, s100, 0x4000
	s_addc_u32 s101, s101, 0
	global_load_dword v151, v113, s[100:101]
	s_add_u32 s100, s100, 0x4000
	s_addc_u32 s101, s101, 0
	global_load_dword v152, v113, s[100:101]
	s_add_u32 s100, s100, 0x4000
	s_addc_u32 s101, s101, 0
	global_load_dword v153, v113, s[100:101]
	s_add_u32 s100, s100, 0x4000
	s_addc_u32 s101, s101, 0
	global_load_dword v154, v113, s[100:101]
	s_add_u32 s100, s100, 0x4000
	s_addc_u32 s101, s101, 0
	global_load_dword v155, v113, s[100:101]
	s_add_u32 s100, s100, 0x4000
	s_addc_u32 s101, s101, 0
	global_load_dword v156, v113, s[100:101]
	s_add_u32 s100, s100, 0x4000
	s_addc_u32 s101, s101, 0
	global_load_dword v157, v113, s[100:101]
	s_add_u32 s100, s100, 0x4000
	s_addc_u32 s101, s101, 0
	global_load_dword v158, v113, s[100:101]
	s_add_u32 s100, s100, 0x4000
	s_addc_u32 s101, s101, 0
	global_load_dword v159, v113, s[100:101]
	s_add_u32 s100, s100, 0x4000
	s_addc_u32 s101, s101, 0
	global_load_dword v160, v113, s[100:101]
	s_add_u32 s100, s100, 0x4000
	s_addc_u32 s101, s101, 0
	global_load_dword v161, v113, s[100:101]
	s_add_u32 s100, s100, 0x4000
	s_addc_u32 s101, s101, 0
	global_load_dword v162, v113, s[100:101]
	s_add_u32 s100, s100, 0x4000
	s_addc_u32 s101, s101, 0
	global_load_dword v163, v113, s[100:101]
	s_waitcnt vmcnt(48)
	v_mov_b32_e32 v82, 0x300
	ds_read_b128 v[56:59], v82
	ds_read_b128 v[60:63], v82 offset:16
	ds_read_b128 v[64:67], v82 offset:32
	ds_read_b128 v[78:81], v82 offset:48
	s_waitcnt lgkmcnt(3)
	v_pk_fma_f32 v[38:39], v[164:165], v[56:57], v[38:39] op_sel_hi:[0,1,1]
	v_pk_fma_f32 v[36:37], v[164:165], v[58:59], v[36:37] op_sel_hi:[0,1,1]
	s_waitcnt lgkmcnt(2)
	v_pk_fma_f32 v[38:39], v[164:165], v[60:61], v[38:39] op_sel:[1,0,0]
	v_pk_fma_f32 v[36:37], v[164:165], v[62:63], v[36:37] op_sel:[1,0,0]
	s_waitcnt lgkmcnt(1)
	v_pk_fma_f32 v[38:39], v[166:167], v[64:65], v[38:39] op_sel_hi:[0,1,1]
	v_mov_b32_e32 v56, v167
	v_pk_fma_f32 v[36:37], v[166:167], v[66:67], v[36:37] op_sel_hi:[0,1,1]
	s_waitcnt lgkmcnt(0)
	v_pk_fma_f32 v[60:61], v[56:57], v[78:79], v[38:39] op_sel_hi:[0,1,1]
	v_pk_fma_f32 v[64:65], v[56:57], v[80:81], v[36:37] op_sel_hi:[0,1,1]
	ds_read_b128 v[36:39], v82 offset:64
	ds_read_b128 v[40:43], v82 offset:80
	ds_read_b128 v[56:59], v82 offset:96
	s_waitcnt lgkmcnt(2)
	v_pk_fma_f32 v[36:37], v[168:169], v[36:37], v[60:61] op_sel_hi:[0,1,1]
	ds_read_b128 v[60:63], v82 offset:112
	s_waitcnt lgkmcnt(2)
	v_pk_fma_f32 v[36:37], v[168:169], v[40:41], v[36:37] op_sel:[1,0,0]
	v_mov_b32_e32 v40, v171
	s_waitcnt lgkmcnt(1)
	v_pk_fma_f32 v[36:37], v[170:171], v[56:57], v[36:37] op_sel_hi:[0,1,1]
	s_waitcnt lgkmcnt(0)
	v_pk_fma_f32 v[56:57], v[40:41], v[60:61], v[36:37] op_sel_hi:[0,1,1]
	v_pk_fma_f32 v[36:37], v[168:169], v[38:39], v[64:65] op_sel_hi:[0,1,1]
	v_pk_fma_f32 v[36:37], v[168:169], v[42:43], v[36:37] op_sel:[1,0,0]
	s_nop 0
	v_pk_fma_f32 v[36:37], v[170:171], v[58:59], v[36:37] op_sel_hi:[0,1,1]
	v_pk_fma_f32 v[60:61], v[40:41], v[62:63], v[36:37] op_sel_hi:[0,1,1]
	ds_read_b128 v[36:39], v82 offset:128
	ds_read_b128 v[40:43], v82 offset:144
	ds_read_b128 v[52:55], v82 offset:160
	s_waitcnt lgkmcnt(2)
; __device__ void ph_filter_gen(const Params& P, int j, const float* __restrict__ a3, float* __restrict__ kf, float* sl) {
;     ...
;         for (int i = 0; i < 8; ++i) { const int t = tid + NT * i; const float4* ar = (const float4*)(a3 + (size_t)t * 64);
;             float a0 = 0.f, a1 = 0.f, a2 = 0.f, a3v = 0.f;
; #pragma unroll 4
;             for (int jq = 0; jq < 16; ++jq) { const float4 av = ar[jq]; const float ae[4] = {av.x, av.y, av.z, av.w};
; #pragma unroll
;                 for (int e = 0; e < 4; ++e) { const float4 wv = *(const float4*)(sw + (jq * 4 + e) * 4); a0 += ae[e] * wv.x; a1 += ae[e] * wv.y; a2 += ae[e] * wv.z; a3v += ae[e] * wv.w; } }
;             const float dec = expf(-((float)t / (float)(SEQ - 1)) * delta);
;             hv[i][0] = a0 * dec; hv[i][1] = a1 * dec; hv[i][2] = a2 * dec; hv[i][3] = a3v * dec;
	v_pk_fma_f32 v[36:37], v[172:173], v[36:37], v[56:57] op_sel_hi:[0,1,1]
	ds_read_b128 v[56:59], v82 offset:176
	v_pk_fma_f32 v[38:39], v[172:173], v[38:39], v[60:61] op_sel_hi:[0,1,1]
	s_waitcnt lgkmcnt(2)
	v_pk_fma_f32 v[36:37], v[172:173], v[40:41], v[36:37] op_sel:[1,0,0]
	v_pk_fma_f32 v[38:39], v[172:173], v[42:43], v[38:39] op_sel:[1,0,0]
	s_waitcnt lgkmcnt(1)
	v_pk_fma_f32 v[36:37], v[174:175], v[52:53], v[36:37] op_sel_hi:[0,1,1]
	v_mov_b32_e32 v40, v175
	v_pk_fma_f32 v[38:39], v[174:175], v[54:55], v[38:39] op_sel_hi:[0,1,1]
	s_waitcnt lgkmcnt(0)
	v_pk_fma_f32 v[36:37], v[40:41], v[56:57], v[36:37] op_sel_hi:[0,1,1]
	v_pk_fma_f32 v[42:43], v[40:41], v[58:59], v[38:39] op_sel_hi:[0,1,1]
	ds_read_b128 v[38:41], v82 offset:192
	ds_read_b128 v[48:51], v82 offset:208
	ds_read_b128 v[52:55], v82 offset:224
	ds_read_b128 v[56:59], v82 offset:240
	s_waitcnt lgkmcnt(3)
	v_pk_fma_f32 v[36:37], v[176:177], v[38:39], v[36:37] op_sel_hi:[0,1,1]
	s_waitcnt lgkmcnt(2)
	v_pk_fma_f32 v[36:37], v[176:177], v[48:49], v[36:37] op_sel:[1,0,0]
	v_mov_b32_e32 v48, v179
	s_waitcnt lgkmcnt(1)
	v_pk_fma_f32 v[36:37], v[178:179], v[52:53], v[36:37] op_sel_hi:[0,1,1]
	s_waitcnt lgkmcnt(0)
	v_pk_fma_f32 v[38:39], v[48:49], v[56:57], v[36:37] op_sel_hi:[0,1,1]
	v_pk_fma_f32 v[36:37], v[176:177], v[40:41], v[42:43] op_sel_hi:[0,1,1]
	v_pk_fma_f32 v[36:37], v[176:177], v[50:51], v[36:37] op_sel:[1,0,0]
	s_nop 0
	v_pk_fma_f32 v[36:37], v[178:179], v[54:55], v[36:37] op_sel_hi:[0,1,1]
	v_pk_fma_f32 v[36:37], v[48:49], v[58:59], v[36:37] op_sel_hi:[0,1,1]
	s_add_u32 s100, s78, 0x1e8c0000
	s_addc_u32 s101, s79, 0
	global_load_dword v164, v113, s[100:101]
	s_add_u32 s100, s100, 0x4000
	s_addc_u32 s101, s101, 0
	global_load_dword v165, v113, s[100:101]
	s_add_u32 s100, s100, 0x4000
	s_addc_u32 s101, s101, 0
	global_load_dword v166, v113, s[100:101]
	s_add_u32 s100, s100, 0x4000
	s_addc_u32 s101, s101, 0
	global_load_dword v167, v113, s[100:101]
	s_add_u32 s100, s100, 0x4000
	s_addc_u32 s101, s101, 0
	global_load_dword v168, v113, s[100:101]
	s_add_u32 s100, s100, 0x4000
	s_addc_u32 s101, s101, 0
	global_load_dword v169, v113, s[100:101]
	s_add_u32 s100, s100, 0x4000
	s_addc_u32 s101, s101, 0
	global_load_dword v170, v113, s[100:101]
	s_add_u32 s100, s100, 0x4000
	s_addc_u32 s101, s101, 0
	global_load_dword v171, v113, s[100:101]
	s_add_u32 s100, s100, 0x4000
	s_addc_u32 s101, s101, 0
	global_load_dword v172, v113, s[100:101]
	s_add_u32 s100, s100, 0x4000
	s_addc_u32 s101, s101, 0
	global_load_dword v173, v113, s[100:101]
	s_add_u32 s100, s100, 0x4000
	s_addc_u32 s101, s101, 0
	global_load_dword v174, v113, s[100:101]
	s_add_u32 s100, s100, 0x4000
	s_addc_u32 s101, s101, 0
	global_load_dword v175, v113, s[100:101]
	s_add_u32 s100, s100, 0x4000
	s_addc_u32 s101, s101, 0
	global_load_dword v176, v113, s[100:101]
	s_add_u32 s100, s100, 0x4000
	s_addc_u32 s101, s101, 0
	global_load_dword v177, v113, s[100:101]
	s_add_u32 s100, s100, 0x4000
	s_addc_u32 s101, s101, 0
	global_load_dword v178, v113, s[100:101]
	s_add_u32 s100, s100, 0x4000
	s_addc_u32 s101, s101, 0
	global_load_dword v179, v113, s[100:101]
	v_mov_b32_e32 v42, 0
	s_mov_b32 s0, 0
	s_mov_b64 s[14:15], 0
	v_mov_b32_e32 v43, v42
	v_mov_b32_e32 v40, v42
	v_mov_b32_e32 v41, v42
.LBB0_223:
	v_add_u32_e32 v113, 0x1000, v68
	s_waitcnt vmcnt(48)
	v_mov_b32_e32 v86, 0
	ds_read_b128 v[60:63], v86
	ds_read_b128 v[64:67], v86 offset:16
	ds_read_b128 v[78:81], v86 offset:32
	ds_read_b128 v[82:85], v86 offset:48
	s_waitcnt lgkmcnt(3)
	v_pk_fma_f32 v[42:43], v[116:117], v[60:61], v[42:43] op_sel_hi:[0,1,1]
	v_pk_fma_f32 v[40:41], v[116:117], v[62:63], v[40:41] op_sel_hi:[0,1,1]
	s_waitcnt lgkmcnt(2)
	v_pk_fma_f32 v[42:43], v[116:117], v[64:65], v[42:43] op_sel:[1,0,0]
	v_pk_fma_f32 v[40:41], v[116:117], v[66:67], v[40:41] op_sel:[1,0,0]
	s_waitcnt lgkmcnt(1)
	v_pk_fma_f32 v[42:43], v[118:119], v[78:79], v[42:43] op_sel_hi:[0,1,1]
	v_mov_b32_e32 v60, v119
	v_pk_fma_f32 v[40:41], v[118:119], v[80:81], v[40:41] op_sel_hi:[0,1,1]
	s_waitcnt lgkmcnt(0)
	v_pk_fma_f32 v[64:65], v[60:61], v[82:83], v[42:43] op_sel_hi:[0,1,1]
	v_pk_fma_f32 v[78:79], v[60:61], v[84:85], v[40:41] op_sel_hi:[0,1,1]
	ds_read_b128 v[40:43], v86 offset:64
	ds_read_b128 v[44:47], v86 offset:80
	ds_read_b128 v[60:63], v86 offset:96
	s_waitcnt lgkmcnt(2)
	v_pk_fma_f32 v[40:41], v[120:121], v[40:41], v[64:65] op_sel_hi:[0,1,1]
	ds_read_b128 v[64:67], v86 offset:112
	s_waitcnt lgkmcnt(2)
	v_pk_fma_f32 v[40:41], v[120:121], v[44:45], v[40:41] op_sel:[1,0,0]
	v_mov_b32_e32 v44, v123
	s_waitcnt lgkmcnt(1)
	v_pk_fma_f32 v[40:41], v[122:123], v[60:61], v[40:41] op_sel_hi:[0,1,1]
	s_waitcnt lgkmcnt(0)
	v_pk_fma_f32 v[60:61], v[44:45], v[64:65], v[40:41] op_sel_hi:[0,1,1]
	v_pk_fma_f32 v[40:41], v[120:121], v[42:43], v[78:79] op_sel_hi:[0,1,1]
	v_pk_fma_f32 v[40:41], v[120:121], v[46:47], v[40:41] op_sel:[1,0,0]
	s_nop 0
	v_pk_fma_f32 v[40:41], v[122:123], v[62:63], v[40:41] op_sel_hi:[0,1,1]
	v_pk_fma_f32 v[64:65], v[44:45], v[66:67], v[40:41] op_sel_hi:[0,1,1]
	ds_read_b128 v[40:43], v86 offset:128
	ds_read_b128 v[44:47], v86 offset:144
	ds_read_b128 v[56:59], v86 offset:160
	s_waitcnt lgkmcnt(2)
	v_pk_fma_f32 v[40:41], v[124:125], v[40:41], v[60:61] op_sel_hi:[0,1,1]
	ds_read_b128 v[60:63], v86 offset:176
	v_pk_fma_f32 v[42:43], v[124:125], v[42:43], v[64:65] op_sel_hi:[0,1,1]
	s_waitcnt lgkmcnt(2)
	v_pk_fma_f32 v[40:41], v[124:125], v[44:45], v[40:41] op_sel:[1,0,0]
	v_pk_fma_f32 v[42:43], v[124:125], v[46:47], v[42:43] op_sel:[1,0,0]
	s_waitcnt lgkmcnt(1)
	v_pk_fma_f32 v[40:41], v[126:127], v[56:57], v[40:41] op_sel_hi:[0,1,1]
	v_mov_b32_e32 v44, v127
	v_pk_fma_f32 v[42:43], v[126:127], v[58:59], v[42:43] op_sel_hi:[0,1,1]
	s_waitcnt lgkmcnt(0)
; __device__ void ph_filter_gen(const Params& P, int j, const float* __restrict__ a3, float* __restrict__ kf, float* sl) {
;     ...
;         for (int i = 0; i < 8; ++i) { const int t = tid + NT * i; const float4* ar = (const float4*)(a3 + (size_t)t * 64);
;             float a0 = 0.f, a1 = 0.f, a2 = 0.f, a3v = 0.f;
; #pragma unroll 4
;             for (int jq = 0; jq < 16; ++jq) { const float4 av = ar[jq]; const float ae[4] = {av.x, av.y, av.z, av.w};
; #pragma unroll
;                 for (int e = 0; e < 4; ++e) { const float4 wv = *(const float4*)(sw + (jq * 4 + e) * 4); a0 += ae[e] * wv.x; a1 += ae[e] * wv.y; a2 += ae[e] * wv.z; a3v += ae[e] * wv.w; } }
;             const float dec = expf(-((float)t / (float)(SEQ - 1)) * delta);
;             hv[i][0] = a0 * dec; hv[i][1] = a1 * dec; hv[i][2] = a2 * dec; hv[i][3] = a3v * dec;
	v_pk_fma_f32 v[40:41], v[44:45], v[60:61], v[40:41] op_sel_hi:[0,1,1]
	v_pk_fma_f32 v[46:47], v[44:45], v[62:63], v[42:43] op_sel_hi:[0,1,1]
	ds_read_b128 v[42:45], v86 offset:192
	ds_read_b128 v[52:55], v86 offset:208
	ds_read_b128 v[56:59], v86 offset:224
	ds_read_b128 v[60:63], v86 offset:240
	s_waitcnt lgkmcnt(3)
	v_pk_fma_f32 v[40:41], v[128:129], v[42:43], v[40:41] op_sel_hi:[0,1,1]
	s_waitcnt lgkmcnt(2)
	v_pk_fma_f32 v[40:41], v[128:129], v[52:53], v[40:41] op_sel:[1,0,0]
	v_mov_b32_e32 v52, v131
	s_waitcnt lgkmcnt(1)
	v_pk_fma_f32 v[40:41], v[130:131], v[56:57], v[40:41] op_sel_hi:[0,1,1]
	s_waitcnt lgkmcnt(0)
	v_pk_fma_f32 v[42:43], v[52:53], v[60:61], v[40:41] op_sel_hi:[0,1,1]
	v_pk_fma_f32 v[40:41], v[128:129], v[44:45], v[46:47] op_sel_hi:[0,1,1]
	v_pk_fma_f32 v[40:41], v[128:129], v[54:55], v[40:41] op_sel:[1,0,0]
	s_nop 0
	v_pk_fma_f32 v[40:41], v[130:131], v[58:59], v[40:41] op_sel_hi:[0,1,1]
	v_pk_fma_f32 v[40:41], v[52:53], v[62:63], v[40:41] op_sel_hi:[0,1,1]
	s_add_u32 s100, s78, 0x1e800000
	s_addc_u32 s101, s79, 0
	global_load_dword v116, v113, s[100:101]
	s_add_u32 s100, s100, 0x4000
	s_addc_u32 s101, s101, 0
	global_load_dword v117, v113, s[100:101]
	s_add_u32 s100, s100, 0x4000
	s_addc_u32 s101, s101, 0
	global_load_dword v118, v113, s[100:101]
	s_add_u32 s100, s100, 0x4000
	s_addc_u32 s101, s101, 0
	global_load_dword v119, v113, s[100:101]
	s_add_u32 s100, s100, 0x4000
	s_addc_u32 s101, s101, 0
	global_load_dword v120, v113, s[100:101]
	s_add_u32 s100, s100, 0x4000
	s_addc_u32 s101, s101, 0
	global_load_dword v121, v113, s[100:101]
	s_add_u32 s100, s100, 0x4000
	s_addc_u32 s101, s101, 0
	global_load_dword v122, v113, s[100:101]
	s_add_u32 s100, s100, 0x4000
	s_addc_u32 s101, s101, 0
	global_load_dword v123, v113, s[100:101]
	s_add_u32 s100, s100, 0x4000
	s_addc_u32 s101, s101, 0
	global_load_dword v124, v113, s[100:101]
	s_add_u32 s100, s100, 0x4000
	s_addc_u32 s101, s101, 0
	global_load_dword v125, v113, s[100:101]
	s_add_u32 s100, s100, 0x4000
	s_addc_u32 s101, s101, 0
	global_load_dword v126, v113, s[100:101]
	s_add_u32 s100, s100, 0x4000
	s_addc_u32 s101, s101, 0
	global_load_dword v127, v113, s[100:101]
	s_add_u32 s100, s100, 0x4000
	s_addc_u32 s101, s101, 0
	global_load_dword v128, v113, s[100:101]
	s_add_u32 s100, s100, 0x4000
	s_addc_u32 s101, s101, 0
	global_load_dword v129, v113, s[100:101]
	s_add_u32 s100, s100, 0x4000
	s_addc_u32 s101, s101, 0
	global_load_dword v130, v113, s[100:101]
	s_add_u32 s100, s100, 0x4000
	s_addc_u32 s101, s101, 0
	global_load_dword v131, v113, s[100:101]
	s_waitcnt vmcnt(48)
	v_mov_b32_e32 v86, 0x100
	ds_read_b128 v[60:63], v86
	ds_read_b128 v[64:67], v86 offset:16
	ds_read_b128 v[78:81], v86 offset:32
	ds_read_b128 v[82:85], v86 offset:48
	s_waitcnt lgkmcnt(3)
	v_pk_fma_f32 v[42:43], v[132:133], v[60:61], v[42:43] op_sel_hi:[0,1,1]
	v_pk_fma_f32 v[40:41], v[132:133], v[62:63], v[40:41] op_sel_hi:[0,1,1]
	s_waitcnt lgkmcnt(2)
	v_pk_fma_f32 v[42:43], v[132:133], v[64:65], v[42:43] op_sel:[1,0,0]
	v_pk_fma_f32 v[40:41], v[132:133], v[66:67], v[40:41] op_sel:[1,0,0]
	s_waitcnt lgkmcnt(1)
	v_pk_fma_f32 v[42:43], v[134:135], v[78:79], v[42:43] op_sel_hi:[0,1,1]
	v_mov_b32_e32 v60, v135
	v_pk_fma_f32 v[40:41], v[134:135], v[80:81], v[40:41] op_sel_hi:[0,1,1]
	s_waitcnt lgkmcnt(0)
	v_pk_fma_f32 v[64:65], v[60:61], v[82:83], v[42:43] op_sel_hi:[0,1,1]
	v_pk_fma_f32 v[78:79], v[60:61], v[84:85], v[40:41] op_sel_hi:[0,1,1]
	ds_read_b128 v[40:43], v86 offset:64
	ds_read_b128 v[44:47], v86 offset:80
	ds_read_b128 v[60:63], v86 offset:96
	s_waitcnt lgkmcnt(2)
	v_pk_fma_f32 v[40:41], v[136:137], v[40:41], v[64:65] op_sel_hi:[0,1,1]
	ds_read_b128 v[64:67], v86 offset:112
	s_waitcnt lgkmcnt(2)
	v_pk_fma_f32 v[40:41], v[136:137], v[44:45], v[40:41] op_sel:[1,0,0]
	v_mov_b32_e32 v44, v139
	s_waitcnt lgkmcnt(1)
	v_pk_fma_f32 v[40:41], v[138:139], v[60:61], v[40:41] op_sel_hi:[0,1,1]
	s_waitcnt lgkmcnt(0)
	v_pk_fma_f32 v[60:61], v[44:45], v[64:65], v[40:41] op_sel_hi:[0,1,1]
	v_pk_fma_f32 v[40:41], v[136:137], v[42:43], v[78:79] op_sel_hi:[0,1,1]
	v_pk_fma_f32 v[40:41], v[136:137], v[46:47], v[40:41] op_sel:[1,0,0]
	s_nop 0
	v_pk_fma_f32 v[40:41], v[138:139], v[62:63], v[40:41] op_sel_hi:[0,1,1]
	v_pk_fma_f32 v[64:65], v[44:45], v[66:67], v[40:41] op_sel_hi:[0,1,1]
	ds_read_b128 v[40:43], v86 offset:128
	ds_read_b128 v[44:47], v86 offset:144
	ds_read_b128 v[56:59], v86 offset:160
	s_waitcnt lgkmcnt(2)
	v_pk_fma_f32 v[40:41], v[140:141], v[40:41], v[60:61] op_sel_hi:[0,1,1]
	ds_read_b128 v[60:63], v86 offset:176
	v_pk_fma_f32 v[42:43], v[140:141], v[42:43], v[64:65] op_sel_hi:[0,1,1]
	s_waitcnt lgkmcnt(2)
	v_pk_fma_f32 v[40:41], v[140:141], v[44:45], v[40:41] op_sel:[1,0,0]
	v_pk_fma_f32 v[42:43], v[140:141], v[46:47], v[42:43] op_sel:[1,0,0]
	s_waitcnt lgkmcnt(1)
	v_pk_fma_f32 v[40:41], v[142:143], v[56:57], v[40:41] op_sel_hi:[0,1,1]
	v_mov_b32_e32 v44, v143
	v_pk_fma_f32 v[42:43], v[142:143], v[58:59], v[42:43] op_sel_hi:[0,1,1]
	s_waitcnt lgkmcnt(0)
	v_pk_fma_f32 v[40:41], v[44:45], v[60:61], v[40:41] op_sel_hi:[0,1,1]
	v_pk_fma_f32 v[46:47], v[44:45], v[62:63], v[42:43] op_sel_hi:[0,1,1]
	ds_read_b128 v[42:45], v86 offset:192
	ds_read_b128 v[52:55], v86 offset:208
	ds_read_b128 v[56:59], v86 offset:224
	ds_read_b128 v[60:63], v86 offset:240
	s_waitcnt lgkmcnt(3)
	v_pk_fma_f32 v[40:41], v[144:145], v[42:43], v[40:41] op_sel_hi:[0,1,1]
	s_waitcnt lgkmcnt(2)
	v_pk_fma_f32 v[40:41], v[144:145], v[52:53], v[40:41] op_sel:[1,0,0]
	v_mov_b32_e32 v52, v147
	s_waitcnt lgkmcnt(1)
	v_pk_fma_f32 v[40:41], v[146:147], v[56:57], v[40:41] op_sel_hi:[0,1,1]
	s_waitcnt lgkmcnt(0)
; __device__ void ph_filter_gen(const Params& P, int j, const float* __restrict__ a3, float* __restrict__ kf, float* sl) {
;     ...
;         for (int i = 0; i < 8; ++i) { const int t = tid + NT * i; const float4* ar = (const float4*)(a3 + (size_t)t * 64);
;             float a0 = 0.f, a1 = 0.f, a2 = 0.f, a3v = 0.f;
; #pragma unroll 4
;             for (int jq = 0; jq < 16; ++jq) { const float4 av = ar[jq]; const float ae[4] = {av.x, av.y, av.z, av.w};
; #pragma unroll
;                 for (int e = 0; e < 4; ++e) { const float4 wv = *(const float4*)(sw + (jq * 4 + e) * 4); a0 += ae[e] * wv.x; a1 += ae[e] * wv.y; a2 += ae[e] * wv.z; a3v += ae[e] * wv.w; } }
;             const float dec = expf(-((float)t / (float)(SEQ - 1)) * delta);
;             hv[i][0] = a0 * dec; hv[i][1] = a1 * dec; hv[i][2] = a2 * dec; hv[i][3] = a3v * dec;
	v_pk_fma_f32 v[42:43], v[52:53], v[60:61], v[40:41] op_sel_hi:[0,1,1]
	v_pk_fma_f32 v[40:41], v[144:145], v[44:45], v[46:47] op_sel_hi:[0,1,1]
	v_pk_fma_f32 v[40:41], v[144:145], v[54:55], v[40:41] op_sel:[1,0,0]
	s_nop 0
	v_pk_fma_f32 v[40:41], v[146:147], v[58:59], v[40:41] op_sel_hi:[0,1,1]
	v_pk_fma_f32 v[40:41], v[52:53], v[62:63], v[40:41] op_sel_hi:[0,1,1]
	s_add_u32 s100, s78, 0x1e840000
	s_addc_u32 s101, s79, 0
	global_load_dword v132, v113, s[100:101]
	s_add_u32 s100, s100, 0x4000
	s_addc_u32 s101, s101, 0
	global_load_dword v133, v113, s[100:101]
	s_add_u32 s100, s100, 0x4000
	s_addc_u32 s101, s101, 0
	global_load_dword v134, v113, s[100:101]
	s_add_u32 s100, s100, 0x4000
	s_addc_u32 s101, s101, 0
	global_load_dword v135, v113, s[100:101]
	s_add_u32 s100, s100, 0x4000
	s_addc_u32 s101, s101, 0
	global_load_dword v136, v113, s[100:101]
	s_add_u32 s100, s100, 0x4000
	s_addc_u32 s101, s101, 0
	global_load_dword v137, v113, s[100:101]
	s_add_u32 s100, s100, 0x4000
	s_addc_u32 s101, s101, 0
	global_load_dword v138, v113, s[100:101]
	s_add_u32 s100, s100, 0x4000
	s_addc_u32 s101, s101, 0
	global_load_dword v139, v113, s[100:101]
	s_add_u32 s100, s100, 0x4000
	s_addc_u32 s101, s101, 0
	global_load_dword v140, v113, s[100:101]
	s_add_u32 s100, s100, 0x4000
	s_addc_u32 s101, s101, 0
	global_load_dword v141, v113, s[100:101]
	s_add_u32 s100, s100, 0x4000
	s_addc_u32 s101, s101, 0
	global_load_dword v142, v113, s[100:101]
	s_add_u32 s100, s100, 0x4000
	s_addc_u32 s101, s101, 0
	global_load_dword v143, v113, s[100:101]
	s_add_u32 s100, s100, 0x4000
	s_addc_u32 s101, s101, 0
	global_load_dword v144, v113, s[100:101]
	s_add_u32 s100, s100, 0x4000
	s_addc_u32 s101, s101, 0
	global_load_dword v145, v113, s[100:101]
	s_add_u32 s100, s100, 0x4000
	s_addc_u32 s101, s101, 0
	global_load_dword v146, v113, s[100:101]
	s_add_u32 s100, s100, 0x4000
	s_addc_u32 s101, s101, 0
	global_load_dword v147, v113, s[100:101]
	s_waitcnt vmcnt(48)
	v_mov_b32_e32 v86, 0x200
	ds_read_b128 v[60:63], v86
	ds_read_b128 v[64:67], v86 offset:16
	ds_read_b128 v[78:81], v86 offset:32
	ds_read_b128 v[82:85], v86 offset:48
	s_waitcnt lgkmcnt(3)
	v_pk_fma_f32 v[42:43], v[148:149], v[60:61], v[42:43] op_sel_hi:[0,1,1]
	v_pk_fma_f32 v[40:41], v[148:149], v[62:63], v[40:41] op_sel_hi:[0,1,1]
	s_waitcnt lgkmcnt(2)
	v_pk_fma_f32 v[42:43], v[148:149], v[64:65], v[42:43] op_sel:[1,0,0]
	v_pk_fma_f32 v[40:41], v[148:149], v[66:67], v[40:41] op_sel:[1,0,0]
	s_waitcnt lgkmcnt(1)
	v_pk_fma_f32 v[42:43], v[150:151], v[78:79], v[42:43] op_sel_hi:[0,1,1]
	v_mov_b32_e32 v60, v151
	v_pk_fma_f32 v[40:41], v[150:151], v[80:81], v[40:41] op_sel_hi:[0,1,1]
	s_waitcnt lgkmcnt(0)
	v_pk_fma_f32 v[64:65], v[60:61], v[82:83], v[42:43] op_sel_hi:[0,1,1]
	v_pk_fma_f32 v[78:79], v[60:61], v[84:85], v[40:41] op_sel_hi:[0,1,1]
	ds_read_b128 v[40:43], v86 offset:64
	ds_read_b128 v[44:47], v86 offset:80
	ds_read_b128 v[60:63], v86 offset:96
	s_waitcnt lgkmcnt(2)
	v_pk_fma_f32 v[40:41], v[152:153], v[40:41], v[64:65] op_sel_hi:[0,1,1]
	ds_read_b128 v[64:67], v86 offset:112
	s_waitcnt lgkmcnt(2)
	v_pk_fma_f32 v[40:41], v[152:153], v[44:45], v[40:41] op_sel:[1,0,0]
	v_mov_b32_e32 v44, v155
	s_waitcnt lgkmcnt(1)
	v_pk_fma_f32 v[40:41], v[154:155], v[60:61], v[40:41] op_sel_hi:[0,1,1]
	s_waitcnt lgkmcnt(0)
	v_pk_fma_f32 v[60:61], v[44:45], v[64:65], v[40:41] op_sel_hi:[0,1,1]
	v_pk_fma_f32 v[40:41], v[152:153], v[42:43], v[78:79] op_sel_hi:[0,1,1]
	v_pk_fma_f32 v[40:41], v[152:153], v[46:47], v[40:41] op_sel:[1,0,0]
	s_nop 0
	v_pk_fma_f32 v[40:41], v[154:155], v[62:63], v[40:41] op_sel_hi:[0,1,1]
	v_pk_fma_f32 v[64:65], v[44:45], v[66:67], v[40:41] op_sel_hi:[0,1,1]
	ds_read_b128 v[40:43], v86 offset:128
	ds_read_b128 v[44:47], v86 offset:144
	ds_read_b128 v[56:59], v86 offset:160
	s_waitcnt lgkmcnt(2)
	v_pk_fma_f32 v[40:41], v[156:157], v[40:41], v[60:61] op_sel_hi:[0,1,1]
	ds_read_b128 v[60:63], v86 offset:176
	v_pk_fma_f32 v[42:43], v[156:157], v[42:43], v[64:65] op_sel_hi:[0,1,1]
	s_waitcnt lgkmcnt(2)
	v_pk_fma_f32 v[40:41], v[156:157], v[44:45], v[40:41] op_sel:[1,0,0]
	v_pk_fma_f32 v[42:43], v[156:157], v[46:47], v[42:43] op_sel:[1,0,0]
	s_waitcnt lgkmcnt(1)
	v_pk_fma_f32 v[40:41], v[158:159], v[56:57], v[40:41] op_sel_hi:[0,1,1]
	v_mov_b32_e32 v44, v159
	v_pk_fma_f32 v[42:43], v[158:159], v[58:59], v[42:43] op_sel_hi:[0,1,1]
	s_waitcnt lgkmcnt(0)
	v_pk_fma_f32 v[40:41], v[44:45], v[60:61], v[40:41] op_sel_hi:[0,1,1]
	v_pk_fma_f32 v[46:47], v[44:45], v[62:63], v[42:43] op_sel_hi:[0,1,1]
	ds_read_b128 v[42:45], v86 offset:192
	ds_read_b128 v[52:55], v86 offset:208
	ds_read_b128 v[56:59], v86 offset:224
	ds_read_b128 v[60:63], v86 offset:240
	s_waitcnt lgkmcnt(3)
	v_pk_fma_f32 v[40:41], v[160:161], v[42:43], v[40:41] op_sel_hi:[0,1,1]
	s_waitcnt lgkmcnt(2)
	v_pk_fma_f32 v[40:41], v[160:161], v[52:53], v[40:41] op_sel:[1,0,0]
	v_mov_b32_e32 v52, v163
	s_waitcnt lgkmcnt(1)
	v_pk_fma_f32 v[40:41], v[162:163], v[56:57], v[40:41] op_sel_hi:[0,1,1]
	s_waitcnt lgkmcnt(0)
; __device__ void ph_filter_gen(const Params& P, int j, const float* __restrict__ a3, float* __restrict__ kf, float* sl) {
;     ...
;         for (int i = 0; i < 8; ++i) { const int t = tid + NT * i; const float4* ar = (const float4*)(a3 + (size_t)t * 64);
;             float a0 = 0.f, a1 = 0.f, a2 = 0.f, a3v = 0.f;
; #pragma unroll 4
;             for (int jq = 0; jq < 16; ++jq) { const float4 av = ar[jq]; const float ae[4] = {av.x, av.y, av.z, av.w};
; #pragma unroll
;                 for (int e = 0; e < 4; ++e) { const float4 wv = *(const float4*)(sw + (jq * 4 + e) * 4); a0 += ae[e] * wv.x; a1 += ae[e] * wv.y; a2 += ae[e] * wv.z; a3v += ae[e] * wv.w; } }
;             const float dec = expf(-((float)t / (float)(SEQ - 1)) * delta);
;             hv[i][0] = a0 * dec; hv[i][1] = a1 * dec; hv[i][2] = a2 * dec; hv[i][3] = a3v * dec;
	v_pk_fma_f32 v[42:43], v[52:53], v[60:61], v[40:41] op_sel_hi:[0,1,1]
	v_pk_fma_f32 v[40:41], v[160:161], v[44:45], v[46:47] op_sel_hi:[0,1,1]
	v_pk_fma_f32 v[40:41], v[160:161], v[54:55], v[40:41] op_sel:[1,0,0]
	s_nop 0
	v_pk_fma_f32 v[40:41], v[162:163], v[58:59], v[40:41] op_sel_hi:[0,1,1]
	v_pk_fma_f32 v[40:41], v[52:53], v[62:63], v[40:41] op_sel_hi:[0,1,1]
	s_add_u32 s100, s78, 0x1e880000
	s_addc_u32 s101, s79, 0
	global_load_dword v148, v113, s[100:101]
	s_add_u32 s100, s100, 0x4000
	s_addc_u32 s101, s101, 0
	global_load_dword v149, v113, s[100:101]
	s_add_u32 s100, s100, 0x4000
	s_addc_u32 s101, s101, 0
	global_load_dword v150, v113, s[100:101]
	s_add_u32 s100, s100, 0x4000
	s_addc_u32 s101, s101, 0
	global_load_dword v151, v113, s[100:101]
	s_add_u32 s100, s100, 0x4000
	s_addc_u32 s101, s101, 0
	global_load_dword v152, v113, s[100:101]
	s_add_u32 s100, s100, 0x4000
	s_addc_u32 s101, s101, 0
	global_load_dword v153, v113, s[100:101]
	s_add_u32 s100, s100, 0x4000
	s_addc_u32 s101, s101, 0
	global_load_dword v154, v113, s[100:101]
	s_add_u32 s100, s100, 0x4000
	s_addc_u32 s101, s101, 0
	global_load_dword v155, v113, s[100:101]
	s_add_u32 s100, s100, 0x4000
	s_addc_u32 s101, s101, 0
	global_load_dword v156, v113, s[100:101]
	s_add_u32 s100, s100, 0x4000
	s_addc_u32 s101, s101, 0
	global_load_dword v157, v113, s[100:101]
	s_add_u32 s100, s100, 0x4000
	s_addc_u32 s101, s101, 0
	global_load_dword v158, v113, s[100:101]
	s_add_u32 s100, s100, 0x4000
	s_addc_u32 s101, s101, 0
	global_load_dword v159, v113, s[100:101]
	s_add_u32 s100, s100, 0x4000
	s_addc_u32 s101, s101, 0
	global_load_dword v160, v113, s[100:101]
	s_add_u32 s100, s100, 0x4000
	s_addc_u32 s101, s101, 0
	global_load_dword v161, v113, s[100:101]
	s_add_u32 s100, s100, 0x4000
	s_addc_u32 s101, s101, 0
	global_load_dword v162, v113, s[100:101]
	s_add_u32 s100, s100, 0x4000
	s_addc_u32 s101, s101, 0
	global_load_dword v163, v113, s[100:101]
	s_waitcnt vmcnt(48)
	v_mov_b32_e32 v86, 0x300
	ds_read_b128 v[60:63], v86
	ds_read_b128 v[64:67], v86 offset:16
	ds_read_b128 v[78:81], v86 offset:32
	ds_read_b128 v[82:85], v86 offset:48
	s_waitcnt lgkmcnt(3)
	v_pk_fma_f32 v[42:43], v[164:165], v[60:61], v[42:43] op_sel_hi:[0,1,1]
	v_pk_fma_f32 v[40:41], v[164:165], v[62:63], v[40:41] op_sel_hi:[0,1,1]
	s_waitcnt lgkmcnt(2)
	v_pk_fma_f32 v[42:43], v[164:165], v[64:65], v[42:43] op_sel:[1,0,0]
	v_pk_fma_f32 v[40:41], v[164:165], v[66:67], v[40:41] op_sel:[1,0,0]
	s_waitcnt lgkmcnt(1)
	v_pk_fma_f32 v[42:43], v[166:167], v[78:79], v[42:43] op_sel_hi:[0,1,1]
	v_mov_b32_e32 v60, v167
	v_pk_fma_f32 v[40:41], v[166:167], v[80:81], v[40:41] op_sel_hi:[0,1,1]
	s_waitcnt lgkmcnt(0)
	v_pk_fma_f32 v[64:65], v[60:61], v[82:83], v[42:43] op_sel_hi:[0,1,1]
	v_pk_fma_f32 v[78:79], v[60:61], v[84:85], v[40:41] op_sel_hi:[0,1,1]
	ds_read_b128 v[40:43], v86 offset:64
	ds_read_b128 v[44:47], v86 offset:80
	ds_read_b128 v[60:63], v86 offset:96
	s_waitcnt lgkmcnt(2)
	v_pk_fma_f32 v[40:41], v[168:169], v[40:41], v[64:65] op_sel_hi:[0,1,1]
	ds_read_b128 v[64:67], v86 offset:112
	s_waitcnt lgkmcnt(2)
	v_pk_fma_f32 v[40:41], v[168:169], v[44:45], v[40:41] op_sel:[1,0,0]
	v_mov_b32_e32 v44, v171
	s_waitcnt lgkmcnt(1)
	v_pk_fma_f32 v[40:41], v[170:171], v[60:61], v[40:41] op_sel_hi:[0,1,1]
	s_waitcnt lgkmcnt(0)
	v_pk_fma_f32 v[60:61], v[44:45], v[64:65], v[40:41] op_sel_hi:[0,1,1]
	v_pk_fma_f32 v[40:41], v[168:169], v[42:43], v[78:79] op_sel_hi:[0,1,1]
	v_pk_fma_f32 v[40:41], v[168:169], v[46:47], v[40:41] op_sel:[1,0,0]
	s_nop 0
	v_pk_fma_f32 v[40:41], v[170:171], v[62:63], v[40:41] op_sel_hi:[0,1,1]
	v_pk_fma_f32 v[64:65], v[44:45], v[66:67], v[40:41] op_sel_hi:[0,1,1]
	ds_read_b128 v[40:43], v86 offset:128
	ds_read_b128 v[44:47], v86 offset:144
	ds_read_b128 v[56:59], v86 offset:160
	s_waitcnt lgkmcnt(2)
	v_pk_fma_f32 v[40:41], v[172:173], v[40:41], v[60:61] op_sel_hi:[0,1,1]
	ds_read_b128 v[60:63], v86 offset:176
	v_pk_fma_f32 v[42:43], v[172:173], v[42:43], v[64:65] op_sel_hi:[0,1,1]
	s_waitcnt lgkmcnt(2)
	v_pk_fma_f32 v[40:41], v[172:173], v[44:45], v[40:41] op_sel:[1,0,0]
	v_pk_fma_f32 v[42:43], v[172:173], v[46:47], v[42:43] op_sel:[1,0,0]
	s_waitcnt lgkmcnt(1)
	v_pk_fma_f32 v[40:41], v[174:175], v[56:57], v[40:41] op_sel_hi:[0,1,1]
	v_mov_b32_e32 v44, v175
	v_pk_fma_f32 v[42:43], v[174:175], v[58:59], v[42:43] op_sel_hi:[0,1,1]
	s_waitcnt lgkmcnt(0)
	v_pk_fma_f32 v[40:41], v[44:45], v[60:61], v[40:41] op_sel_hi:[0,1,1]
	v_pk_fma_f32 v[46:47], v[44:45], v[62:63], v[42:43] op_sel_hi:[0,1,1]
	ds_read_b128 v[42:45], v86 offset:192
	ds_read_b128 v[52:55], v86 offset:208
	ds_read_b128 v[56:59], v86 offset:224
	ds_read_b128 v[60:63], v86 offset:240
	s_waitcnt lgkmcnt(3)
	v_pk_fma_f32 v[40:41], v[176:177], v[42:43], v[40:41] op_sel_hi:[0,1,1]
	s_waitcnt lgkmcnt(2)
	v_pk_fma_f32 v[40:41], v[176:177], v[52:53], v[40:41] op_sel:[1,0,0]
	v_mov_b32_e32 v52, v179
	s_waitcnt lgkmcnt(1)
	v_pk_fma_f32 v[40:41], v[178:179], v[56:57], v[40:41] op_sel_hi:[0,1,1]
	s_waitcnt lgkmcnt(0)
; __device__ void ph_filter_gen(const Params& P, int j, const float* __restrict__ a3, float* __restrict__ kf, float* sl) {
;     ...
;         for (int i = 0; i < 8; ++i) { const int t = tid + NT * i; const float4* ar = (const float4*)(a3 + (size_t)t * 64);
;             float a0 = 0.f, a1 = 0.f, a2 = 0.f, a3v = 0.f;
; #pragma unroll 4
;             for (int jq = 0; jq < 16; ++jq) { const float4 av = ar[jq]; const float ae[4] = {av.x, av.y, av.z, av.w};
; #pragma unroll
;                 for (int e = 0; e < 4; ++e) { const float4 wv = *(const float4*)(sw + (jq * 4 + e) * 4); a0 += ae[e] * wv.x; a1 += ae[e] * wv.y; a2 += ae[e] * wv.z; a3v += ae[e] * wv.w; } }
;             const float dec = expf(-((float)t / (float)(SEQ - 1)) * delta);
;             hv[i][0] = a0 * dec; hv[i][1] = a1 * dec; hv[i][2] = a2 * dec; hv[i][3] = a3v * dec;
	v_pk_fma_f32 v[42:43], v[52:53], v[60:61], v[40:41] op_sel_hi:[0,1,1]
	v_pk_fma_f32 v[40:41], v[176:177], v[44:45], v[46:47] op_sel_hi:[0,1,1]
	v_pk_fma_f32 v[40:41], v[176:177], v[54:55], v[40:41] op_sel:[1,0,0]
	s_nop 0
	v_pk_fma_f32 v[40:41], v[178:179], v[58:59], v[40:41] op_sel_hi:[0,1,1]
	v_pk_fma_f32 v[40:41], v[52:53], v[62:63], v[40:41] op_sel_hi:[0,1,1]
	s_add_u32 s100, s78, 0x1e8c0000
	s_addc_u32 s101, s79, 0
	global_load_dword v164, v113, s[100:101]
	s_add_u32 s100, s100, 0x4000
	s_addc_u32 s101, s101, 0
	global_load_dword v165, v113, s[100:101]
	s_add_u32 s100, s100, 0x4000
	s_addc_u32 s101, s101, 0
	global_load_dword v166, v113, s[100:101]
	s_add_u32 s100, s100, 0x4000
	s_addc_u32 s101, s101, 0
	global_load_dword v167, v113, s[100:101]
	s_add_u32 s100, s100, 0x4000
	s_addc_u32 s101, s101, 0
	global_load_dword v168, v113, s[100:101]
	s_add_u32 s100, s100, 0x4000
	s_addc_u32 s101, s101, 0
	global_load_dword v169, v113, s[100:101]
	s_add_u32 s100, s100, 0x4000
	s_addc_u32 s101, s101, 0
	global_load_dword v170, v113, s[100:101]
	s_add_u32 s100, s100, 0x4000
	s_addc_u32 s101, s101, 0
	global_load_dword v171, v113, s[100:101]
	s_add_u32 s100, s100, 0x4000
	s_addc_u32 s101, s101, 0
	global_load_dword v172, v113, s[100:101]
	s_add_u32 s100, s100, 0x4000
	s_addc_u32 s101, s101, 0
	global_load_dword v173, v113, s[100:101]
	s_add_u32 s100, s100, 0x4000
	s_addc_u32 s101, s101, 0
	global_load_dword v174, v113, s[100:101]
	s_add_u32 s100, s100, 0x4000
	s_addc_u32 s101, s101, 0
	global_load_dword v175, v113, s[100:101]
	s_add_u32 s100, s100, 0x4000
	s_addc_u32 s101, s101, 0
	global_load_dword v176, v113, s[100:101]
	s_add_u32 s100, s100, 0x4000
	s_addc_u32 s101, s101, 0
	global_load_dword v177, v113, s[100:101]
	s_add_u32 s100, s100, 0x4000
	s_addc_u32 s101, s101, 0
	global_load_dword v178, v113, s[100:101]
	s_add_u32 s100, s100, 0x4000
	s_addc_u32 s101, s101, 0
	global_load_dword v179, v113, s[100:101]
	v_mov_b32_e32 v46, 0
	s_mov_b32 s0, 0
	s_mov_b64 s[14:15], 0
	v_mov_b32_e32 v47, v46
	v_mov_b32_e32 v44, v46
	v_mov_b32_e32 v45, v46
.LBB0_225:
	v_add_u32_e32 v113, 0x1800, v68
	s_waitcnt vmcnt(48)
	v_mov_b32_e32 v90, 0
	ds_read_b128 v[64:67], v90
	ds_read_b128 v[78:81], v90 offset:16
	ds_read_b128 v[82:85], v90 offset:32
	ds_read_b128 v[86:89], v90 offset:48
	s_waitcnt lgkmcnt(3)
	v_pk_fma_f32 v[46:47], v[116:117], v[64:65], v[46:47] op_sel_hi:[0,1,1]
	v_pk_fma_f32 v[44:45], v[116:117], v[66:67], v[44:45] op_sel_hi:[0,1,1]
	s_waitcnt lgkmcnt(2)
	v_pk_fma_f32 v[46:47], v[116:117], v[78:79], v[46:47] op_sel:[1,0,0]
	v_pk_fma_f32 v[44:45], v[116:117], v[80:81], v[44:45] op_sel:[1,0,0]
	s_waitcnt lgkmcnt(1)
	v_pk_fma_f32 v[46:47], v[118:119], v[82:83], v[46:47] op_sel_hi:[0,1,1]
	v_mov_b32_e32 v64, v119
	v_pk_fma_f32 v[44:45], v[118:119], v[84:85], v[44:45] op_sel_hi:[0,1,1]
	s_waitcnt lgkmcnt(0)
	v_pk_fma_f32 v[78:79], v[64:65], v[86:87], v[46:47] op_sel_hi:[0,1,1]
	v_pk_fma_f32 v[82:83], v[64:65], v[88:89], v[44:45] op_sel_hi:[0,1,1]
	ds_read_b128 v[44:47], v90 offset:64
	ds_read_b128 v[48:51], v90 offset:80
	ds_read_b128 v[64:67], v90 offset:96
	s_waitcnt lgkmcnt(2)
	v_pk_fma_f32 v[44:45], v[120:121], v[44:45], v[78:79] op_sel_hi:[0,1,1]
	ds_read_b128 v[78:81], v90 offset:112
	s_waitcnt lgkmcnt(2)
	v_pk_fma_f32 v[44:45], v[120:121], v[48:49], v[44:45] op_sel:[1,0,0]
	v_mov_b32_e32 v48, v123
	s_waitcnt lgkmcnt(1)
	v_pk_fma_f32 v[44:45], v[122:123], v[64:65], v[44:45] op_sel_hi:[0,1,1]
	s_waitcnt lgkmcnt(0)
	v_pk_fma_f32 v[64:65], v[48:49], v[78:79], v[44:45] op_sel_hi:[0,1,1]
	v_pk_fma_f32 v[44:45], v[120:121], v[46:47], v[82:83] op_sel_hi:[0,1,1]
	v_pk_fma_f32 v[44:45], v[120:121], v[50:51], v[44:45] op_sel:[1,0,0]
	s_nop 0
	v_pk_fma_f32 v[44:45], v[122:123], v[66:67], v[44:45] op_sel_hi:[0,1,1]
	v_pk_fma_f32 v[78:79], v[48:49], v[80:81], v[44:45] op_sel_hi:[0,1,1]
	ds_read_b128 v[44:47], v90 offset:128
	ds_read_b128 v[48:51], v90 offset:144
	ds_read_b128 v[60:63], v90 offset:160
	s_waitcnt lgkmcnt(2)
	v_pk_fma_f32 v[44:45], v[124:125], v[44:45], v[64:65] op_sel_hi:[0,1,1]
	ds_read_b128 v[64:67], v90 offset:176
	v_pk_fma_f32 v[46:47], v[124:125], v[46:47], v[78:79] op_sel_hi:[0,1,1]
	s_waitcnt lgkmcnt(2)
	v_pk_fma_f32 v[44:45], v[124:125], v[48:49], v[44:45] op_sel:[1,0,0]
	v_pk_fma_f32 v[46:47], v[124:125], v[50:51], v[46:47] op_sel:[1,0,0]
	s_waitcnt lgkmcnt(1)
	v_pk_fma_f32 v[44:45], v[126:127], v[60:61], v[44:45] op_sel_hi:[0,1,1]
	v_mov_b32_e32 v48, v127
	v_pk_fma_f32 v[46:47], v[126:127], v[62:63], v[46:47] op_sel_hi:[0,1,1]
	s_waitcnt lgkmcnt(0)
	v_pk_fma_f32 v[44:45], v[48:49], v[64:65], v[44:45] op_sel_hi:[0,1,1]
	v_pk_fma_f32 v[50:51], v[48:49], v[66:67], v[46:47] op_sel_hi:[0,1,1]
	ds_read_b128 v[46:49], v90 offset:192
	ds_read_b128 v[56:59], v90 offset:208
	ds_read_b128 v[60:63], v90 offset:224
	ds_read_b128 v[64:67], v90 offset:240
	s_waitcnt lgkmcnt(3)
	v_pk_fma_f32 v[44:45], v[128:129], v[46:47], v[44:45] op_sel_hi:[0,1,1]
	s_waitcnt lgkmcnt(2)
	v_pk_fma_f32 v[44:45], v[128:129], v[56:57], v[44:45] op_sel:[1,0,0]
	v_mov_b32_e32 v56, v131
	s_waitcnt lgkmcnt(1)
	v_pk_fma_f32 v[44:45], v[130:131], v[60:61], v[44:45] op_sel_hi:[0,1,1]
	s_waitcnt lgkmcnt(0)
; __device__ void ph_filter_gen(const Params& P, int j, const float* __restrict__ a3, float* __restrict__ kf, float* sl) {
;     ...
;         for (int i = 0; i < 8; ++i) { const int t = tid + NT * i; const float4* ar = (const float4*)(a3 + (size_t)t * 64);
;             float a0 = 0.f, a1 = 0.f, a2 = 0.f, a3v = 0.f;
; #pragma unroll 4
;             for (int jq = 0; jq < 16; ++jq) { const float4 av = ar[jq]; const float ae[4] = {av.x, av.y, av.z, av.w};
; #pragma unroll
;                 for (int e = 0; e < 4; ++e) { const float4 wv = *(const float4*)(sw + (jq * 4 + e) * 4); a0 += ae[e] * wv.x; a1 += ae[e] * wv.y; a2 += ae[e] * wv.z; a3v += ae[e] * wv.w; } }
;             const float dec = expf(-((float)t / (float)(SEQ - 1)) * delta);
;             hv[i][0] = a0 * dec; hv[i][1] = a1 * dec; hv[i][2] = a2 * dec; hv[i][3] = a3v * dec;
	v_pk_fma_f32 v[46:47], v[56:57], v[64:65], v[44:45] op_sel_hi:[0,1,1]
	v_pk_fma_f32 v[44:45], v[128:129], v[48:49], v[50:51] op_sel_hi:[0,1,1]
	v_pk_fma_f32 v[44:45], v[128:129], v[58:59], v[44:45] op_sel:[1,0,0]
	s_nop 0
	v_pk_fma_f32 v[44:45], v[130:131], v[62:63], v[44:45] op_sel_hi:[0,1,1]
	v_pk_fma_f32 v[44:45], v[56:57], v[66:67], v[44:45] op_sel_hi:[0,1,1]
	s_add_u32 s100, s78, 0x1e800000
	s_addc_u32 s101, s79, 0
	global_load_dword v116, v113, s[100:101]
	s_add_u32 s100, s100, 0x4000
	s_addc_u32 s101, s101, 0
	global_load_dword v117, v113, s[100:101]
	s_add_u32 s100, s100, 0x4000
	s_addc_u32 s101, s101, 0
	global_load_dword v118, v113, s[100:101]
	s_add_u32 s100, s100, 0x4000
	s_addc_u32 s101, s101, 0
	global_load_dword v119, v113, s[100:101]
	s_add_u32 s100, s100, 0x4000
	s_addc_u32 s101, s101, 0
	global_load_dword v120, v113, s[100:101]
	s_add_u32 s100, s100, 0x4000
	s_addc_u32 s101, s101, 0
	global_load_dword v121, v113, s[100:101]
	s_add_u32 s100, s100, 0x4000
	s_addc_u32 s101, s101, 0
	global_load_dword v122, v113, s[100:101]
	s_add_u32 s100, s100, 0x4000
	s_addc_u32 s101, s101, 0
	global_load_dword v123, v113, s[100:101]
	s_add_u32 s100, s100, 0x4000
	s_addc_u32 s101, s101, 0
	global_load_dword v124, v113, s[100:101]
	s_add_u32 s100, s100, 0x4000
	s_addc_u32 s101, s101, 0
	global_load_dword v125, v113, s[100:101]
	s_add_u32 s100, s100, 0x4000
	s_addc_u32 s101, s101, 0
	global_load_dword v126, v113, s[100:101]
	s_add_u32 s100, s100, 0x4000
	s_addc_u32 s101, s101, 0
	global_load_dword v127, v113, s[100:101]
	s_add_u32 s100, s100, 0x4000
	s_addc_u32 s101, s101, 0
	global_load_dword v128, v113, s[100:101]
	s_add_u32 s100, s100, 0x4000
	s_addc_u32 s101, s101, 0
	global_load_dword v129, v113, s[100:101]
	s_add_u32 s100, s100, 0x4000
	s_addc_u32 s101, s101, 0
	global_load_dword v130, v113, s[100:101]
	s_add_u32 s100, s100, 0x4000
	s_addc_u32 s101, s101, 0
	global_load_dword v131, v113, s[100:101]
	s_waitcnt vmcnt(48)
	v_mov_b32_e32 v90, 0x100
	ds_read_b128 v[64:67], v90
	ds_read_b128 v[78:81], v90 offset:16
	ds_read_b128 v[82:85], v90 offset:32
	ds_read_b128 v[86:89], v90 offset:48
	s_waitcnt lgkmcnt(3)
	v_pk_fma_f32 v[46:47], v[132:133], v[64:65], v[46:47] op_sel_hi:[0,1,1]
	v_pk_fma_f32 v[44:45], v[132:133], v[66:67], v[44:45] op_sel_hi:[0,1,1]
	s_waitcnt lgkmcnt(2)
	v_pk_fma_f32 v[46:47], v[132:133], v[78:79], v[46:47] op_sel:[1,0,0]
	v_pk_fma_f32 v[44:45], v[132:133], v[80:81], v[44:45] op_sel:[1,0,0]
	s_waitcnt lgkmcnt(1)
	v_pk_fma_f32 v[46:47], v[134:135], v[82:83], v[46:47] op_sel_hi:[0,1,1]
	v_mov_b32_e32 v64, v135
	v_pk_fma_f32 v[44:45], v[134:135], v[84:85], v[44:45] op_sel_hi:[0,1,1]
	s_waitcnt lgkmcnt(0)
	v_pk_fma_f32 v[78:79], v[64:65], v[86:87], v[46:47] op_sel_hi:[0,1,1]
	v_pk_fma_f32 v[82:83], v[64:65], v[88:89], v[44:45] op_sel_hi:[0,1,1]
	ds_read_b128 v[44:47], v90 offset:64
	ds_read_b128 v[48:51], v90 offset:80
	ds_read_b128 v[64:67], v90 offset:96
	s_waitcnt lgkmcnt(2)
	v_pk_fma_f32 v[44:45], v[136:137], v[44:45], v[78:79] op_sel_hi:[0,1,1]
	ds_read_b128 v[78:81], v90 offset:112
	s_waitcnt lgkmcnt(2)
	v_pk_fma_f32 v[44:45], v[136:137], v[48:49], v[44:45] op_sel:[1,0,0]
	v_mov_b32_e32 v48, v139
	s_waitcnt lgkmcnt(1)
	v_pk_fma_f32 v[44:45], v[138:139], v[64:65], v[44:45] op_sel_hi:[0,1,1]
	s_waitcnt lgkmcnt(0)
	v_pk_fma_f32 v[64:65], v[48:49], v[78:79], v[44:45] op_sel_hi:[0,1,1]
	v_pk_fma_f32 v[44:45], v[136:137], v[46:47], v[82:83] op_sel_hi:[0,1,1]
	v_pk_fma_f32 v[44:45], v[136:137], v[50:51], v[44:45] op_sel:[1,0,0]
	s_nop 0
	v_pk_fma_f32 v[44:45], v[138:139], v[66:67], v[44:45] op_sel_hi:[0,1,1]
	v_pk_fma_f32 v[78:79], v[48:49], v[80:81], v[44:45] op_sel_hi:[0,1,1]
	ds_read_b128 v[44:47], v90 offset:128
	ds_read_b128 v[48:51], v90 offset:144
	ds_read_b128 v[60:63], v90 offset:160
	s_waitcnt lgkmcnt(2)
	v_pk_fma_f32 v[44:45], v[140:141], v[44:45], v[64:65] op_sel_hi:[0,1,1]
	ds_read_b128 v[64:67], v90 offset:176
	v_pk_fma_f32 v[46:47], v[140:141], v[46:47], v[78:79] op_sel_hi:[0,1,1]
	s_waitcnt lgkmcnt(2)
	v_pk_fma_f32 v[44:45], v[140:141], v[48:49], v[44:45] op_sel:[1,0,0]
	v_pk_fma_f32 v[46:47], v[140:141], v[50:51], v[46:47] op_sel:[1,0,0]
	s_waitcnt lgkmcnt(1)
	v_pk_fma_f32 v[44:45], v[142:143], v[60:61], v[44:45] op_sel_hi:[0,1,1]
	v_mov_b32_e32 v48, v143
	v_pk_fma_f32 v[46:47], v[142:143], v[62:63], v[46:47] op_sel_hi:[0,1,1]
	s_waitcnt lgkmcnt(0)
	v_pk_fma_f32 v[44:45], v[48:49], v[64:65], v[44:45] op_sel_hi:[0,1,1]
	v_pk_fma_f32 v[50:51], v[48:49], v[66:67], v[46:47] op_sel_hi:[0,1,1]
	ds_read_b128 v[46:49], v90 offset:192
	ds_read_b128 v[56:59], v90 offset:208
	ds_read_b128 v[60:63], v90 offset:224
	ds_read_b128 v[64:67], v90 offset:240
	s_waitcnt lgkmcnt(3)
	v_pk_fma_f32 v[44:45], v[144:145], v[46:47], v[44:45] op_sel_hi:[0,1,1]
	s_waitcnt lgkmcnt(2)
	v_pk_fma_f32 v[44:45], v[144:145], v[56:57], v[44:45] op_sel:[1,0,0]
	v_mov_b32_e32 v56, v147
	s_waitcnt lgkmcnt(1)
	v_pk_fma_f32 v[44:45], v[146:147], v[60:61], v[44:45] op_sel_hi:[0,1,1]
	s_waitcnt lgkmcnt(0)
; __device__ void ph_filter_gen(const Params& P, int j, const float* __restrict__ a3, float* __restrict__ kf, float* sl) {
;     ...
;         for (int i = 0; i < 8; ++i) { const int t = tid + NT * i; const float4* ar = (const float4*)(a3 + (size_t)t * 64);
;             float a0 = 0.f, a1 = 0.f, a2 = 0.f, a3v = 0.f;
; #pragma unroll 4
;             for (int jq = 0; jq < 16; ++jq) { const float4 av = ar[jq]; const float ae[4] = {av.x, av.y, av.z, av.w};
; #pragma unroll
;                 for (int e = 0; e < 4; ++e) { const float4 wv = *(const float4*)(sw + (jq * 4 + e) * 4); a0 += ae[e] * wv.x; a1 += ae[e] * wv.y; a2 += ae[e] * wv.z; a3v += ae[e] * wv.w; } }
;             const float dec = expf(-((float)t / (float)(SEQ - 1)) * delta);
;             hv[i][0] = a0 * dec; hv[i][1] = a1 * dec; hv[i][2] = a2 * dec; hv[i][3] = a3v * dec;
	v_pk_fma_f32 v[46:47], v[56:57], v[64:65], v[44:45] op_sel_hi:[0,1,1]
	v_pk_fma_f32 v[44:45], v[144:145], v[48:49], v[50:51] op_sel_hi:[0,1,1]
	v_pk_fma_f32 v[44:45], v[144:145], v[58:59], v[44:45] op_sel:[1,0,0]
	s_nop 0
	v_pk_fma_f32 v[44:45], v[146:147], v[62:63], v[44:45] op_sel_hi:[0,1,1]
	v_pk_fma_f32 v[44:45], v[56:57], v[66:67], v[44:45] op_sel_hi:[0,1,1]
	s_add_u32 s100, s78, 0x1e840000
	s_addc_u32 s101, s79, 0
	global_load_dword v132, v113, s[100:101]
	s_add_u32 s100, s100, 0x4000
	s_addc_u32 s101, s101, 0
	global_load_dword v133, v113, s[100:101]
	s_add_u32 s100, s100, 0x4000
	s_addc_u32 s101, s101, 0
	global_load_dword v134, v113, s[100:101]
	s_add_u32 s100, s100, 0x4000
	s_addc_u32 s101, s101, 0
	global_load_dword v135, v113, s[100:101]
	s_add_u32 s100, s100, 0x4000
	s_addc_u32 s101, s101, 0
	global_load_dword v136, v113, s[100:101]
	s_add_u32 s100, s100, 0x4000
	s_addc_u32 s101, s101, 0
	global_load_dword v137, v113, s[100:101]
	s_add_u32 s100, s100, 0x4000
	s_addc_u32 s101, s101, 0
	global_load_dword v138, v113, s[100:101]
	s_add_u32 s100, s100, 0x4000
	s_addc_u32 s101, s101, 0
	global_load_dword v139, v113, s[100:101]
	s_add_u32 s100, s100, 0x4000
	s_addc_u32 s101, s101, 0
	global_load_dword v140, v113, s[100:101]
	s_add_u32 s100, s100, 0x4000
	s_addc_u32 s101, s101, 0
	global_load_dword v141, v113, s[100:101]
	s_add_u32 s100, s100, 0x4000
	s_addc_u32 s101, s101, 0
	global_load_dword v142, v113, s[100:101]
	s_add_u32 s100, s100, 0x4000
	s_addc_u32 s101, s101, 0
	global_load_dword v143, v113, s[100:101]
	s_add_u32 s100, s100, 0x4000
	s_addc_u32 s101, s101, 0
	global_load_dword v144, v113, s[100:101]
	s_add_u32 s100, s100, 0x4000
	s_addc_u32 s101, s101, 0
	global_load_dword v145, v113, s[100:101]
	s_add_u32 s100, s100, 0x4000
	s_addc_u32 s101, s101, 0
	global_load_dword v146, v113, s[100:101]
	s_add_u32 s100, s100, 0x4000
	s_addc_u32 s101, s101, 0
	global_load_dword v147, v113, s[100:101]
	s_waitcnt vmcnt(48)
	v_mov_b32_e32 v90, 0x200
	ds_read_b128 v[64:67], v90
	ds_read_b128 v[78:81], v90 offset:16
	ds_read_b128 v[82:85], v90 offset:32
	ds_read_b128 v[86:89], v90 offset:48
	s_waitcnt lgkmcnt(3)
	v_pk_fma_f32 v[46:47], v[148:149], v[64:65], v[46:47] op_sel_hi:[0,1,1]
	v_pk_fma_f32 v[44:45], v[148:149], v[66:67], v[44:45] op_sel_hi:[0,1,1]
	s_waitcnt lgkmcnt(2)
	v_pk_fma_f32 v[46:47], v[148:149], v[78:79], v[46:47] op_sel:[1,0,0]
	v_pk_fma_f32 v[44:45], v[148:149], v[80:81], v[44:45] op_sel:[1,0,0]
	s_waitcnt lgkmcnt(1)
	v_pk_fma_f32 v[46:47], v[150:151], v[82:83], v[46:47] op_sel_hi:[0,1,1]
	v_mov_b32_e32 v64, v151
	v_pk_fma_f32 v[44:45], v[150:151], v[84:85], v[44:45] op_sel_hi:[0,1,1]
	s_waitcnt lgkmcnt(0)
	v_pk_fma_f32 v[78:79], v[64:65], v[86:87], v[46:47] op_sel_hi:[0,1,1]
	v_pk_fma_f32 v[82:83], v[64:65], v[88:89], v[44:45] op_sel_hi:[0,1,1]
	ds_read_b128 v[44:47], v90 offset:64
	ds_read_b128 v[48:51], v90 offset:80
	ds_read_b128 v[64:67], v90 offset:96
	s_waitcnt lgkmcnt(2)
	v_pk_fma_f32 v[44:45], v[152:153], v[44:45], v[78:79] op_sel_hi:[0,1,1]
	ds_read_b128 v[78:81], v90 offset:112
	s_waitcnt lgkmcnt(2)
	v_pk_fma_f32 v[44:45], v[152:153], v[48:49], v[44:45] op_sel:[1,0,0]
	v_mov_b32_e32 v48, v155
	s_waitcnt lgkmcnt(1)
	v_pk_fma_f32 v[44:45], v[154:155], v[64:65], v[44:45] op_sel_hi:[0,1,1]
	s_waitcnt lgkmcnt(0)
	v_pk_fma_f32 v[64:65], v[48:49], v[78:79], v[44:45] op_sel_hi:[0,1,1]
	v_pk_fma_f32 v[44:45], v[152:153], v[46:47], v[82:83] op_sel_hi:[0,1,1]
	v_pk_fma_f32 v[44:45], v[152:153], v[50:51], v[44:45] op_sel:[1,0,0]
	s_nop 0
	v_pk_fma_f32 v[44:45], v[154:155], v[66:67], v[44:45] op_sel_hi:[0,1,1]
	v_pk_fma_f32 v[78:79], v[48:49], v[80:81], v[44:45] op_sel_hi:[0,1,1]
	ds_read_b128 v[44:47], v90 offset:128
	ds_read_b128 v[48:51], v90 offset:144
	ds_read_b128 v[60:63], v90 offset:160
	s_waitcnt lgkmcnt(2)
	v_pk_fma_f32 v[44:45], v[156:157], v[44:45], v[64:65] op_sel_hi:[0,1,1]
	ds_read_b128 v[64:67], v90 offset:176
	v_pk_fma_f32 v[46:47], v[156:157], v[46:47], v[78:79] op_sel_hi:[0,1,1]
	s_waitcnt lgkmcnt(2)
	v_pk_fma_f32 v[44:45], v[156:157], v[48:49], v[44:45] op_sel:[1,0,0]
	v_pk_fma_f32 v[46:47], v[156:157], v[50:51], v[46:47] op_sel:[1,0,0]
	s_waitcnt lgkmcnt(1)
	v_pk_fma_f32 v[44:45], v[158:159], v[60:61], v[44:45] op_sel_hi:[0,1,1]
	v_mov_b32_e32 v48, v159
	v_pk_fma_f32 v[46:47], v[158:159], v[62:63], v[46:47] op_sel_hi:[0,1,1]
	s_waitcnt lgkmcnt(0)
	v_pk_fma_f32 v[44:45], v[48:49], v[64:65], v[44:45] op_sel_hi:[0,1,1]
	v_pk_fma_f32 v[50:51], v[48:49], v[66:67], v[46:47] op_sel_hi:[0,1,1]
	ds_read_b128 v[46:49], v90 offset:192
	ds_read_b128 v[56:59], v90 offset:208
	ds_read_b128 v[60:63], v90 offset:224
	ds_read_b128 v[64:67], v90 offset:240
	s_waitcnt lgkmcnt(3)
	v_pk_fma_f32 v[44:45], v[160:161], v[46:47], v[44:45] op_sel_hi:[0,1,1]
	s_waitcnt lgkmcnt(2)
	v_pk_fma_f32 v[44:45], v[160:161], v[56:57], v[44:45] op_sel:[1,0,0]
	v_mov_b32_e32 v56, v163
	s_waitcnt lgkmcnt(1)
	v_pk_fma_f32 v[44:45], v[162:163], v[60:61], v[44:45] op_sel_hi:[0,1,1]
	s_waitcnt lgkmcnt(0)
; __device__ void ph_filter_gen(const Params& P, int j, const float* __restrict__ a3, float* __restrict__ kf, float* sl) {
;     ...
;         for (int i = 0; i < 8; ++i) { const int t = tid + NT * i; const float4* ar = (const float4*)(a3 + (size_t)t * 64);
;             float a0 = 0.f, a1 = 0.f, a2 = 0.f, a3v = 0.f;
; #pragma unroll 4
;             for (int jq = 0; jq < 16; ++jq) { const float4 av = ar[jq]; const float ae[4] = {av.x, av.y, av.z, av.w};
; #pragma unroll
;                 for (int e = 0; e < 4; ++e) { const float4 wv = *(const float4*)(sw + (jq * 4 + e) * 4); a0 += ae[e] * wv.x; a1 += ae[e] * wv.y; a2 += ae[e] * wv.z; a3v += ae[e] * wv.w; } }
;             const float dec = expf(-((float)t / (float)(SEQ - 1)) * delta);
;             hv[i][0] = a0 * dec; hv[i][1] = a1 * dec; hv[i][2] = a2 * dec; hv[i][3] = a3v * dec;
	v_pk_fma_f32 v[46:47], v[56:57], v[64:65], v[44:45] op_sel_hi:[0,1,1]
	v_pk_fma_f32 v[44:45], v[160:161], v[48:49], v[50:51] op_sel_hi:[0,1,1]
	v_pk_fma_f32 v[44:45], v[160:161], v[58:59], v[44:45] op_sel:[1,0,0]
	s_nop 0
	v_pk_fma_f32 v[44:45], v[162:163], v[62:63], v[44:45] op_sel_hi:[0,1,1]
	v_pk_fma_f32 v[44:45], v[56:57], v[66:67], v[44:45] op_sel_hi:[0,1,1]
	s_add_u32 s100, s78, 0x1e880000
	s_addc_u32 s101, s79, 0
	global_load_dword v148, v113, s[100:101]
	s_add_u32 s100, s100, 0x4000
	s_addc_u32 s101, s101, 0
	global_load_dword v149, v113, s[100:101]
	s_add_u32 s100, s100, 0x4000
	s_addc_u32 s101, s101, 0
	global_load_dword v150, v113, s[100:101]
	s_add_u32 s100, s100, 0x4000
	s_addc_u32 s101, s101, 0
	global_load_dword v151, v113, s[100:101]
	s_add_u32 s100, s100, 0x4000
	s_addc_u32 s101, s101, 0
	global_load_dword v152, v113, s[100:101]
	s_add_u32 s100, s100, 0x4000
	s_addc_u32 s101, s101, 0
	global_load_dword v153, v113, s[100:101]
	s_add_u32 s100, s100, 0x4000
	s_addc_u32 s101, s101, 0
	global_load_dword v154, v113, s[100:101]
	s_add_u32 s100, s100, 0x4000
	s_addc_u32 s101, s101, 0
	global_load_dword v155, v113, s[100:101]
	s_add_u32 s100, s100, 0x4000
	s_addc_u32 s101, s101, 0
	global_load_dword v156, v113, s[100:101]
	s_add_u32 s100, s100, 0x4000
	s_addc_u32 s101, s101, 0
	global_load_dword v157, v113, s[100:101]
	s_add_u32 s100, s100, 0x4000
	s_addc_u32 s101, s101, 0
	global_load_dword v158, v113, s[100:101]
	s_add_u32 s100, s100, 0x4000
	s_addc_u32 s101, s101, 0
	global_load_dword v159, v113, s[100:101]
	s_add_u32 s100, s100, 0x4000
	s_addc_u32 s101, s101, 0
	global_load_dword v160, v113, s[100:101]
	s_add_u32 s100, s100, 0x4000
	s_addc_u32 s101, s101, 0
	global_load_dword v161, v113, s[100:101]
	s_add_u32 s100, s100, 0x4000
	s_addc_u32 s101, s101, 0
	global_load_dword v162, v113, s[100:101]
	s_add_u32 s100, s100, 0x4000
	s_addc_u32 s101, s101, 0
	global_load_dword v163, v113, s[100:101]
	s_waitcnt vmcnt(48)
	v_mov_b32_e32 v90, 0x300
	ds_read_b128 v[64:67], v90
	ds_read_b128 v[78:81], v90 offset:16
	ds_read_b128 v[82:85], v90 offset:32
	ds_read_b128 v[86:89], v90 offset:48
	s_waitcnt lgkmcnt(3)
	v_pk_fma_f32 v[46:47], v[164:165], v[64:65], v[46:47] op_sel_hi:[0,1,1]
	v_pk_fma_f32 v[44:45], v[164:165], v[66:67], v[44:45] op_sel_hi:[0,1,1]
	s_waitcnt lgkmcnt(2)
	v_pk_fma_f32 v[46:47], v[164:165], v[78:79], v[46:47] op_sel:[1,0,0]
	v_pk_fma_f32 v[44:45], v[164:165], v[80:81], v[44:45] op_sel:[1,0,0]
	s_waitcnt lgkmcnt(1)
	v_pk_fma_f32 v[46:47], v[166:167], v[82:83], v[46:47] op_sel_hi:[0,1,1]
	v_mov_b32_e32 v64, v167
	v_pk_fma_f32 v[44:45], v[166:167], v[84:85], v[44:45] op_sel_hi:[0,1,1]
	s_waitcnt lgkmcnt(0)
	v_pk_fma_f32 v[78:79], v[64:65], v[86:87], v[46:47] op_sel_hi:[0,1,1]
	v_pk_fma_f32 v[82:83], v[64:65], v[88:89], v[44:45] op_sel_hi:[0,1,1]
	ds_read_b128 v[44:47], v90 offset:64
	ds_read_b128 v[48:51], v90 offset:80
	ds_read_b128 v[64:67], v90 offset:96
	s_waitcnt lgkmcnt(2)
	v_pk_fma_f32 v[44:45], v[168:169], v[44:45], v[78:79] op_sel_hi:[0,1,1]
	ds_read_b128 v[78:81], v90 offset:112
	s_waitcnt lgkmcnt(2)
	v_pk_fma_f32 v[44:45], v[168:169], v[48:49], v[44:45] op_sel:[1,0,0]
	v_mov_b32_e32 v48, v171
	s_waitcnt lgkmcnt(1)
	v_pk_fma_f32 v[44:45], v[170:171], v[64:65], v[44:45] op_sel_hi:[0,1,1]
	s_waitcnt lgkmcnt(0)
	v_pk_fma_f32 v[64:65], v[48:49], v[78:79], v[44:45] op_sel_hi:[0,1,1]
	v_pk_fma_f32 v[44:45], v[168:169], v[46:47], v[82:83] op_sel_hi:[0,1,1]
	v_pk_fma_f32 v[44:45], v[168:169], v[50:51], v[44:45] op_sel:[1,0,0]
	s_nop 0
	v_pk_fma_f32 v[44:45], v[170:171], v[66:67], v[44:45] op_sel_hi:[0,1,1]
	v_pk_fma_f32 v[78:79], v[48:49], v[80:81], v[44:45] op_sel_hi:[0,1,1]
	ds_read_b128 v[44:47], v90 offset:128
	ds_read_b128 v[48:51], v90 offset:144
	ds_read_b128 v[60:63], v90 offset:160
	s_waitcnt lgkmcnt(2)
	v_pk_fma_f32 v[44:45], v[172:173], v[44:45], v[64:65] op_sel_hi:[0,1,1]
	ds_read_b128 v[64:67], v90 offset:176
	v_pk_fma_f32 v[46:47], v[172:173], v[46:47], v[78:79] op_sel_hi:[0,1,1]
	s_waitcnt lgkmcnt(2)
	v_pk_fma_f32 v[44:45], v[172:173], v[48:49], v[44:45] op_sel:[1,0,0]
	v_pk_fma_f32 v[46:47], v[172:173], v[50:51], v[46:47] op_sel:[1,0,0]
	s_waitcnt lgkmcnt(1)
	v_pk_fma_f32 v[44:45], v[174:175], v[60:61], v[44:45] op_sel_hi:[0,1,1]
	v_mov_b32_e32 v48, v175
	v_pk_fma_f32 v[46:47], v[174:175], v[62:63], v[46:47] op_sel_hi:[0,1,1]
	s_waitcnt lgkmcnt(0)
	v_pk_fma_f32 v[44:45], v[48:49], v[64:65], v[44:45] op_sel_hi:[0,1,1]
	v_pk_fma_f32 v[50:51], v[48:49], v[66:67], v[46:47] op_sel_hi:[0,1,1]
	ds_read_b128 v[46:49], v90 offset:192
	ds_read_b128 v[56:59], v90 offset:208
	ds_read_b128 v[60:63], v90 offset:224
	ds_read_b128 v[64:67], v90 offset:240
	s_waitcnt lgkmcnt(3)
	v_pk_fma_f32 v[44:45], v[176:177], v[46:47], v[44:45] op_sel_hi:[0,1,1]
	s_waitcnt lgkmcnt(2)
	v_pk_fma_f32 v[44:45], v[176:177], v[56:57], v[44:45] op_sel:[1,0,0]
	v_mov_b32_e32 v56, v179
	s_waitcnt lgkmcnt(1)
	v_pk_fma_f32 v[44:45], v[178:179], v[60:61], v[44:45] op_sel_hi:[0,1,1]
	s_waitcnt lgkmcnt(0)
; __device__ void ph_filter_gen(const Params& P, int j, const float* __restrict__ a3, float* __restrict__ kf, float* sl) {
;     ...
;         for (int i = 0; i < 8; ++i) { const int t = tid + NT * i; const float4* ar = (const float4*)(a3 + (size_t)t * 64);
;             float a0 = 0.f, a1 = 0.f, a2 = 0.f, a3v = 0.f;
; #pragma unroll 4
;             for (int jq = 0; jq < 16; ++jq) { const float4 av = ar[jq]; const float ae[4] = {av.x, av.y, av.z, av.w};
; #pragma unroll
;                 for (int e = 0; e < 4; ++e) { const float4 wv = *(const float4*)(sw + (jq * 4 + e) * 4); a0 += ae[e] * wv.x; a1 += ae[e] * wv.y; a2 += ae[e] * wv.z; a3v += ae[e] * wv.w; } }
;             const float dec = expf(-((float)t / (float)(SEQ - 1)) * delta);
;             hv[i][0] = a0 * dec; hv[i][1] = a1 * dec; hv[i][2] = a2 * dec; hv[i][3] = a3v * dec;
	v_pk_fma_f32 v[46:47], v[56:57], v[64:65], v[44:45] op_sel_hi:[0,1,1]
	v_pk_fma_f32 v[44:45], v[176:177], v[48:49], v[50:51] op_sel_hi:[0,1,1]
	v_pk_fma_f32 v[44:45], v[176:177], v[58:59], v[44:45] op_sel:[1,0,0]
	s_nop 0
	v_pk_fma_f32 v[44:45], v[178:179], v[62:63], v[44:45] op_sel_hi:[0,1,1]
	v_pk_fma_f32 v[44:45], v[56:57], v[66:67], v[44:45] op_sel_hi:[0,1,1]
	s_add_u32 s100, s78, 0x1e8c0000
	s_addc_u32 s101, s79, 0
	global_load_dword v164, v113, s[100:101]
	s_add_u32 s100, s100, 0x4000
	s_addc_u32 s101, s101, 0
	global_load_dword v165, v113, s[100:101]
	s_add_u32 s100, s100, 0x4000
	s_addc_u32 s101, s101, 0
	global_load_dword v166, v113, s[100:101]
	s_add_u32 s100, s100, 0x4000
	s_addc_u32 s101, s101, 0
	global_load_dword v167, v113, s[100:101]
	s_add_u32 s100, s100, 0x4000
	s_addc_u32 s101, s101, 0
	global_load_dword v168, v113, s[100:101]
	s_add_u32 s100, s100, 0x4000
	s_addc_u32 s101, s101, 0
	global_load_dword v169, v113, s[100:101]
	s_add_u32 s100, s100, 0x4000
	s_addc_u32 s101, s101, 0
	global_load_dword v170, v113, s[100:101]
	s_add_u32 s100, s100, 0x4000
	s_addc_u32 s101, s101, 0
	global_load_dword v171, v113, s[100:101]
	s_add_u32 s100, s100, 0x4000
	s_addc_u32 s101, s101, 0
	global_load_dword v172, v113, s[100:101]
	s_add_u32 s100, s100, 0x4000
	s_addc_u32 s101, s101, 0
	global_load_dword v173, v113, s[100:101]
	s_add_u32 s100, s100, 0x4000
	s_addc_u32 s101, s101, 0
	global_load_dword v174, v113, s[100:101]
	s_add_u32 s100, s100, 0x4000
	s_addc_u32 s101, s101, 0
	global_load_dword v175, v113, s[100:101]
	s_add_u32 s100, s100, 0x4000
	s_addc_u32 s101, s101, 0
	global_load_dword v176, v113, s[100:101]
	s_add_u32 s100, s100, 0x4000
	s_addc_u32 s101, s101, 0
	global_load_dword v177, v113, s[100:101]
	s_add_u32 s100, s100, 0x4000
	s_addc_u32 s101, s101, 0
	global_load_dword v178, v113, s[100:101]
	s_add_u32 s100, s100, 0x4000
	s_addc_u32 s101, s101, 0
	global_load_dword v179, v113, s[100:101]
	v_mov_b32_e32 v50, 0
	s_mov_b32 s0, 0
	s_mov_b64 s[14:15], 0
	v_mov_b32_e32 v51, v50
	v_mov_b32_e32 v48, v50
	v_mov_b32_e32 v49, v50
.LBB0_227:
	v_add_u32_e32 v113, 0x2000, v68
	s_waitcnt vmcnt(48)
	v_mov_b32_e32 v94, 0
	ds_read_b128 v[78:81], v94
	ds_read_b128 v[82:85], v94 offset:16
	ds_read_b128 v[86:89], v94 offset:32
	ds_read_b128 v[90:93], v94 offset:48
	s_waitcnt lgkmcnt(3)
	v_pk_fma_f32 v[50:51], v[116:117], v[78:79], v[50:51] op_sel_hi:[0,1,1]
	v_pk_fma_f32 v[48:49], v[116:117], v[80:81], v[48:49] op_sel_hi:[0,1,1]
	s_waitcnt lgkmcnt(2)
	v_pk_fma_f32 v[50:51], v[116:117], v[82:83], v[50:51] op_sel:[1,0,0]
	v_pk_fma_f32 v[48:49], v[116:117], v[84:85], v[48:49] op_sel:[1,0,0]
	s_waitcnt lgkmcnt(1)
	v_pk_fma_f32 v[50:51], v[118:119], v[86:87], v[50:51] op_sel_hi:[0,1,1]
	v_mov_b32_e32 v78, v119
	v_pk_fma_f32 v[48:49], v[118:119], v[88:89], v[48:49] op_sel_hi:[0,1,1]
	s_waitcnt lgkmcnt(0)
	v_pk_fma_f32 v[82:83], v[78:79], v[90:91], v[50:51] op_sel_hi:[0,1,1]
	v_pk_fma_f32 v[86:87], v[78:79], v[92:93], v[48:49] op_sel_hi:[0,1,1]
	ds_read_b128 v[48:51], v94 offset:64
	ds_read_b128 v[52:55], v94 offset:80
	ds_read_b128 v[78:81], v94 offset:96
	s_waitcnt lgkmcnt(2)
	v_pk_fma_f32 v[48:49], v[120:121], v[48:49], v[82:83] op_sel_hi:[0,1,1]
	ds_read_b128 v[82:85], v94 offset:112
	s_waitcnt lgkmcnt(2)
	v_pk_fma_f32 v[48:49], v[120:121], v[52:53], v[48:49] op_sel:[1,0,0]
	v_mov_b32_e32 v52, v123
	s_waitcnt lgkmcnt(1)
	v_pk_fma_f32 v[48:49], v[122:123], v[78:79], v[48:49] op_sel_hi:[0,1,1]
	s_waitcnt lgkmcnt(0)
	v_pk_fma_f32 v[78:79], v[52:53], v[82:83], v[48:49] op_sel_hi:[0,1,1]
	v_pk_fma_f32 v[48:49], v[120:121], v[50:51], v[86:87] op_sel_hi:[0,1,1]
	v_pk_fma_f32 v[48:49], v[120:121], v[54:55], v[48:49] op_sel:[1,0,0]
	s_nop 0
	v_pk_fma_f32 v[48:49], v[122:123], v[80:81], v[48:49] op_sel_hi:[0,1,1]
	v_pk_fma_f32 v[82:83], v[52:53], v[84:85], v[48:49] op_sel_hi:[0,1,1]
	ds_read_b128 v[48:51], v94 offset:128
	ds_read_b128 v[52:55], v94 offset:144
	ds_read_b128 v[64:67], v94 offset:160
	s_waitcnt lgkmcnt(2)
	v_pk_fma_f32 v[48:49], v[124:125], v[48:49], v[78:79] op_sel_hi:[0,1,1]
	ds_read_b128 v[78:81], v94 offset:176
	v_pk_fma_f32 v[50:51], v[124:125], v[50:51], v[82:83] op_sel_hi:[0,1,1]
	s_waitcnt lgkmcnt(2)
	v_pk_fma_f32 v[48:49], v[124:125], v[52:53], v[48:49] op_sel:[1,0,0]
	v_pk_fma_f32 v[50:51], v[124:125], v[54:55], v[50:51] op_sel:[1,0,0]
	s_waitcnt lgkmcnt(1)
	v_pk_fma_f32 v[48:49], v[126:127], v[64:65], v[48:49] op_sel_hi:[0,1,1]
	v_mov_b32_e32 v52, v127
	v_pk_fma_f32 v[50:51], v[126:127], v[66:67], v[50:51] op_sel_hi:[0,1,1]
	s_waitcnt lgkmcnt(0)
	v_pk_fma_f32 v[48:49], v[52:53], v[78:79], v[48:49] op_sel_hi:[0,1,1]
	v_pk_fma_f32 v[54:55], v[52:53], v[80:81], v[50:51] op_sel_hi:[0,1,1]
	ds_read_b128 v[50:53], v94 offset:192
	ds_read_b128 v[60:63], v94 offset:208
	ds_read_b128 v[64:67], v94 offset:224
	ds_read_b128 v[78:81], v94 offset:240
	s_waitcnt lgkmcnt(3)
	v_pk_fma_f32 v[48:49], v[128:129], v[50:51], v[48:49] op_sel_hi:[0,1,1]
	s_waitcnt lgkmcnt(2)
	v_pk_fma_f32 v[48:49], v[128:129], v[60:61], v[48:49] op_sel:[1,0,0]
	v_mov_b32_e32 v60, v131
	s_waitcnt lgkmcnt(1)
	v_pk_fma_f32 v[48:49], v[130:131], v[64:65], v[48:49] op_sel_hi:[0,1,1]
	s_waitcnt lgkmcnt(0)
; __device__ void ph_filter_gen(const Params& P, int j, const float* __restrict__ a3, float* __restrict__ kf, float* sl) {
;     ...
;         for (int i = 0; i < 8; ++i) { const int t = tid + NT * i; const float4* ar = (const float4*)(a3 + (size_t)t * 64);
;             float a0 = 0.f, a1 = 0.f, a2 = 0.f, a3v = 0.f;
; #pragma unroll 4
;             for (int jq = 0; jq < 16; ++jq) { const float4 av = ar[jq]; const float ae[4] = {av.x, av.y, av.z, av.w};
; #pragma unroll
;                 for (int e = 0; e < 4; ++e) { const float4 wv = *(const float4*)(sw + (jq * 4 + e) * 4); a0 += ae[e] * wv.x; a1 += ae[e] * wv.y; a2 += ae[e] * wv.z; a3v += ae[e] * wv.w; } }
;             const float dec = expf(-((float)t / (float)(SEQ - 1)) * delta);
;             hv[i][0] = a0 * dec; hv[i][1] = a1 * dec; hv[i][2] = a2 * dec; hv[i][3] = a3v * dec;
	v_pk_fma_f32 v[50:51], v[60:61], v[78:79], v[48:49] op_sel_hi:[0,1,1]
	v_pk_fma_f32 v[48:49], v[128:129], v[52:53], v[54:55] op_sel_hi:[0,1,1]
	v_pk_fma_f32 v[48:49], v[128:129], v[62:63], v[48:49] op_sel:[1,0,0]
	s_nop 0
	v_pk_fma_f32 v[48:49], v[130:131], v[66:67], v[48:49] op_sel_hi:[0,1,1]
	v_pk_fma_f32 v[48:49], v[60:61], v[80:81], v[48:49] op_sel_hi:[0,1,1]
	s_add_u32 s100, s78, 0x1e800000
	s_addc_u32 s101, s79, 0
	global_load_dword v116, v113, s[100:101]
	s_add_u32 s100, s100, 0x4000
	s_addc_u32 s101, s101, 0
	global_load_dword v117, v113, s[100:101]
	s_add_u32 s100, s100, 0x4000
	s_addc_u32 s101, s101, 0
	global_load_dword v118, v113, s[100:101]
	s_add_u32 s100, s100, 0x4000
	s_addc_u32 s101, s101, 0
	global_load_dword v119, v113, s[100:101]
	s_add_u32 s100, s100, 0x4000
	s_addc_u32 s101, s101, 0
	global_load_dword v120, v113, s[100:101]
	s_add_u32 s100, s100, 0x4000
	s_addc_u32 s101, s101, 0
	global_load_dword v121, v113, s[100:101]
	s_add_u32 s100, s100, 0x4000
	s_addc_u32 s101, s101, 0
	global_load_dword v122, v113, s[100:101]
	s_add_u32 s100, s100, 0x4000
	s_addc_u32 s101, s101, 0
	global_load_dword v123, v113, s[100:101]
	s_add_u32 s100, s100, 0x4000
	s_addc_u32 s101, s101, 0
	global_load_dword v124, v113, s[100:101]
	s_add_u32 s100, s100, 0x4000
	s_addc_u32 s101, s101, 0
	global_load_dword v125, v113, s[100:101]
	s_add_u32 s100, s100, 0x4000
	s_addc_u32 s101, s101, 0
	global_load_dword v126, v113, s[100:101]
	s_add_u32 s100, s100, 0x4000
	s_addc_u32 s101, s101, 0
	global_load_dword v127, v113, s[100:101]
	s_add_u32 s100, s100, 0x4000
	s_addc_u32 s101, s101, 0
	global_load_dword v128, v113, s[100:101]
	s_add_u32 s100, s100, 0x4000
	s_addc_u32 s101, s101, 0
	global_load_dword v129, v113, s[100:101]
	s_add_u32 s100, s100, 0x4000
	s_addc_u32 s101, s101, 0
	global_load_dword v130, v113, s[100:101]
	s_add_u32 s100, s100, 0x4000
	s_addc_u32 s101, s101, 0
	global_load_dword v131, v113, s[100:101]
	s_waitcnt vmcnt(48)
	v_mov_b32_e32 v94, 0x100
	ds_read_b128 v[78:81], v94
	ds_read_b128 v[82:85], v94 offset:16
	ds_read_b128 v[86:89], v94 offset:32
	ds_read_b128 v[90:93], v94 offset:48
	s_waitcnt lgkmcnt(3)
	v_pk_fma_f32 v[50:51], v[132:133], v[78:79], v[50:51] op_sel_hi:[0,1,1]
	v_pk_fma_f32 v[48:49], v[132:133], v[80:81], v[48:49] op_sel_hi:[0,1,1]
	s_waitcnt lgkmcnt(2)
	v_pk_fma_f32 v[50:51], v[132:133], v[82:83], v[50:51] op_sel:[1,0,0]
	v_pk_fma_f32 v[48:49], v[132:133], v[84:85], v[48:49] op_sel:[1,0,0]
	s_waitcnt lgkmcnt(1)
	v_pk_fma_f32 v[50:51], v[134:135], v[86:87], v[50:51] op_sel_hi:[0,1,1]
	v_mov_b32_e32 v78, v135
	v_pk_fma_f32 v[48:49], v[134:135], v[88:89], v[48:49] op_sel_hi:[0,1,1]
	s_waitcnt lgkmcnt(0)
	v_pk_fma_f32 v[82:83], v[78:79], v[90:91], v[50:51] op_sel_hi:[0,1,1]
	v_pk_fma_f32 v[86:87], v[78:79], v[92:93], v[48:49] op_sel_hi:[0,1,1]
	ds_read_b128 v[48:51], v94 offset:64
	ds_read_b128 v[52:55], v94 offset:80
	ds_read_b128 v[78:81], v94 offset:96
	s_waitcnt lgkmcnt(2)
	v_pk_fma_f32 v[48:49], v[136:137], v[48:49], v[82:83] op_sel_hi:[0,1,1]
	ds_read_b128 v[82:85], v94 offset:112
	s_waitcnt lgkmcnt(2)
	v_pk_fma_f32 v[48:49], v[136:137], v[52:53], v[48:49] op_sel:[1,0,0]
	v_mov_b32_e32 v52, v139
	s_waitcnt lgkmcnt(1)
	v_pk_fma_f32 v[48:49], v[138:139], v[78:79], v[48:49] op_sel_hi:[0,1,1]
	s_waitcnt lgkmcnt(0)
	v_pk_fma_f32 v[78:79], v[52:53], v[82:83], v[48:49] op_sel_hi:[0,1,1]
	v_pk_fma_f32 v[48:49], v[136:137], v[50:51], v[86:87] op_sel_hi:[0,1,1]
	v_pk_fma_f32 v[48:49], v[136:137], v[54:55], v[48:49] op_sel:[1,0,0]
	s_nop 0
	v_pk_fma_f32 v[48:49], v[138:139], v[80:81], v[48:49] op_sel_hi:[0,1,1]
	v_pk_fma_f32 v[82:83], v[52:53], v[84:85], v[48:49] op_sel_hi:[0,1,1]
	ds_read_b128 v[48:51], v94 offset:128
	ds_read_b128 v[52:55], v94 offset:144
	ds_read_b128 v[64:67], v94 offset:160
	s_waitcnt lgkmcnt(2)
	v_pk_fma_f32 v[48:49], v[140:141], v[48:49], v[78:79] op_sel_hi:[0,1,1]
	ds_read_b128 v[78:81], v94 offset:176
	v_pk_fma_f32 v[50:51], v[140:141], v[50:51], v[82:83] op_sel_hi:[0,1,1]
	s_waitcnt lgkmcnt(2)
	v_pk_fma_f32 v[48:49], v[140:141], v[52:53], v[48:49] op_sel:[1,0,0]
	v_pk_fma_f32 v[50:51], v[140:141], v[54:55], v[50:51] op_sel:[1,0,0]
	s_waitcnt lgkmcnt(1)
	v_pk_fma_f32 v[48:49], v[142:143], v[64:65], v[48:49] op_sel_hi:[0,1,1]
	v_mov_b32_e32 v52, v143
	v_pk_fma_f32 v[50:51], v[142:143], v[66:67], v[50:51] op_sel_hi:[0,1,1]
	s_waitcnt lgkmcnt(0)
	v_pk_fma_f32 v[48:49], v[52:53], v[78:79], v[48:49] op_sel_hi:[0,1,1]
	v_pk_fma_f32 v[54:55], v[52:53], v[80:81], v[50:51] op_sel_hi:[0,1,1]
	ds_read_b128 v[50:53], v94 offset:192
	ds_read_b128 v[60:63], v94 offset:208
	ds_read_b128 v[64:67], v94 offset:224
	ds_read_b128 v[78:81], v94 offset:240
	s_waitcnt lgkmcnt(3)
	v_pk_fma_f32 v[48:49], v[144:145], v[50:51], v[48:49] op_sel_hi:[0,1,1]
	s_waitcnt lgkmcnt(2)
	v_pk_fma_f32 v[48:49], v[144:145], v[60:61], v[48:49] op_sel:[1,0,0]
	v_mov_b32_e32 v60, v147
	s_waitcnt lgkmcnt(1)
	v_pk_fma_f32 v[48:49], v[146:147], v[64:65], v[48:49] op_sel_hi:[0,1,1]
	s_waitcnt lgkmcnt(0)
; __device__ void ph_filter_gen(const Params& P, int j, const float* __restrict__ a3, float* __restrict__ kf, float* sl) {
;     ...
;         for (int i = 0; i < 8; ++i) { const int t = tid + NT * i; const float4* ar = (const float4*)(a3 + (size_t)t * 64);
;             float a0 = 0.f, a1 = 0.f, a2 = 0.f, a3v = 0.f;
; #pragma unroll 4
;             for (int jq = 0; jq < 16; ++jq) { const float4 av = ar[jq]; const float ae[4] = {av.x, av.y, av.z, av.w};
; #pragma unroll
;                 for (int e = 0; e < 4; ++e) { const float4 wv = *(const float4*)(sw + (jq * 4 + e) * 4); a0 += ae[e] * wv.x; a1 += ae[e] * wv.y; a2 += ae[e] * wv.z; a3v += ae[e] * wv.w; } }
;             const float dec = expf(-((float)t / (float)(SEQ - 1)) * delta);
;             hv[i][0] = a0 * dec; hv[i][1] = a1 * dec; hv[i][2] = a2 * dec; hv[i][3] = a3v * dec;
	v_pk_fma_f32 v[50:51], v[60:61], v[78:79], v[48:49] op_sel_hi:[0,1,1]
	v_pk_fma_f32 v[48:49], v[144:145], v[52:53], v[54:55] op_sel_hi:[0,1,1]
	v_pk_fma_f32 v[48:49], v[144:145], v[62:63], v[48:49] op_sel:[1,0,0]
	s_nop 0
	v_pk_fma_f32 v[48:49], v[146:147], v[66:67], v[48:49] op_sel_hi:[0,1,1]
	v_pk_fma_f32 v[48:49], v[60:61], v[80:81], v[48:49] op_sel_hi:[0,1,1]
	s_add_u32 s100, s78, 0x1e840000
	s_addc_u32 s101, s79, 0
	global_load_dword v132, v113, s[100:101]
	s_add_u32 s100, s100, 0x4000
	s_addc_u32 s101, s101, 0
	global_load_dword v133, v113, s[100:101]
	s_add_u32 s100, s100, 0x4000
	s_addc_u32 s101, s101, 0
	global_load_dword v134, v113, s[100:101]
	s_add_u32 s100, s100, 0x4000
	s_addc_u32 s101, s101, 0
	global_load_dword v135, v113, s[100:101]
	s_add_u32 s100, s100, 0x4000
	s_addc_u32 s101, s101, 0
	global_load_dword v136, v113, s[100:101]
	s_add_u32 s100, s100, 0x4000
	s_addc_u32 s101, s101, 0
	global_load_dword v137, v113, s[100:101]
	s_add_u32 s100, s100, 0x4000
	s_addc_u32 s101, s101, 0
	global_load_dword v138, v113, s[100:101]
	s_add_u32 s100, s100, 0x4000
	s_addc_u32 s101, s101, 0
	global_load_dword v139, v113, s[100:101]
	s_add_u32 s100, s100, 0x4000
	s_addc_u32 s101, s101, 0
	global_load_dword v140, v113, s[100:101]
	s_add_u32 s100, s100, 0x4000
	s_addc_u32 s101, s101, 0
	global_load_dword v141, v113, s[100:101]
	s_add_u32 s100, s100, 0x4000
	s_addc_u32 s101, s101, 0
	global_load_dword v142, v113, s[100:101]
	s_add_u32 s100, s100, 0x4000
	s_addc_u32 s101, s101, 0
	global_load_dword v143, v113, s[100:101]
	s_add_u32 s100, s100, 0x4000
	s_addc_u32 s101, s101, 0
	global_load_dword v144, v113, s[100:101]
	s_add_u32 s100, s100, 0x4000
	s_addc_u32 s101, s101, 0
	global_load_dword v145, v113, s[100:101]
	s_add_u32 s100, s100, 0x4000
	s_addc_u32 s101, s101, 0
	global_load_dword v146, v113, s[100:101]
	s_add_u32 s100, s100, 0x4000
	s_addc_u32 s101, s101, 0
	global_load_dword v147, v113, s[100:101]
	s_waitcnt vmcnt(48)
	v_mov_b32_e32 v94, 0x200
	ds_read_b128 v[78:81], v94
	ds_read_b128 v[82:85], v94 offset:16
	ds_read_b128 v[86:89], v94 offset:32
	ds_read_b128 v[90:93], v94 offset:48
	s_waitcnt lgkmcnt(3)
	v_pk_fma_f32 v[50:51], v[148:149], v[78:79], v[50:51] op_sel_hi:[0,1,1]
	v_pk_fma_f32 v[48:49], v[148:149], v[80:81], v[48:49] op_sel_hi:[0,1,1]
	s_waitcnt lgkmcnt(2)
	v_pk_fma_f32 v[50:51], v[148:149], v[82:83], v[50:51] op_sel:[1,0,0]
	v_pk_fma_f32 v[48:49], v[148:149], v[84:85], v[48:49] op_sel:[1,0,0]
	s_waitcnt lgkmcnt(1)
	v_pk_fma_f32 v[50:51], v[150:151], v[86:87], v[50:51] op_sel_hi:[0,1,1]
	v_mov_b32_e32 v78, v151
	v_pk_fma_f32 v[48:49], v[150:151], v[88:89], v[48:49] op_sel_hi:[0,1,1]
	s_waitcnt lgkmcnt(0)
	v_pk_fma_f32 v[82:83], v[78:79], v[90:91], v[50:51] op_sel_hi:[0,1,1]
	v_pk_fma_f32 v[86:87], v[78:79], v[92:93], v[48:49] op_sel_hi:[0,1,1]
	ds_read_b128 v[48:51], v94 offset:64
	ds_read_b128 v[52:55], v94 offset:80
	ds_read_b128 v[78:81], v94 offset:96
	s_waitcnt lgkmcnt(2)
	v_pk_fma_f32 v[48:49], v[152:153], v[48:49], v[82:83] op_sel_hi:[0,1,1]
	ds_read_b128 v[82:85], v94 offset:112
	s_waitcnt lgkmcnt(2)
	v_pk_fma_f32 v[48:49], v[152:153], v[52:53], v[48:49] op_sel:[1,0,0]
	v_mov_b32_e32 v52, v155
	s_waitcnt lgkmcnt(1)
	v_pk_fma_f32 v[48:49], v[154:155], v[78:79], v[48:49] op_sel_hi:[0,1,1]
	s_waitcnt lgkmcnt(0)
	v_pk_fma_f32 v[78:79], v[52:53], v[82:83], v[48:49] op_sel_hi:[0,1,1]
	v_pk_fma_f32 v[48:49], v[152:153], v[50:51], v[86:87] op_sel_hi:[0,1,1]
	v_pk_fma_f32 v[48:49], v[152:153], v[54:55], v[48:49] op_sel:[1,0,0]
	s_nop 0
	v_pk_fma_f32 v[48:49], v[154:155], v[80:81], v[48:49] op_sel_hi:[0,1,1]
	v_pk_fma_f32 v[82:83], v[52:53], v[84:85], v[48:49] op_sel_hi:[0,1,1]
	ds_read_b128 v[48:51], v94 offset:128
	ds_read_b128 v[52:55], v94 offset:144
	ds_read_b128 v[64:67], v94 offset:160
	s_waitcnt lgkmcnt(2)
	v_pk_fma_f32 v[48:49], v[156:157], v[48:49], v[78:79] op_sel_hi:[0,1,1]
	ds_read_b128 v[78:81], v94 offset:176
	v_pk_fma_f32 v[50:51], v[156:157], v[50:51], v[82:83] op_sel_hi:[0,1,1]
	s_waitcnt lgkmcnt(2)
	v_pk_fma_f32 v[48:49], v[156:157], v[52:53], v[48:49] op_sel:[1,0,0]
	v_pk_fma_f32 v[50:51], v[156:157], v[54:55], v[50:51] op_sel:[1,0,0]
	s_waitcnt lgkmcnt(1)
	v_pk_fma_f32 v[48:49], v[158:159], v[64:65], v[48:49] op_sel_hi:[0,1,1]
	v_mov_b32_e32 v52, v159
	v_pk_fma_f32 v[50:51], v[158:159], v[66:67], v[50:51] op_sel_hi:[0,1,1]
	s_waitcnt lgkmcnt(0)
	v_pk_fma_f32 v[48:49], v[52:53], v[78:79], v[48:49] op_sel_hi:[0,1,1]
	v_pk_fma_f32 v[54:55], v[52:53], v[80:81], v[50:51] op_sel_hi:[0,1,1]
	ds_read_b128 v[50:53], v94 offset:192
	ds_read_b128 v[60:63], v94 offset:208
	ds_read_b128 v[64:67], v94 offset:224
	ds_read_b128 v[78:81], v94 offset:240
	s_waitcnt lgkmcnt(3)
	v_pk_fma_f32 v[48:49], v[160:161], v[50:51], v[48:49] op_sel_hi:[0,1,1]
	s_waitcnt lgkmcnt(2)
	v_pk_fma_f32 v[48:49], v[160:161], v[60:61], v[48:49] op_sel:[1,0,0]
	v_mov_b32_e32 v60, v163
	s_waitcnt lgkmcnt(1)
	v_pk_fma_f32 v[48:49], v[162:163], v[64:65], v[48:49] op_sel_hi:[0,1,1]
	s_waitcnt lgkmcnt(0)
; __device__ void ph_filter_gen(const Params& P, int j, const float* __restrict__ a3, float* __restrict__ kf, float* sl) {
;     ...
;         for (int i = 0; i < 8; ++i) { const int t = tid + NT * i; const float4* ar = (const float4*)(a3 + (size_t)t * 64);
;             float a0 = 0.f, a1 = 0.f, a2 = 0.f, a3v = 0.f;
; #pragma unroll 4
;             for (int jq = 0; jq < 16; ++jq) { const float4 av = ar[jq]; const float ae[4] = {av.x, av.y, av.z, av.w};
; #pragma unroll
;                 for (int e = 0; e < 4; ++e) { const float4 wv = *(const float4*)(sw + (jq * 4 + e) * 4); a0 += ae[e] * wv.x; a1 += ae[e] * wv.y; a2 += ae[e] * wv.z; a3v += ae[e] * wv.w; } }
;             const float dec = expf(-((float)t / (float)(SEQ - 1)) * delta);
;             hv[i][0] = a0 * dec; hv[i][1] = a1 * dec; hv[i][2] = a2 * dec; hv[i][3] = a3v * dec;
	v_pk_fma_f32 v[50:51], v[60:61], v[78:79], v[48:49] op_sel_hi:[0,1,1]
	v_pk_fma_f32 v[48:49], v[160:161], v[52:53], v[54:55] op_sel_hi:[0,1,1]
	v_pk_fma_f32 v[48:49], v[160:161], v[62:63], v[48:49] op_sel:[1,0,0]
	s_nop 0
	v_pk_fma_f32 v[48:49], v[162:163], v[66:67], v[48:49] op_sel_hi:[0,1,1]
	v_pk_fma_f32 v[48:49], v[60:61], v[80:81], v[48:49] op_sel_hi:[0,1,1]
	s_add_u32 s100, s78, 0x1e880000
	s_addc_u32 s101, s79, 0
	global_load_dword v148, v113, s[100:101]
	s_add_u32 s100, s100, 0x4000
	s_addc_u32 s101, s101, 0
	global_load_dword v149, v113, s[100:101]
	s_add_u32 s100, s100, 0x4000
	s_addc_u32 s101, s101, 0
	global_load_dword v150, v113, s[100:101]
	s_add_u32 s100, s100, 0x4000
	s_addc_u32 s101, s101, 0
	global_load_dword v151, v113, s[100:101]
	s_add_u32 s100, s100, 0x4000
	s_addc_u32 s101, s101, 0
	global_load_dword v152, v113, s[100:101]
	s_add_u32 s100, s100, 0x4000
	s_addc_u32 s101, s101, 0
	global_load_dword v153, v113, s[100:101]
	s_add_u32 s100, s100, 0x4000
	s_addc_u32 s101, s101, 0
	global_load_dword v154, v113, s[100:101]
	s_add_u32 s100, s100, 0x4000
	s_addc_u32 s101, s101, 0
	global_load_dword v155, v113, s[100:101]
	s_add_u32 s100, s100, 0x4000
	s_addc_u32 s101, s101, 0
	global_load_dword v156, v113, s[100:101]
	s_add_u32 s100, s100, 0x4000
	s_addc_u32 s101, s101, 0
	global_load_dword v157, v113, s[100:101]
	s_add_u32 s100, s100, 0x4000
	s_addc_u32 s101, s101, 0
	global_load_dword v158, v113, s[100:101]
	s_add_u32 s100, s100, 0x4000
	s_addc_u32 s101, s101, 0
	global_load_dword v159, v113, s[100:101]
	s_add_u32 s100, s100, 0x4000
	s_addc_u32 s101, s101, 0
	global_load_dword v160, v113, s[100:101]
	s_add_u32 s100, s100, 0x4000
	s_addc_u32 s101, s101, 0
	global_load_dword v161, v113, s[100:101]
	s_add_u32 s100, s100, 0x4000
	s_addc_u32 s101, s101, 0
	global_load_dword v162, v113, s[100:101]
	s_add_u32 s100, s100, 0x4000
	s_addc_u32 s101, s101, 0
	global_load_dword v163, v113, s[100:101]
	s_waitcnt vmcnt(48)
	v_mov_b32_e32 v94, 0x300
	ds_read_b128 v[78:81], v94
	ds_read_b128 v[82:85], v94 offset:16
	ds_read_b128 v[86:89], v94 offset:32
	ds_read_b128 v[90:93], v94 offset:48
	s_waitcnt lgkmcnt(3)
	v_pk_fma_f32 v[50:51], v[164:165], v[78:79], v[50:51] op_sel_hi:[0,1,1]
	v_pk_fma_f32 v[48:49], v[164:165], v[80:81], v[48:49] op_sel_hi:[0,1,1]
	s_waitcnt lgkmcnt(2)
	v_pk_fma_f32 v[50:51], v[164:165], v[82:83], v[50:51] op_sel:[1,0,0]
	v_pk_fma_f32 v[48:49], v[164:165], v[84:85], v[48:49] op_sel:[1,0,0]
	s_waitcnt lgkmcnt(1)
	v_pk_fma_f32 v[50:51], v[166:167], v[86:87], v[50:51] op_sel_hi:[0,1,1]
	v_mov_b32_e32 v78, v167
	v_pk_fma_f32 v[48:49], v[166:167], v[88:89], v[48:49] op_sel_hi:[0,1,1]
	s_waitcnt lgkmcnt(0)
	v_pk_fma_f32 v[82:83], v[78:79], v[90:91], v[50:51] op_sel_hi:[0,1,1]
	v_pk_fma_f32 v[86:87], v[78:79], v[92:93], v[48:49] op_sel_hi:[0,1,1]
	ds_read_b128 v[48:51], v94 offset:64
	ds_read_b128 v[52:55], v94 offset:80
	ds_read_b128 v[78:81], v94 offset:96
	s_waitcnt lgkmcnt(2)
	v_pk_fma_f32 v[48:49], v[168:169], v[48:49], v[82:83] op_sel_hi:[0,1,1]
	ds_read_b128 v[82:85], v94 offset:112
	s_waitcnt lgkmcnt(2)
	v_pk_fma_f32 v[48:49], v[168:169], v[52:53], v[48:49] op_sel:[1,0,0]
	v_mov_b32_e32 v52, v171
	s_waitcnt lgkmcnt(1)
	v_pk_fma_f32 v[48:49], v[170:171], v[78:79], v[48:49] op_sel_hi:[0,1,1]
	s_waitcnt lgkmcnt(0)
	v_pk_fma_f32 v[78:79], v[52:53], v[82:83], v[48:49] op_sel_hi:[0,1,1]
	v_pk_fma_f32 v[48:49], v[168:169], v[50:51], v[86:87] op_sel_hi:[0,1,1]
	v_pk_fma_f32 v[48:49], v[168:169], v[54:55], v[48:49] op_sel:[1,0,0]
	s_nop 0
	v_pk_fma_f32 v[48:49], v[170:171], v[80:81], v[48:49] op_sel_hi:[0,1,1]
	v_pk_fma_f32 v[82:83], v[52:53], v[84:85], v[48:49] op_sel_hi:[0,1,1]
	ds_read_b128 v[48:51], v94 offset:128
	ds_read_b128 v[52:55], v94 offset:144
	ds_read_b128 v[64:67], v94 offset:160
	s_waitcnt lgkmcnt(2)
	v_pk_fma_f32 v[48:49], v[172:173], v[48:49], v[78:79] op_sel_hi:[0,1,1]
	ds_read_b128 v[78:81], v94 offset:176
	v_pk_fma_f32 v[50:51], v[172:173], v[50:51], v[82:83] op_sel_hi:[0,1,1]
	s_waitcnt lgkmcnt(2)
	v_pk_fma_f32 v[48:49], v[172:173], v[52:53], v[48:49] op_sel:[1,0,0]
	v_pk_fma_f32 v[50:51], v[172:173], v[54:55], v[50:51] op_sel:[1,0,0]
	s_waitcnt lgkmcnt(1)
	v_pk_fma_f32 v[48:49], v[174:175], v[64:65], v[48:49] op_sel_hi:[0,1,1]
	v_mov_b32_e32 v52, v175
	v_pk_fma_f32 v[50:51], v[174:175], v[66:67], v[50:51] op_sel_hi:[0,1,1]
	s_waitcnt lgkmcnt(0)
	v_pk_fma_f32 v[48:49], v[52:53], v[78:79], v[48:49] op_sel_hi:[0,1,1]
	v_pk_fma_f32 v[54:55], v[52:53], v[80:81], v[50:51] op_sel_hi:[0,1,1]
	ds_read_b128 v[50:53], v94 offset:192
	ds_read_b128 v[60:63], v94 offset:208
	ds_read_b128 v[64:67], v94 offset:224
	ds_read_b128 v[78:81], v94 offset:240
	s_waitcnt lgkmcnt(3)
	v_pk_fma_f32 v[48:49], v[176:177], v[50:51], v[48:49] op_sel_hi:[0,1,1]
	s_waitcnt lgkmcnt(2)
	v_pk_fma_f32 v[48:49], v[176:177], v[60:61], v[48:49] op_sel:[1,0,0]
	v_mov_b32_e32 v60, v179
	s_waitcnt lgkmcnt(1)
	v_pk_fma_f32 v[48:49], v[178:179], v[64:65], v[48:49] op_sel_hi:[0,1,1]
	s_waitcnt lgkmcnt(0)
; __device__ void ph_filter_gen(const Params& P, int j, const float* __restrict__ a3, float* __restrict__ kf, float* sl) {
;     ...
;         for (int i = 0; i < 8; ++i) { const int t = tid + NT * i; const float4* ar = (const float4*)(a3 + (size_t)t * 64);
;             float a0 = 0.f, a1 = 0.f, a2 = 0.f, a3v = 0.f;
; #pragma unroll 4
;             for (int jq = 0; jq < 16; ++jq) { const float4 av = ar[jq]; const float ae[4] = {av.x, av.y, av.z, av.w};
; #pragma unroll
;                 for (int e = 0; e < 4; ++e) { const float4 wv = *(const float4*)(sw + (jq * 4 + e) * 4); a0 += ae[e] * wv.x; a1 += ae[e] * wv.y; a2 += ae[e] * wv.z; a3v += ae[e] * wv.w; } }
;             const float dec = expf(-((float)t / (float)(SEQ - 1)) * delta);
;             hv[i][0] = a0 * dec; hv[i][1] = a1 * dec; hv[i][2] = a2 * dec; hv[i][3] = a3v * dec;
	v_pk_fma_f32 v[50:51], v[60:61], v[78:79], v[48:49] op_sel_hi:[0,1,1]
	v_pk_fma_f32 v[48:49], v[176:177], v[52:53], v[54:55] op_sel_hi:[0,1,1]
	v_pk_fma_f32 v[48:49], v[176:177], v[62:63], v[48:49] op_sel:[1,0,0]
	s_nop 0
	v_pk_fma_f32 v[48:49], v[178:179], v[66:67], v[48:49] op_sel_hi:[0,1,1]
	v_pk_fma_f32 v[48:49], v[60:61], v[80:81], v[48:49] op_sel_hi:[0,1,1]
	s_add_u32 s100, s78, 0x1e8c0000
	s_addc_u32 s101, s79, 0
	global_load_dword v164, v113, s[100:101]
	s_add_u32 s100, s100, 0x4000
	s_addc_u32 s101, s101, 0
	global_load_dword v165, v113, s[100:101]
	s_add_u32 s100, s100, 0x4000
	s_addc_u32 s101, s101, 0
	global_load_dword v166, v113, s[100:101]
	s_add_u32 s100, s100, 0x4000
	s_addc_u32 s101, s101, 0
	global_load_dword v167, v113, s[100:101]
	s_add_u32 s100, s100, 0x4000
	s_addc_u32 s101, s101, 0
	global_load_dword v168, v113, s[100:101]
	s_add_u32 s100, s100, 0x4000
	s_addc_u32 s101, s101, 0
	global_load_dword v169, v113, s[100:101]
	s_add_u32 s100, s100, 0x4000
	s_addc_u32 s101, s101, 0
	global_load_dword v170, v113, s[100:101]
	s_add_u32 s100, s100, 0x4000
	s_addc_u32 s101, s101, 0
	global_load_dword v171, v113, s[100:101]
	s_add_u32 s100, s100, 0x4000
	s_addc_u32 s101, s101, 0
	global_load_dword v172, v113, s[100:101]
	s_add_u32 s100, s100, 0x4000
	s_addc_u32 s101, s101, 0
	global_load_dword v173, v113, s[100:101]
	s_add_u32 s100, s100, 0x4000
	s_addc_u32 s101, s101, 0
	global_load_dword v174, v113, s[100:101]
	s_add_u32 s100, s100, 0x4000
	s_addc_u32 s101, s101, 0
	global_load_dword v175, v113, s[100:101]
	s_add_u32 s100, s100, 0x4000
	s_addc_u32 s101, s101, 0
	global_load_dword v176, v113, s[100:101]
	s_add_u32 s100, s100, 0x4000
	s_addc_u32 s101, s101, 0
	global_load_dword v177, v113, s[100:101]
	s_add_u32 s100, s100, 0x4000
	s_addc_u32 s101, s101, 0
	global_load_dword v178, v113, s[100:101]
	s_add_u32 s100, s100, 0x4000
	s_addc_u32 s101, s101, 0
	global_load_dword v179, v113, s[100:101]
	v_mov_b32_e32 v54, 0
	s_mov_b32 s0, 0
	s_mov_b64 s[14:15], 0
	v_mov_b32_e32 v55, v54
	v_mov_b32_e32 v52, v54
	v_mov_b32_e32 v53, v54
.LBB0_229:
	v_add_u32_e32 v113, 0x2800, v68
	s_waitcnt vmcnt(48)
	v_mov_b32_e32 v98, 0
	ds_read_b128 v[82:85], v98
	ds_read_b128 v[86:89], v98 offset:16
	ds_read_b128 v[90:93], v98 offset:32
	ds_read_b128 v[94:97], v98 offset:48
	s_waitcnt lgkmcnt(3)
	v_pk_fma_f32 v[54:55], v[116:117], v[82:83], v[54:55] op_sel_hi:[0,1,1]
	v_pk_fma_f32 v[52:53], v[116:117], v[84:85], v[52:53] op_sel_hi:[0,1,1]
	s_waitcnt lgkmcnt(2)
	v_pk_fma_f32 v[54:55], v[116:117], v[86:87], v[54:55] op_sel:[1,0,0]
	v_pk_fma_f32 v[52:53], v[116:117], v[88:89], v[52:53] op_sel:[1,0,0]
	s_waitcnt lgkmcnt(1)
	v_pk_fma_f32 v[54:55], v[118:119], v[90:91], v[54:55] op_sel_hi:[0,1,1]
	v_mov_b32_e32 v82, v119
	v_pk_fma_f32 v[52:53], v[118:119], v[92:93], v[52:53] op_sel_hi:[0,1,1]
	s_waitcnt lgkmcnt(0)
	v_pk_fma_f32 v[86:87], v[82:83], v[94:95], v[54:55] op_sel_hi:[0,1,1]
	v_pk_fma_f32 v[90:91], v[82:83], v[96:97], v[52:53] op_sel_hi:[0,1,1]
	ds_read_b128 v[52:55], v98 offset:64
	ds_read_b128 v[56:59], v98 offset:80
	ds_read_b128 v[82:85], v98 offset:96
	s_waitcnt lgkmcnt(2)
	v_pk_fma_f32 v[52:53], v[120:121], v[52:53], v[86:87] op_sel_hi:[0,1,1]
	ds_read_b128 v[86:89], v98 offset:112
	s_waitcnt lgkmcnt(2)
	v_pk_fma_f32 v[52:53], v[120:121], v[56:57], v[52:53] op_sel:[1,0,0]
	v_mov_b32_e32 v56, v123
	s_waitcnt lgkmcnt(1)
	v_pk_fma_f32 v[52:53], v[122:123], v[82:83], v[52:53] op_sel_hi:[0,1,1]
	s_waitcnt lgkmcnt(0)
	v_pk_fma_f32 v[82:83], v[56:57], v[86:87], v[52:53] op_sel_hi:[0,1,1]
	v_pk_fma_f32 v[52:53], v[120:121], v[54:55], v[90:91] op_sel_hi:[0,1,1]
	v_pk_fma_f32 v[52:53], v[120:121], v[58:59], v[52:53] op_sel:[1,0,0]
	s_nop 0
	v_pk_fma_f32 v[52:53], v[122:123], v[84:85], v[52:53] op_sel_hi:[0,1,1]
	v_pk_fma_f32 v[86:87], v[56:57], v[88:89], v[52:53] op_sel_hi:[0,1,1]
	ds_read_b128 v[52:55], v98 offset:128
	ds_read_b128 v[56:59], v98 offset:144
	ds_read_b128 v[78:81], v98 offset:160
	s_waitcnt lgkmcnt(2)
	v_pk_fma_f32 v[52:53], v[124:125], v[52:53], v[82:83] op_sel_hi:[0,1,1]
	ds_read_b128 v[82:85], v98 offset:176
	v_pk_fma_f32 v[54:55], v[124:125], v[54:55], v[86:87] op_sel_hi:[0,1,1]
	s_waitcnt lgkmcnt(2)
	v_pk_fma_f32 v[52:53], v[124:125], v[56:57], v[52:53] op_sel:[1,0,0]
	v_pk_fma_f32 v[54:55], v[124:125], v[58:59], v[54:55] op_sel:[1,0,0]
	s_waitcnt lgkmcnt(1)
	v_pk_fma_f32 v[52:53], v[126:127], v[78:79], v[52:53] op_sel_hi:[0,1,1]
	v_mov_b32_e32 v56, v127
	v_pk_fma_f32 v[54:55], v[126:127], v[80:81], v[54:55] op_sel_hi:[0,1,1]
	s_waitcnt lgkmcnt(0)
	v_pk_fma_f32 v[52:53], v[56:57], v[82:83], v[52:53] op_sel_hi:[0,1,1]
	v_pk_fma_f32 v[58:59], v[56:57], v[84:85], v[54:55] op_sel_hi:[0,1,1]
	ds_read_b128 v[54:57], v98 offset:192
	ds_read_b128 v[64:67], v98 offset:208
	ds_read_b128 v[78:81], v98 offset:224
	ds_read_b128 v[82:85], v98 offset:240
	s_waitcnt lgkmcnt(3)
	v_pk_fma_f32 v[52:53], v[128:129], v[54:55], v[52:53] op_sel_hi:[0,1,1]
	s_waitcnt lgkmcnt(2)
	v_pk_fma_f32 v[52:53], v[128:129], v[64:65], v[52:53] op_sel:[1,0,0]
	v_mov_b32_e32 v64, v131
	s_waitcnt lgkmcnt(1)
	v_pk_fma_f32 v[52:53], v[130:131], v[78:79], v[52:53] op_sel_hi:[0,1,1]
	s_waitcnt lgkmcnt(0)
; __device__ void ph_filter_gen(const Params& P, int j, const float* __restrict__ a3, float* __restrict__ kf, float* sl) {
;     ...
;         for (int i = 0; i < 8; ++i) { const int t = tid + NT * i; const float4* ar = (const float4*)(a3 + (size_t)t * 64);
;             float a0 = 0.f, a1 = 0.f, a2 = 0.f, a3v = 0.f;
; #pragma unroll 4
;             for (int jq = 0; jq < 16; ++jq) { const float4 av = ar[jq]; const float ae[4] = {av.x, av.y, av.z, av.w};
; #pragma unroll
;                 for (int e = 0; e < 4; ++e) { const float4 wv = *(const float4*)(sw + (jq * 4 + e) * 4); a0 += ae[e] * wv.x; a1 += ae[e] * wv.y; a2 += ae[e] * wv.z; a3v += ae[e] * wv.w; } }
;             const float dec = expf(-((float)t / (float)(SEQ - 1)) * delta);
;             hv[i][0] = a0 * dec; hv[i][1] = a1 * dec; hv[i][2] = a2 * dec; hv[i][3] = a3v * dec;
	v_pk_fma_f32 v[54:55], v[64:65], v[82:83], v[52:53] op_sel_hi:[0,1,1]
	v_pk_fma_f32 v[52:53], v[128:129], v[56:57], v[58:59] op_sel_hi:[0,1,1]
	v_pk_fma_f32 v[52:53], v[128:129], v[66:67], v[52:53] op_sel:[1,0,0]
	s_nop 0
	v_pk_fma_f32 v[52:53], v[130:131], v[80:81], v[52:53] op_sel_hi:[0,1,1]
	v_pk_fma_f32 v[52:53], v[64:65], v[84:85], v[52:53] op_sel_hi:[0,1,1]
	s_add_u32 s100, s78, 0x1e800000
	s_addc_u32 s101, s79, 0
	global_load_dword v116, v113, s[100:101]
	s_add_u32 s100, s100, 0x4000
	s_addc_u32 s101, s101, 0
	global_load_dword v117, v113, s[100:101]
	s_add_u32 s100, s100, 0x4000
	s_addc_u32 s101, s101, 0
	global_load_dword v118, v113, s[100:101]
	s_add_u32 s100, s100, 0x4000
	s_addc_u32 s101, s101, 0
	global_load_dword v119, v113, s[100:101]
	s_add_u32 s100, s100, 0x4000
	s_addc_u32 s101, s101, 0
	global_load_dword v120, v113, s[100:101]
	s_add_u32 s100, s100, 0x4000
	s_addc_u32 s101, s101, 0
	global_load_dword v121, v113, s[100:101]
	s_add_u32 s100, s100, 0x4000
	s_addc_u32 s101, s101, 0
	global_load_dword v122, v113, s[100:101]
	s_add_u32 s100, s100, 0x4000
	s_addc_u32 s101, s101, 0
	global_load_dword v123, v113, s[100:101]
	s_add_u32 s100, s100, 0x4000
	s_addc_u32 s101, s101, 0
	global_load_dword v124, v113, s[100:101]
	s_add_u32 s100, s100, 0x4000
	s_addc_u32 s101, s101, 0
	global_load_dword v125, v113, s[100:101]
	s_add_u32 s100, s100, 0x4000
	s_addc_u32 s101, s101, 0
	global_load_dword v126, v113, s[100:101]
	s_add_u32 s100, s100, 0x4000
	s_addc_u32 s101, s101, 0
	global_load_dword v127, v113, s[100:101]
	s_add_u32 s100, s100, 0x4000
	s_addc_u32 s101, s101, 0
	global_load_dword v128, v113, s[100:101]
	s_add_u32 s100, s100, 0x4000
	s_addc_u32 s101, s101, 0
	global_load_dword v129, v113, s[100:101]
	s_add_u32 s100, s100, 0x4000
	s_addc_u32 s101, s101, 0
	global_load_dword v130, v113, s[100:101]
	s_add_u32 s100, s100, 0x4000
	s_addc_u32 s101, s101, 0
	global_load_dword v131, v113, s[100:101]
	s_waitcnt vmcnt(48)
	v_mov_b32_e32 v98, 0x100
	ds_read_b128 v[82:85], v98
	ds_read_b128 v[86:89], v98 offset:16
	ds_read_b128 v[90:93], v98 offset:32
	ds_read_b128 v[94:97], v98 offset:48
	s_waitcnt lgkmcnt(3)
	v_pk_fma_f32 v[54:55], v[132:133], v[82:83], v[54:55] op_sel_hi:[0,1,1]
	v_pk_fma_f32 v[52:53], v[132:133], v[84:85], v[52:53] op_sel_hi:[0,1,1]
	s_waitcnt lgkmcnt(2)
	v_pk_fma_f32 v[54:55], v[132:133], v[86:87], v[54:55] op_sel:[1,0,0]
	v_pk_fma_f32 v[52:53], v[132:133], v[88:89], v[52:53] op_sel:[1,0,0]
	s_waitcnt lgkmcnt(1)
	v_pk_fma_f32 v[54:55], v[134:135], v[90:91], v[54:55] op_sel_hi:[0,1,1]
	v_mov_b32_e32 v82, v135
	v_pk_fma_f32 v[52:53], v[134:135], v[92:93], v[52:53] op_sel_hi:[0,1,1]
	s_waitcnt lgkmcnt(0)
	v_pk_fma_f32 v[86:87], v[82:83], v[94:95], v[54:55] op_sel_hi:[0,1,1]
	v_pk_fma_f32 v[90:91], v[82:83], v[96:97], v[52:53] op_sel_hi:[0,1,1]
	ds_read_b128 v[52:55], v98 offset:64
	ds_read_b128 v[56:59], v98 offset:80
	ds_read_b128 v[82:85], v98 offset:96
	s_waitcnt lgkmcnt(2)
	v_pk_fma_f32 v[52:53], v[136:137], v[52:53], v[86:87] op_sel_hi:[0,1,1]
	ds_read_b128 v[86:89], v98 offset:112
	s_waitcnt lgkmcnt(2)
	v_pk_fma_f32 v[52:53], v[136:137], v[56:57], v[52:53] op_sel:[1,0,0]
	v_mov_b32_e32 v56, v139
	s_waitcnt lgkmcnt(1)
	v_pk_fma_f32 v[52:53], v[138:139], v[82:83], v[52:53] op_sel_hi:[0,1,1]
	s_waitcnt lgkmcnt(0)
	v_pk_fma_f32 v[82:83], v[56:57], v[86:87], v[52:53] op_sel_hi:[0,1,1]
	v_pk_fma_f32 v[52:53], v[136:137], v[54:55], v[90:91] op_sel_hi:[0,1,1]
	v_pk_fma_f32 v[52:53], v[136:137], v[58:59], v[52:53] op_sel:[1,0,0]
	s_nop 0
	v_pk_fma_f32 v[52:53], v[138:139], v[84:85], v[52:53] op_sel_hi:[0,1,1]
	v_pk_fma_f32 v[86:87], v[56:57], v[88:89], v[52:53] op_sel_hi:[0,1,1]
	ds_read_b128 v[52:55], v98 offset:128
	ds_read_b128 v[56:59], v98 offset:144
	ds_read_b128 v[78:81], v98 offset:160
	s_waitcnt lgkmcnt(2)
	v_pk_fma_f32 v[52:53], v[140:141], v[52:53], v[82:83] op_sel_hi:[0,1,1]
	ds_read_b128 v[82:85], v98 offset:176
	v_pk_fma_f32 v[54:55], v[140:141], v[54:55], v[86:87] op_sel_hi:[0,1,1]
	s_waitcnt lgkmcnt(2)
	v_pk_fma_f32 v[52:53], v[140:141], v[56:57], v[52:53] op_sel:[1,0,0]
	v_pk_fma_f32 v[54:55], v[140:141], v[58:59], v[54:55] op_sel:[1,0,0]
	s_waitcnt lgkmcnt(1)
	v_pk_fma_f32 v[52:53], v[142:143], v[78:79], v[52:53] op_sel_hi:[0,1,1]
	v_mov_b32_e32 v56, v143
	v_pk_fma_f32 v[54:55], v[142:143], v[80:81], v[54:55] op_sel_hi:[0,1,1]
	s_waitcnt lgkmcnt(0)
	v_pk_fma_f32 v[52:53], v[56:57], v[82:83], v[52:53] op_sel_hi:[0,1,1]
	v_pk_fma_f32 v[58:59], v[56:57], v[84:85], v[54:55] op_sel_hi:[0,1,1]
	ds_read_b128 v[54:57], v98 offset:192
	ds_read_b128 v[64:67], v98 offset:208
	ds_read_b128 v[78:81], v98 offset:224
	ds_read_b128 v[82:85], v98 offset:240
	s_waitcnt lgkmcnt(3)
	v_pk_fma_f32 v[52:53], v[144:145], v[54:55], v[52:53] op_sel_hi:[0,1,1]
	s_waitcnt lgkmcnt(2)
	v_pk_fma_f32 v[52:53], v[144:145], v[64:65], v[52:53] op_sel:[1,0,0]
	v_mov_b32_e32 v64, v147
	s_waitcnt lgkmcnt(1)
	v_pk_fma_f32 v[52:53], v[146:147], v[78:79], v[52:53] op_sel_hi:[0,1,1]
	s_waitcnt lgkmcnt(0)
; __device__ void ph_filter_gen(const Params& P, int j, const float* __restrict__ a3, float* __restrict__ kf, float* sl) {
;     ...
;         for (int i = 0; i < 8; ++i) { const int t = tid + NT * i; const float4* ar = (const float4*)(a3 + (size_t)t * 64);
;             float a0 = 0.f, a1 = 0.f, a2 = 0.f, a3v = 0.f;
; #pragma unroll 4
;             for (int jq = 0; jq < 16; ++jq) { const float4 av = ar[jq]; const float ae[4] = {av.x, av.y, av.z, av.w};
; #pragma unroll
;                 for (int e = 0; e < 4; ++e) { const float4 wv = *(const float4*)(sw + (jq * 4 + e) * 4); a0 += ae[e] * wv.x; a1 += ae[e] * wv.y; a2 += ae[e] * wv.z; a3v += ae[e] * wv.w; } }
;             const float dec = expf(-((float)t / (float)(SEQ - 1)) * delta);
;             hv[i][0] = a0 * dec; hv[i][1] = a1 * dec; hv[i][2] = a2 * dec; hv[i][3] = a3v * dec;
	v_pk_fma_f32 v[54:55], v[64:65], v[82:83], v[52:53] op_sel_hi:[0,1,1]
	v_pk_fma_f32 v[52:53], v[144:145], v[56:57], v[58:59] op_sel_hi:[0,1,1]
	v_pk_fma_f32 v[52:53], v[144:145], v[66:67], v[52:53] op_sel:[1,0,0]
	s_nop 0
	v_pk_fma_f32 v[52:53], v[146:147], v[80:81], v[52:53] op_sel_hi:[0,1,1]
	v_pk_fma_f32 v[52:53], v[64:65], v[84:85], v[52:53] op_sel_hi:[0,1,1]
	s_add_u32 s100, s78, 0x1e840000
	s_addc_u32 s101, s79, 0
	global_load_dword v132, v113, s[100:101]
	s_add_u32 s100, s100, 0x4000
	s_addc_u32 s101, s101, 0
	global_load_dword v133, v113, s[100:101]
	s_add_u32 s100, s100, 0x4000
	s_addc_u32 s101, s101, 0
	global_load_dword v134, v113, s[100:101]
	s_add_u32 s100, s100, 0x4000
	s_addc_u32 s101, s101, 0
	global_load_dword v135, v113, s[100:101]
	s_add_u32 s100, s100, 0x4000
	s_addc_u32 s101, s101, 0
	global_load_dword v136, v113, s[100:101]
	s_add_u32 s100, s100, 0x4000
	s_addc_u32 s101, s101, 0
	global_load_dword v137, v113, s[100:101]
	s_add_u32 s100, s100, 0x4000
	s_addc_u32 s101, s101, 0
	global_load_dword v138, v113, s[100:101]
	s_add_u32 s100, s100, 0x4000
	s_addc_u32 s101, s101, 0
	global_load_dword v139, v113, s[100:101]
	s_add_u32 s100, s100, 0x4000
	s_addc_u32 s101, s101, 0
	global_load_dword v140, v113, s[100:101]
	s_add_u32 s100, s100, 0x4000
	s_addc_u32 s101, s101, 0
	global_load_dword v141, v113, s[100:101]
	s_add_u32 s100, s100, 0x4000
	s_addc_u32 s101, s101, 0
	global_load_dword v142, v113, s[100:101]
	s_add_u32 s100, s100, 0x4000
	s_addc_u32 s101, s101, 0
	global_load_dword v143, v113, s[100:101]
	s_add_u32 s100, s100, 0x4000
	s_addc_u32 s101, s101, 0
	global_load_dword v144, v113, s[100:101]
	s_add_u32 s100, s100, 0x4000
	s_addc_u32 s101, s101, 0
	global_load_dword v145, v113, s[100:101]
	s_add_u32 s100, s100, 0x4000
	s_addc_u32 s101, s101, 0
	global_load_dword v146, v113, s[100:101]
	s_add_u32 s100, s100, 0x4000
	s_addc_u32 s101, s101, 0
	global_load_dword v147, v113, s[100:101]
	s_waitcnt vmcnt(48)
	v_mov_b32_e32 v98, 0x200
	ds_read_b128 v[82:85], v98
	ds_read_b128 v[86:89], v98 offset:16
	ds_read_b128 v[90:93], v98 offset:32
	ds_read_b128 v[94:97], v98 offset:48
	s_waitcnt lgkmcnt(3)
	v_pk_fma_f32 v[54:55], v[148:149], v[82:83], v[54:55] op_sel_hi:[0,1,1]
	v_pk_fma_f32 v[52:53], v[148:149], v[84:85], v[52:53] op_sel_hi:[0,1,1]
	s_waitcnt lgkmcnt(2)
	v_pk_fma_f32 v[54:55], v[148:149], v[86:87], v[54:55] op_sel:[1,0,0]
	v_pk_fma_f32 v[52:53], v[148:149], v[88:89], v[52:53] op_sel:[1,0,0]
	s_waitcnt lgkmcnt(1)
	v_pk_fma_f32 v[54:55], v[150:151], v[90:91], v[54:55] op_sel_hi:[0,1,1]
	v_mov_b32_e32 v82, v151
	v_pk_fma_f32 v[52:53], v[150:151], v[92:93], v[52:53] op_sel_hi:[0,1,1]
	s_waitcnt lgkmcnt(0)
	v_pk_fma_f32 v[86:87], v[82:83], v[94:95], v[54:55] op_sel_hi:[0,1,1]
	v_pk_fma_f32 v[90:91], v[82:83], v[96:97], v[52:53] op_sel_hi:[0,1,1]
	ds_read_b128 v[52:55], v98 offset:64
	ds_read_b128 v[56:59], v98 offset:80
	ds_read_b128 v[82:85], v98 offset:96
	s_waitcnt lgkmcnt(2)
	v_pk_fma_f32 v[52:53], v[152:153], v[52:53], v[86:87] op_sel_hi:[0,1,1]
	ds_read_b128 v[86:89], v98 offset:112
	s_waitcnt lgkmcnt(2)
	v_pk_fma_f32 v[52:53], v[152:153], v[56:57], v[52:53] op_sel:[1,0,0]
	v_mov_b32_e32 v56, v155
	s_waitcnt lgkmcnt(1)
	v_pk_fma_f32 v[52:53], v[154:155], v[82:83], v[52:53] op_sel_hi:[0,1,1]
	s_waitcnt lgkmcnt(0)
	v_pk_fma_f32 v[82:83], v[56:57], v[86:87], v[52:53] op_sel_hi:[0,1,1]
	v_pk_fma_f32 v[52:53], v[152:153], v[54:55], v[90:91] op_sel_hi:[0,1,1]
	v_pk_fma_f32 v[52:53], v[152:153], v[58:59], v[52:53] op_sel:[1,0,0]
	s_nop 0
	v_pk_fma_f32 v[52:53], v[154:155], v[84:85], v[52:53] op_sel_hi:[0,1,1]
	v_pk_fma_f32 v[86:87], v[56:57], v[88:89], v[52:53] op_sel_hi:[0,1,1]
	ds_read_b128 v[52:55], v98 offset:128
	ds_read_b128 v[56:59], v98 offset:144
	ds_read_b128 v[78:81], v98 offset:160
	s_waitcnt lgkmcnt(2)
	v_pk_fma_f32 v[52:53], v[156:157], v[52:53], v[82:83] op_sel_hi:[0,1,1]
	ds_read_b128 v[82:85], v98 offset:176
	v_pk_fma_f32 v[54:55], v[156:157], v[54:55], v[86:87] op_sel_hi:[0,1,1]
	s_waitcnt lgkmcnt(2)
	v_pk_fma_f32 v[52:53], v[156:157], v[56:57], v[52:53] op_sel:[1,0,0]
	v_pk_fma_f32 v[54:55], v[156:157], v[58:59], v[54:55] op_sel:[1,0,0]
	s_waitcnt lgkmcnt(1)
	v_pk_fma_f32 v[52:53], v[158:159], v[78:79], v[52:53] op_sel_hi:[0,1,1]
	v_mov_b32_e32 v56, v159
	v_pk_fma_f32 v[54:55], v[158:159], v[80:81], v[54:55] op_sel_hi:[0,1,1]
	s_waitcnt lgkmcnt(0)
	v_pk_fma_f32 v[52:53], v[56:57], v[82:83], v[52:53] op_sel_hi:[0,1,1]
	v_pk_fma_f32 v[58:59], v[56:57], v[84:85], v[54:55] op_sel_hi:[0,1,1]
	ds_read_b128 v[54:57], v98 offset:192
	ds_read_b128 v[64:67], v98 offset:208
	ds_read_b128 v[78:81], v98 offset:224
	ds_read_b128 v[82:85], v98 offset:240
	s_waitcnt lgkmcnt(3)
	v_pk_fma_f32 v[52:53], v[160:161], v[54:55], v[52:53] op_sel_hi:[0,1,1]
	s_waitcnt lgkmcnt(2)
	v_pk_fma_f32 v[52:53], v[160:161], v[64:65], v[52:53] op_sel:[1,0,0]
	v_mov_b32_e32 v64, v163
	s_waitcnt lgkmcnt(1)
	v_pk_fma_f32 v[52:53], v[162:163], v[78:79], v[52:53] op_sel_hi:[0,1,1]
	s_waitcnt lgkmcnt(0)
; __device__ void ph_filter_gen(const Params& P, int j, const float* __restrict__ a3, float* __restrict__ kf, float* sl) {
;     ...
;         for (int i = 0; i < 8; ++i) { const int t = tid + NT * i; const float4* ar = (const float4*)(a3 + (size_t)t * 64);
;             float a0 = 0.f, a1 = 0.f, a2 = 0.f, a3v = 0.f;
; #pragma unroll 4
;             for (int jq = 0; jq < 16; ++jq) { const float4 av = ar[jq]; const float ae[4] = {av.x, av.y, av.z, av.w};
; #pragma unroll
;                 for (int e = 0; e < 4; ++e) { const float4 wv = *(const float4*)(sw + (jq * 4 + e) * 4); a0 += ae[e] * wv.x; a1 += ae[e] * wv.y; a2 += ae[e] * wv.z; a3v += ae[e] * wv.w; } }
;             const float dec = expf(-((float)t / (float)(SEQ - 1)) * delta);
;             hv[i][0] = a0 * dec; hv[i][1] = a1 * dec; hv[i][2] = a2 * dec; hv[i][3] = a3v * dec;
	v_pk_fma_f32 v[54:55], v[64:65], v[82:83], v[52:53] op_sel_hi:[0,1,1]
	v_pk_fma_f32 v[52:53], v[160:161], v[56:57], v[58:59] op_sel_hi:[0,1,1]
	v_pk_fma_f32 v[52:53], v[160:161], v[66:67], v[52:53] op_sel:[1,0,0]
	s_nop 0
	v_pk_fma_f32 v[52:53], v[162:163], v[80:81], v[52:53] op_sel_hi:[0,1,1]
	v_pk_fma_f32 v[52:53], v[64:65], v[84:85], v[52:53] op_sel_hi:[0,1,1]
	s_add_u32 s100, s78, 0x1e880000
	s_addc_u32 s101, s79, 0
	global_load_dword v148, v113, s[100:101]
	s_add_u32 s100, s100, 0x4000
	s_addc_u32 s101, s101, 0
	global_load_dword v149, v113, s[100:101]
	s_add_u32 s100, s100, 0x4000
	s_addc_u32 s101, s101, 0
	global_load_dword v150, v113, s[100:101]
	s_add_u32 s100, s100, 0x4000
	s_addc_u32 s101, s101, 0
	global_load_dword v151, v113, s[100:101]
	s_add_u32 s100, s100, 0x4000
	s_addc_u32 s101, s101, 0
	global_load_dword v152, v113, s[100:101]
	s_add_u32 s100, s100, 0x4000
	s_addc_u32 s101, s101, 0
	global_load_dword v153, v113, s[100:101]
	s_add_u32 s100, s100, 0x4000
	s_addc_u32 s101, s101, 0
	global_load_dword v154, v113, s[100:101]
	s_add_u32 s100, s100, 0x4000
	s_addc_u32 s101, s101, 0
	global_load_dword v155, v113, s[100:101]
	s_add_u32 s100, s100, 0x4000
	s_addc_u32 s101, s101, 0
	global_load_dword v156, v113, s[100:101]
	s_add_u32 s100, s100, 0x4000
	s_addc_u32 s101, s101, 0
	global_load_dword v157, v113, s[100:101]
	s_add_u32 s100, s100, 0x4000
	s_addc_u32 s101, s101, 0
	global_load_dword v158, v113, s[100:101]
	s_add_u32 s100, s100, 0x4000
	s_addc_u32 s101, s101, 0
	global_load_dword v159, v113, s[100:101]
	s_add_u32 s100, s100, 0x4000
	s_addc_u32 s101, s101, 0
	global_load_dword v160, v113, s[100:101]
	s_add_u32 s100, s100, 0x4000
	s_addc_u32 s101, s101, 0
	global_load_dword v161, v113, s[100:101]
	s_add_u32 s100, s100, 0x4000
	s_addc_u32 s101, s101, 0
	global_load_dword v162, v113, s[100:101]
	s_add_u32 s100, s100, 0x4000
	s_addc_u32 s101, s101, 0
	global_load_dword v163, v113, s[100:101]
	s_waitcnt vmcnt(48)
	v_mov_b32_e32 v98, 0x300
	ds_read_b128 v[82:85], v98
	ds_read_b128 v[86:89], v98 offset:16
	ds_read_b128 v[90:93], v98 offset:32
	ds_read_b128 v[94:97], v98 offset:48
	s_waitcnt lgkmcnt(3)
	v_pk_fma_f32 v[54:55], v[164:165], v[82:83], v[54:55] op_sel_hi:[0,1,1]
	v_pk_fma_f32 v[52:53], v[164:165], v[84:85], v[52:53] op_sel_hi:[0,1,1]
	s_waitcnt lgkmcnt(2)
	v_pk_fma_f32 v[54:55], v[164:165], v[86:87], v[54:55] op_sel:[1,0,0]
	v_pk_fma_f32 v[52:53], v[164:165], v[88:89], v[52:53] op_sel:[1,0,0]
	s_waitcnt lgkmcnt(1)
	v_pk_fma_f32 v[54:55], v[166:167], v[90:91], v[54:55] op_sel_hi:[0,1,1]
	v_mov_b32_e32 v82, v167
	v_pk_fma_f32 v[52:53], v[166:167], v[92:93], v[52:53] op_sel_hi:[0,1,1]
	s_waitcnt lgkmcnt(0)
	v_pk_fma_f32 v[86:87], v[82:83], v[94:95], v[54:55] op_sel_hi:[0,1,1]
	v_pk_fma_f32 v[90:91], v[82:83], v[96:97], v[52:53] op_sel_hi:[0,1,1]
	ds_read_b128 v[52:55], v98 offset:64
	ds_read_b128 v[56:59], v98 offset:80
	ds_read_b128 v[82:85], v98 offset:96
	s_waitcnt lgkmcnt(2)
	v_pk_fma_f32 v[52:53], v[168:169], v[52:53], v[86:87] op_sel_hi:[0,1,1]
	ds_read_b128 v[86:89], v98 offset:112
	s_waitcnt lgkmcnt(2)
	v_pk_fma_f32 v[52:53], v[168:169], v[56:57], v[52:53] op_sel:[1,0,0]
	v_mov_b32_e32 v56, v171
	s_waitcnt lgkmcnt(1)
	v_pk_fma_f32 v[52:53], v[170:171], v[82:83], v[52:53] op_sel_hi:[0,1,1]
	s_waitcnt lgkmcnt(0)
	v_pk_fma_f32 v[82:83], v[56:57], v[86:87], v[52:53] op_sel_hi:[0,1,1]
	v_pk_fma_f32 v[52:53], v[168:169], v[54:55], v[90:91] op_sel_hi:[0,1,1]
	v_pk_fma_f32 v[52:53], v[168:169], v[58:59], v[52:53] op_sel:[1,0,0]
	s_nop 0
	v_pk_fma_f32 v[52:53], v[170:171], v[84:85], v[52:53] op_sel_hi:[0,1,1]
	v_pk_fma_f32 v[86:87], v[56:57], v[88:89], v[52:53] op_sel_hi:[0,1,1]
	ds_read_b128 v[52:55], v98 offset:128
	ds_read_b128 v[56:59], v98 offset:144
	ds_read_b128 v[78:81], v98 offset:160
	s_waitcnt lgkmcnt(2)
	v_pk_fma_f32 v[52:53], v[172:173], v[52:53], v[82:83] op_sel_hi:[0,1,1]
	ds_read_b128 v[82:85], v98 offset:176
	v_pk_fma_f32 v[54:55], v[172:173], v[54:55], v[86:87] op_sel_hi:[0,1,1]
	s_waitcnt lgkmcnt(2)
	v_pk_fma_f32 v[52:53], v[172:173], v[56:57], v[52:53] op_sel:[1,0,0]
	v_pk_fma_f32 v[54:55], v[172:173], v[58:59], v[54:55] op_sel:[1,0,0]
	s_waitcnt lgkmcnt(1)
	v_pk_fma_f32 v[52:53], v[174:175], v[78:79], v[52:53] op_sel_hi:[0,1,1]
	v_mov_b32_e32 v56, v175
	v_pk_fma_f32 v[54:55], v[174:175], v[80:81], v[54:55] op_sel_hi:[0,1,1]
	s_waitcnt lgkmcnt(0)
	v_pk_fma_f32 v[52:53], v[56:57], v[82:83], v[52:53] op_sel_hi:[0,1,1]
	v_pk_fma_f32 v[58:59], v[56:57], v[84:85], v[54:55] op_sel_hi:[0,1,1]
	ds_read_b128 v[54:57], v98 offset:192
	ds_read_b128 v[64:67], v98 offset:208
	ds_read_b128 v[78:81], v98 offset:224
	ds_read_b128 v[82:85], v98 offset:240
	s_waitcnt lgkmcnt(3)
	v_pk_fma_f32 v[52:53], v[176:177], v[54:55], v[52:53] op_sel_hi:[0,1,1]
	s_waitcnt lgkmcnt(2)
	v_pk_fma_f32 v[52:53], v[176:177], v[64:65], v[52:53] op_sel:[1,0,0]
	v_mov_b32_e32 v64, v179
	s_waitcnt lgkmcnt(1)
	v_pk_fma_f32 v[52:53], v[178:179], v[78:79], v[52:53] op_sel_hi:[0,1,1]
	s_waitcnt lgkmcnt(0)
; __device__ void ph_filter_gen(const Params& P, int j, const float* __restrict__ a3, float* __restrict__ kf, float* sl) {
;     ...
;         for (int i = 0; i < 8; ++i) { const int t = tid + NT * i; const float4* ar = (const float4*)(a3 + (size_t)t * 64);
;             float a0 = 0.f, a1 = 0.f, a2 = 0.f, a3v = 0.f;
; #pragma unroll 4
;             for (int jq = 0; jq < 16; ++jq) { const float4 av = ar[jq]; const float ae[4] = {av.x, av.y, av.z, av.w};
; #pragma unroll
;                 for (int e = 0; e < 4; ++e) { const float4 wv = *(const float4*)(sw + (jq * 4 + e) * 4); a0 += ae[e] * wv.x; a1 += ae[e] * wv.y; a2 += ae[e] * wv.z; a3v += ae[e] * wv.w; } }
;             const float dec = expf(-((float)t / (float)(SEQ - 1)) * delta);
;             hv[i][0] = a0 * dec; hv[i][1] = a1 * dec; hv[i][2] = a2 * dec; hv[i][3] = a3v * dec;
;             n0 += fabsf(hv[i][0]) + (t >= 1 ? fabsf(hv[i][1]) : 0.f); n1 += fabsf(hv[i][2]) + (t >= 1 ? fabsf(hv[i][3]) : 0.f); }
	v_pk_fma_f32 v[54:55], v[64:65], v[82:83], v[52:53] op_sel_hi:[0,1,1]
	v_pk_fma_f32 v[52:53], v[176:177], v[56:57], v[58:59] op_sel_hi:[0,1,1]
	v_pk_fma_f32 v[52:53], v[176:177], v[66:67], v[52:53] op_sel:[1,0,0]
	s_nop 0
	v_pk_fma_f32 v[52:53], v[178:179], v[80:81], v[52:53] op_sel_hi:[0,1,1]
	v_pk_fma_f32 v[52:53], v[64:65], v[84:85], v[52:53] op_sel_hi:[0,1,1]
	s_add_u32 s100, s78, 0x1e8c0000
	s_addc_u32 s101, s79, 0
	global_load_dword v164, v113, s[100:101]
	s_add_u32 s100, s100, 0x4000
	s_addc_u32 s101, s101, 0
	global_load_dword v165, v113, s[100:101]
	s_add_u32 s100, s100, 0x4000
	s_addc_u32 s101, s101, 0
	global_load_dword v166, v113, s[100:101]
	s_add_u32 s100, s100, 0x4000
	s_addc_u32 s101, s101, 0
	global_load_dword v167, v113, s[100:101]
	s_add_u32 s100, s100, 0x4000
	s_addc_u32 s101, s101, 0
	global_load_dword v168, v113, s[100:101]
	s_add_u32 s100, s100, 0x4000
	s_addc_u32 s101, s101, 0
	global_load_dword v169, v113, s[100:101]
	s_add_u32 s100, s100, 0x4000
	s_addc_u32 s101, s101, 0
	global_load_dword v170, v113, s[100:101]
	s_add_u32 s100, s100, 0x4000
	s_addc_u32 s101, s101, 0
	global_load_dword v171, v113, s[100:101]
	s_add_u32 s100, s100, 0x4000
	s_addc_u32 s101, s101, 0
	global_load_dword v172, v113, s[100:101]
	s_add_u32 s100, s100, 0x4000
	s_addc_u32 s101, s101, 0
	global_load_dword v173, v113, s[100:101]
	s_add_u32 s100, s100, 0x4000
	s_addc_u32 s101, s101, 0
	global_load_dword v174, v113, s[100:101]
	s_add_u32 s100, s100, 0x4000
	s_addc_u32 s101, s101, 0
	global_load_dword v175, v113, s[100:101]
	s_add_u32 s100, s100, 0x4000
	s_addc_u32 s101, s101, 0
	global_load_dword v176, v113, s[100:101]
	s_add_u32 s100, s100, 0x4000
	s_addc_u32 s101, s101, 0
	global_load_dword v177, v113, s[100:101]
	s_add_u32 s100, s100, 0x4000
	s_addc_u32 s101, s101, 0
	global_load_dword v178, v113, s[100:101]
	s_add_u32 s100, s100, 0x4000
	s_addc_u32 s101, s101, 0
	global_load_dword v179, v113, s[100:101]
	v_mov_b32_e32 v58, 0
	s_mov_b32 s0, 0
	s_mov_b64 s[14:15], 0
	v_mov_b32_e32 v59, v58
	v_mov_b32_e32 v56, v58
	v_mov_b32_e32 v57, v58
.LBB0_231:
	v_add_u32_e32 v113, 0x3000, v68
	s_waitcnt vmcnt(48)
	v_mov_b32_e32 v102, 0
	ds_read_b128 v[86:89], v102
	ds_read_b128 v[90:93], v102 offset:16
	ds_read_b128 v[94:97], v102 offset:32
	ds_read_b128 v[98:101], v102 offset:48
	s_waitcnt lgkmcnt(3)
	v_pk_fma_f32 v[58:59], v[116:117], v[86:87], v[58:59] op_sel_hi:[0,1,1]
	v_pk_fma_f32 v[56:57], v[116:117], v[88:89], v[56:57] op_sel_hi:[0,1,1]
	s_waitcnt lgkmcnt(2)
	v_pk_fma_f32 v[58:59], v[116:117], v[90:91], v[58:59] op_sel:[1,0,0]
	v_pk_fma_f32 v[56:57], v[116:117], v[92:93], v[56:57] op_sel:[1,0,0]
	s_waitcnt lgkmcnt(1)
	v_pk_fma_f32 v[58:59], v[118:119], v[94:95], v[58:59] op_sel_hi:[0,1,1]
	v_mov_b32_e32 v86, v119
	v_pk_fma_f32 v[56:57], v[118:119], v[96:97], v[56:57] op_sel_hi:[0,1,1]
	s_waitcnt lgkmcnt(0)
	v_pk_fma_f32 v[90:91], v[86:87], v[98:99], v[58:59] op_sel_hi:[0,1,1]
	v_pk_fma_f32 v[94:95], v[86:87], v[100:101], v[56:57] op_sel_hi:[0,1,1]
	ds_read_b128 v[56:59], v102 offset:64
	ds_read_b128 v[60:63], v102 offset:80
	ds_read_b128 v[86:89], v102 offset:96
	s_waitcnt lgkmcnt(2)
	v_pk_fma_f32 v[56:57], v[120:121], v[56:57], v[90:91] op_sel_hi:[0,1,1]
	ds_read_b128 v[90:93], v102 offset:112
	s_waitcnt lgkmcnt(2)
	v_pk_fma_f32 v[56:57], v[120:121], v[60:61], v[56:57] op_sel:[1,0,0]
	v_mov_b32_e32 v60, v123
	s_waitcnt lgkmcnt(1)
	v_pk_fma_f32 v[56:57], v[122:123], v[86:87], v[56:57] op_sel_hi:[0,1,1]
	s_waitcnt lgkmcnt(0)
	v_pk_fma_f32 v[86:87], v[60:61], v[90:91], v[56:57] op_sel_hi:[0,1,1]
	v_pk_fma_f32 v[56:57], v[120:121], v[58:59], v[94:95] op_sel_hi:[0,1,1]
	v_pk_fma_f32 v[56:57], v[120:121], v[62:63], v[56:57] op_sel:[1,0,0]
	s_nop 0
	v_pk_fma_f32 v[56:57], v[122:123], v[88:89], v[56:57] op_sel_hi:[0,1,1]
	v_pk_fma_f32 v[90:91], v[60:61], v[92:93], v[56:57] op_sel_hi:[0,1,1]
	ds_read_b128 v[56:59], v102 offset:128
	ds_read_b128 v[60:63], v102 offset:144
	ds_read_b128 v[82:85], v102 offset:160
	s_waitcnt lgkmcnt(2)
	v_pk_fma_f32 v[56:57], v[124:125], v[56:57], v[86:87] op_sel_hi:[0,1,1]
	ds_read_b128 v[86:89], v102 offset:176
	v_pk_fma_f32 v[58:59], v[124:125], v[58:59], v[90:91] op_sel_hi:[0,1,1]
	s_waitcnt lgkmcnt(2)
	v_pk_fma_f32 v[56:57], v[124:125], v[60:61], v[56:57] op_sel:[1,0,0]
	v_pk_fma_f32 v[58:59], v[124:125], v[62:63], v[58:59] op_sel:[1,0,0]
	s_waitcnt lgkmcnt(1)
	v_pk_fma_f32 v[56:57], v[126:127], v[82:83], v[56:57] op_sel_hi:[0,1,1]
	v_mov_b32_e32 v60, v127
	v_pk_fma_f32 v[58:59], v[126:127], v[84:85], v[58:59] op_sel_hi:[0,1,1]
	s_waitcnt lgkmcnt(0)
	v_pk_fma_f32 v[56:57], v[60:61], v[86:87], v[56:57] op_sel_hi:[0,1,1]
	v_pk_fma_f32 v[62:63], v[60:61], v[88:89], v[58:59] op_sel_hi:[0,1,1]
	ds_read_b128 v[58:61], v102 offset:192
	ds_read_b128 v[78:81], v102 offset:208
	ds_read_b128 v[82:85], v102 offset:224
	ds_read_b128 v[86:89], v102 offset:240
	s_waitcnt lgkmcnt(3)
	v_pk_fma_f32 v[56:57], v[128:129], v[58:59], v[56:57] op_sel_hi:[0,1,1]
	s_waitcnt lgkmcnt(2)
	v_pk_fma_f32 v[56:57], v[128:129], v[78:79], v[56:57] op_sel:[1,0,0]
	v_mov_b32_e32 v78, v131
	s_waitcnt lgkmcnt(1)
	v_pk_fma_f32 v[56:57], v[130:131], v[82:83], v[56:57] op_sel_hi:[0,1,1]
	s_waitcnt lgkmcnt(0)
; __device__ void ph_filter_gen(const Params& P, int j, const float* __restrict__ a3, float* __restrict__ kf, float* sl) {
;     ...
;         for (int i = 0; i < 8; ++i) { const int t = tid + NT * i; const float4* ar = (const float4*)(a3 + (size_t)t * 64);
;             float a0 = 0.f, a1 = 0.f, a2 = 0.f, a3v = 0.f;
; #pragma unroll 4
;             for (int jq = 0; jq < 16; ++jq) { const float4 av = ar[jq]; const float ae[4] = {av.x, av.y, av.z, av.w};
; #pragma unroll
;                 for (int e = 0; e < 4; ++e) { const float4 wv = *(const float4*)(sw + (jq * 4 + e) * 4); a0 += ae[e] * wv.x; a1 += ae[e] * wv.y; a2 += ae[e] * wv.z; a3v += ae[e] * wv.w; } }
;             const float dec = expf(-((float)t / (float)(SEQ - 1)) * delta);
;             hv[i][0] = a0 * dec; hv[i][1] = a1 * dec; hv[i][2] = a2 * dec; hv[i][3] = a3v * dec;
;             n0 += fabsf(hv[i][0]) + (t >= 1 ? fabsf(hv[i][1]) : 0.f); n1 += fabsf(hv[i][2]) + (t >= 1 ? fabsf(hv[i][3]) : 0.f); }
	v_pk_fma_f32 v[58:59], v[78:79], v[86:87], v[56:57] op_sel_hi:[0,1,1]
	v_pk_fma_f32 v[56:57], v[128:129], v[60:61], v[62:63] op_sel_hi:[0,1,1]
	v_pk_fma_f32 v[56:57], v[128:129], v[80:81], v[56:57] op_sel:[1,0,0]
	s_nop 0
	v_pk_fma_f32 v[56:57], v[130:131], v[84:85], v[56:57] op_sel_hi:[0,1,1]
	v_pk_fma_f32 v[56:57], v[78:79], v[88:89], v[56:57] op_sel_hi:[0,1,1]
	s_add_u32 s100, s78, 0x1e800000
	s_addc_u32 s101, s79, 0
	global_load_dword v116, v113, s[100:101]
	s_add_u32 s100, s100, 0x4000
	s_addc_u32 s101, s101, 0
	global_load_dword v117, v113, s[100:101]
	s_add_u32 s100, s100, 0x4000
	s_addc_u32 s101, s101, 0
	global_load_dword v118, v113, s[100:101]
	s_add_u32 s100, s100, 0x4000
	s_addc_u32 s101, s101, 0
	global_load_dword v119, v113, s[100:101]
	s_add_u32 s100, s100, 0x4000
	s_addc_u32 s101, s101, 0
	global_load_dword v120, v113, s[100:101]
	s_add_u32 s100, s100, 0x4000
	s_addc_u32 s101, s101, 0
	global_load_dword v121, v113, s[100:101]
	s_add_u32 s100, s100, 0x4000
	s_addc_u32 s101, s101, 0
	global_load_dword v122, v113, s[100:101]
	s_add_u32 s100, s100, 0x4000
	s_addc_u32 s101, s101, 0
	global_load_dword v123, v113, s[100:101]
	s_add_u32 s100, s100, 0x4000
	s_addc_u32 s101, s101, 0
	global_load_dword v124, v113, s[100:101]
	s_add_u32 s100, s100, 0x4000
	s_addc_u32 s101, s101, 0
	global_load_dword v125, v113, s[100:101]
	s_add_u32 s100, s100, 0x4000
	s_addc_u32 s101, s101, 0
	global_load_dword v126, v113, s[100:101]
	s_add_u32 s100, s100, 0x4000
	s_addc_u32 s101, s101, 0
	global_load_dword v127, v113, s[100:101]
	s_add_u32 s100, s100, 0x4000
	s_addc_u32 s101, s101, 0
	global_load_dword v128, v113, s[100:101]
	s_add_u32 s100, s100, 0x4000
	s_addc_u32 s101, s101, 0
	global_load_dword v129, v113, s[100:101]
	s_add_u32 s100, s100, 0x4000
	s_addc_u32 s101, s101, 0
	global_load_dword v130, v113, s[100:101]
	s_add_u32 s100, s100, 0x4000
	s_addc_u32 s101, s101, 0
	global_load_dword v131, v113, s[100:101]
	s_waitcnt vmcnt(48)
	v_mov_b32_e32 v102, 0x100
	ds_read_b128 v[86:89], v102
	ds_read_b128 v[90:93], v102 offset:16
	ds_read_b128 v[94:97], v102 offset:32
	ds_read_b128 v[98:101], v102 offset:48
	s_waitcnt lgkmcnt(3)
	v_pk_fma_f32 v[58:59], v[132:133], v[86:87], v[58:59] op_sel_hi:[0,1,1]
	v_pk_fma_f32 v[56:57], v[132:133], v[88:89], v[56:57] op_sel_hi:[0,1,1]
	s_waitcnt lgkmcnt(2)
	v_pk_fma_f32 v[58:59], v[132:133], v[90:91], v[58:59] op_sel:[1,0,0]
	v_pk_fma_f32 v[56:57], v[132:133], v[92:93], v[56:57] op_sel:[1,0,0]
	s_waitcnt lgkmcnt(1)
	v_pk_fma_f32 v[58:59], v[134:135], v[94:95], v[58:59] op_sel_hi:[0,1,1]
	v_mov_b32_e32 v86, v135
	v_pk_fma_f32 v[56:57], v[134:135], v[96:97], v[56:57] op_sel_hi:[0,1,1]
	s_waitcnt lgkmcnt(0)
	v_pk_fma_f32 v[90:91], v[86:87], v[98:99], v[58:59] op_sel_hi:[0,1,1]
	v_pk_fma_f32 v[94:95], v[86:87], v[100:101], v[56:57] op_sel_hi:[0,1,1]
	ds_read_b128 v[56:59], v102 offset:64
	ds_read_b128 v[60:63], v102 offset:80
	ds_read_b128 v[86:89], v102 offset:96
	s_waitcnt lgkmcnt(2)
	v_pk_fma_f32 v[56:57], v[136:137], v[56:57], v[90:91] op_sel_hi:[0,1,1]
	ds_read_b128 v[90:93], v102 offset:112
	s_waitcnt lgkmcnt(2)
	v_pk_fma_f32 v[56:57], v[136:137], v[60:61], v[56:57] op_sel:[1,0,0]
	v_mov_b32_e32 v60, v139
	s_waitcnt lgkmcnt(1)
	v_pk_fma_f32 v[56:57], v[138:139], v[86:87], v[56:57] op_sel_hi:[0,1,1]
	s_waitcnt lgkmcnt(0)
	v_pk_fma_f32 v[86:87], v[60:61], v[90:91], v[56:57] op_sel_hi:[0,1,1]
	v_pk_fma_f32 v[56:57], v[136:137], v[58:59], v[94:95] op_sel_hi:[0,1,1]
	v_pk_fma_f32 v[56:57], v[136:137], v[62:63], v[56:57] op_sel:[1,0,0]
	s_nop 0
	v_pk_fma_f32 v[56:57], v[138:139], v[88:89], v[56:57] op_sel_hi:[0,1,1]
	v_pk_fma_f32 v[90:91], v[60:61], v[92:93], v[56:57] op_sel_hi:[0,1,1]
	ds_read_b128 v[56:59], v102 offset:128
	ds_read_b128 v[60:63], v102 offset:144
	ds_read_b128 v[82:85], v102 offset:160
	s_waitcnt lgkmcnt(2)
	v_pk_fma_f32 v[56:57], v[140:141], v[56:57], v[86:87] op_sel_hi:[0,1,1]
	ds_read_b128 v[86:89], v102 offset:176
	v_pk_fma_f32 v[58:59], v[140:141], v[58:59], v[90:91] op_sel_hi:[0,1,1]
	s_waitcnt lgkmcnt(2)
	v_pk_fma_f32 v[56:57], v[140:141], v[60:61], v[56:57] op_sel:[1,0,0]
	v_pk_fma_f32 v[58:59], v[140:141], v[62:63], v[58:59] op_sel:[1,0,0]
	s_waitcnt lgkmcnt(1)
	v_pk_fma_f32 v[56:57], v[142:143], v[82:83], v[56:57] op_sel_hi:[0,1,1]
	v_mov_b32_e32 v60, v143
	v_pk_fma_f32 v[58:59], v[142:143], v[84:85], v[58:59] op_sel_hi:[0,1,1]
	s_waitcnt lgkmcnt(0)
	v_pk_fma_f32 v[56:57], v[60:61], v[86:87], v[56:57] op_sel_hi:[0,1,1]
	v_pk_fma_f32 v[62:63], v[60:61], v[88:89], v[58:59] op_sel_hi:[0,1,1]
	ds_read_b128 v[58:61], v102 offset:192
	ds_read_b128 v[78:81], v102 offset:208
	ds_read_b128 v[82:85], v102 offset:224
	ds_read_b128 v[86:89], v102 offset:240
	s_waitcnt lgkmcnt(3)
	v_pk_fma_f32 v[56:57], v[144:145], v[58:59], v[56:57] op_sel_hi:[0,1,1]
	s_waitcnt lgkmcnt(2)
	v_pk_fma_f32 v[56:57], v[144:145], v[78:79], v[56:57] op_sel:[1,0,0]
	v_mov_b32_e32 v78, v147
	s_waitcnt lgkmcnt(1)
	v_pk_fma_f32 v[56:57], v[146:147], v[82:83], v[56:57] op_sel_hi:[0,1,1]
	s_waitcnt lgkmcnt(0)
; __device__ void ph_filter_gen(const Params& P, int j, const float* __restrict__ a3, float* __restrict__ kf, float* sl) {
;     ...
;         for (int i = 0; i < 8; ++i) { const int t = tid + NT * i; const float4* ar = (const float4*)(a3 + (size_t)t * 64);
;             float a0 = 0.f, a1 = 0.f, a2 = 0.f, a3v = 0.f;
; #pragma unroll 4
;             for (int jq = 0; jq < 16; ++jq) { const float4 av = ar[jq]; const float ae[4] = {av.x, av.y, av.z, av.w};
; #pragma unroll
;                 for (int e = 0; e < 4; ++e) { const float4 wv = *(const float4*)(sw + (jq * 4 + e) * 4); a0 += ae[e] * wv.x; a1 += ae[e] * wv.y; a2 += ae[e] * wv.z; a3v += ae[e] * wv.w; } }
;             const float dec = expf(-((float)t / (float)(SEQ - 1)) * delta);
;             hv[i][0] = a0 * dec; hv[i][1] = a1 * dec; hv[i][2] = a2 * dec; hv[i][3] = a3v * dec;
;             n0 += fabsf(hv[i][0]) + (t >= 1 ? fabsf(hv[i][1]) : 0.f); n1 += fabsf(hv[i][2]) + (t >= 1 ? fabsf(hv[i][3]) : 0.f); }
	v_pk_fma_f32 v[58:59], v[78:79], v[86:87], v[56:57] op_sel_hi:[0,1,1]
	v_pk_fma_f32 v[56:57], v[144:145], v[60:61], v[62:63] op_sel_hi:[0,1,1]
	v_pk_fma_f32 v[56:57], v[144:145], v[80:81], v[56:57] op_sel:[1,0,0]
	s_nop 0
	v_pk_fma_f32 v[56:57], v[146:147], v[84:85], v[56:57] op_sel_hi:[0,1,1]
	v_pk_fma_f32 v[56:57], v[78:79], v[88:89], v[56:57] op_sel_hi:[0,1,1]
	s_add_u32 s100, s78, 0x1e840000
	s_addc_u32 s101, s79, 0
	global_load_dword v132, v113, s[100:101]
	s_add_u32 s100, s100, 0x4000
	s_addc_u32 s101, s101, 0
	global_load_dword v133, v113, s[100:101]
	s_add_u32 s100, s100, 0x4000
	s_addc_u32 s101, s101, 0
	global_load_dword v134, v113, s[100:101]
	s_add_u32 s100, s100, 0x4000
	s_addc_u32 s101, s101, 0
	global_load_dword v135, v113, s[100:101]
	s_add_u32 s100, s100, 0x4000
	s_addc_u32 s101, s101, 0
	global_load_dword v136, v113, s[100:101]
	s_add_u32 s100, s100, 0x4000
	s_addc_u32 s101, s101, 0
	global_load_dword v137, v113, s[100:101]
	s_add_u32 s100, s100, 0x4000
	s_addc_u32 s101, s101, 0
	global_load_dword v138, v113, s[100:101]
	s_add_u32 s100, s100, 0x4000
	s_addc_u32 s101, s101, 0
	global_load_dword v139, v113, s[100:101]
	s_add_u32 s100, s100, 0x4000
	s_addc_u32 s101, s101, 0
	global_load_dword v140, v113, s[100:101]
	s_add_u32 s100, s100, 0x4000
	s_addc_u32 s101, s101, 0
	global_load_dword v141, v113, s[100:101]
	s_add_u32 s100, s100, 0x4000
	s_addc_u32 s101, s101, 0
	global_load_dword v142, v113, s[100:101]
	s_add_u32 s100, s100, 0x4000
	s_addc_u32 s101, s101, 0
	global_load_dword v143, v113, s[100:101]
	s_add_u32 s100, s100, 0x4000
	s_addc_u32 s101, s101, 0
	global_load_dword v144, v113, s[100:101]
	s_add_u32 s100, s100, 0x4000
	s_addc_u32 s101, s101, 0
	global_load_dword v145, v113, s[100:101]
	s_add_u32 s100, s100, 0x4000
	s_addc_u32 s101, s101, 0
	global_load_dword v146, v113, s[100:101]
	s_add_u32 s100, s100, 0x4000
	s_addc_u32 s101, s101, 0
	global_load_dword v147, v113, s[100:101]
	s_waitcnt vmcnt(48)
	v_mov_b32_e32 v102, 0x200
	ds_read_b128 v[86:89], v102
	ds_read_b128 v[90:93], v102 offset:16
	ds_read_b128 v[94:97], v102 offset:32
	ds_read_b128 v[98:101], v102 offset:48
	s_waitcnt lgkmcnt(3)
	v_pk_fma_f32 v[58:59], v[148:149], v[86:87], v[58:59] op_sel_hi:[0,1,1]
	v_pk_fma_f32 v[56:57], v[148:149], v[88:89], v[56:57] op_sel_hi:[0,1,1]
	s_waitcnt lgkmcnt(2)
	v_pk_fma_f32 v[58:59], v[148:149], v[90:91], v[58:59] op_sel:[1,0,0]
	v_pk_fma_f32 v[56:57], v[148:149], v[92:93], v[56:57] op_sel:[1,0,0]
	s_waitcnt lgkmcnt(1)
	v_pk_fma_f32 v[58:59], v[150:151], v[94:95], v[58:59] op_sel_hi:[0,1,1]
	v_mov_b32_e32 v86, v151
	v_pk_fma_f32 v[56:57], v[150:151], v[96:97], v[56:57] op_sel_hi:[0,1,1]
	s_waitcnt lgkmcnt(0)
	v_pk_fma_f32 v[90:91], v[86:87], v[98:99], v[58:59] op_sel_hi:[0,1,1]
	v_pk_fma_f32 v[94:95], v[86:87], v[100:101], v[56:57] op_sel_hi:[0,1,1]
	ds_read_b128 v[56:59], v102 offset:64
	ds_read_b128 v[60:63], v102 offset:80
	ds_read_b128 v[86:89], v102 offset:96
	s_waitcnt lgkmcnt(2)
	v_pk_fma_f32 v[56:57], v[152:153], v[56:57], v[90:91] op_sel_hi:[0,1,1]
	ds_read_b128 v[90:93], v102 offset:112
	s_waitcnt lgkmcnt(2)
	v_pk_fma_f32 v[56:57], v[152:153], v[60:61], v[56:57] op_sel:[1,0,0]
	v_mov_b32_e32 v60, v155
	s_waitcnt lgkmcnt(1)
	v_pk_fma_f32 v[56:57], v[154:155], v[86:87], v[56:57] op_sel_hi:[0,1,1]
	s_waitcnt lgkmcnt(0)
	v_pk_fma_f32 v[86:87], v[60:61], v[90:91], v[56:57] op_sel_hi:[0,1,1]
	v_pk_fma_f32 v[56:57], v[152:153], v[58:59], v[94:95] op_sel_hi:[0,1,1]
	v_pk_fma_f32 v[56:57], v[152:153], v[62:63], v[56:57] op_sel:[1,0,0]
	s_nop 0
	v_pk_fma_f32 v[56:57], v[154:155], v[88:89], v[56:57] op_sel_hi:[0,1,1]
	v_pk_fma_f32 v[90:91], v[60:61], v[92:93], v[56:57] op_sel_hi:[0,1,1]
	ds_read_b128 v[56:59], v102 offset:128
	ds_read_b128 v[60:63], v102 offset:144
	ds_read_b128 v[82:85], v102 offset:160
	s_waitcnt lgkmcnt(2)
	v_pk_fma_f32 v[56:57], v[156:157], v[56:57], v[86:87] op_sel_hi:[0,1,1]
	ds_read_b128 v[86:89], v102 offset:176
	v_pk_fma_f32 v[58:59], v[156:157], v[58:59], v[90:91] op_sel_hi:[0,1,1]
	s_waitcnt lgkmcnt(2)
	v_pk_fma_f32 v[56:57], v[156:157], v[60:61], v[56:57] op_sel:[1,0,0]
	v_pk_fma_f32 v[58:59], v[156:157], v[62:63], v[58:59] op_sel:[1,0,0]
	s_waitcnt lgkmcnt(1)
	v_pk_fma_f32 v[56:57], v[158:159], v[82:83], v[56:57] op_sel_hi:[0,1,1]
	v_mov_b32_e32 v60, v159
	v_pk_fma_f32 v[58:59], v[158:159], v[84:85], v[58:59] op_sel_hi:[0,1,1]
	s_waitcnt lgkmcnt(0)
	v_pk_fma_f32 v[56:57], v[60:61], v[86:87], v[56:57] op_sel_hi:[0,1,1]
	v_pk_fma_f32 v[62:63], v[60:61], v[88:89], v[58:59] op_sel_hi:[0,1,1]
	ds_read_b128 v[58:61], v102 offset:192
	ds_read_b128 v[78:81], v102 offset:208
	ds_read_b128 v[82:85], v102 offset:224
	ds_read_b128 v[86:89], v102 offset:240
	s_waitcnt lgkmcnt(3)
	v_pk_fma_f32 v[56:57], v[160:161], v[58:59], v[56:57] op_sel_hi:[0,1,1]
	s_waitcnt lgkmcnt(2)
	v_pk_fma_f32 v[56:57], v[160:161], v[78:79], v[56:57] op_sel:[1,0,0]
	v_mov_b32_e32 v78, v163
	s_waitcnt lgkmcnt(1)
	v_pk_fma_f32 v[56:57], v[162:163], v[82:83], v[56:57] op_sel_hi:[0,1,1]
	s_waitcnt lgkmcnt(0)
; __device__ void ph_filter_gen(const Params& P, int j, const float* __restrict__ a3, float* __restrict__ kf, float* sl) {
;     ...
;         for (int i = 0; i < 8; ++i) { const int t = tid + NT * i; const float4* ar = (const float4*)(a3 + (size_t)t * 64);
;             float a0 = 0.f, a1 = 0.f, a2 = 0.f, a3v = 0.f;
; #pragma unroll 4
;             for (int jq = 0; jq < 16; ++jq) { const float4 av = ar[jq]; const float ae[4] = {av.x, av.y, av.z, av.w};
; #pragma unroll
;                 for (int e = 0; e < 4; ++e) { const float4 wv = *(const float4*)(sw + (jq * 4 + e) * 4); a0 += ae[e] * wv.x; a1 += ae[e] * wv.y; a2 += ae[e] * wv.z; a3v += ae[e] * wv.w; } }
;             const float dec = expf(-((float)t / (float)(SEQ - 1)) * delta);
;             hv[i][0] = a0 * dec; hv[i][1] = a1 * dec; hv[i][2] = a2 * dec; hv[i][3] = a3v * dec;
;             n0 += fabsf(hv[i][0]) + (t >= 1 ? fabsf(hv[i][1]) : 0.f); n1 += fabsf(hv[i][2]) + (t >= 1 ? fabsf(hv[i][3]) : 0.f); }
	v_pk_fma_f32 v[58:59], v[78:79], v[86:87], v[56:57] op_sel_hi:[0,1,1]
	v_pk_fma_f32 v[56:57], v[160:161], v[60:61], v[62:63] op_sel_hi:[0,1,1]
	v_pk_fma_f32 v[56:57], v[160:161], v[80:81], v[56:57] op_sel:[1,0,0]
	s_nop 0
	v_pk_fma_f32 v[56:57], v[162:163], v[84:85], v[56:57] op_sel_hi:[0,1,1]
	v_pk_fma_f32 v[56:57], v[78:79], v[88:89], v[56:57] op_sel_hi:[0,1,1]
	s_add_u32 s100, s78, 0x1e880000
	s_addc_u32 s101, s79, 0
	global_load_dword v148, v113, s[100:101]
	s_add_u32 s100, s100, 0x4000
	s_addc_u32 s101, s101, 0
	global_load_dword v149, v113, s[100:101]
	s_add_u32 s100, s100, 0x4000
	s_addc_u32 s101, s101, 0
	global_load_dword v150, v113, s[100:101]
	s_add_u32 s100, s100, 0x4000
	s_addc_u32 s101, s101, 0
	global_load_dword v151, v113, s[100:101]
	s_add_u32 s100, s100, 0x4000
	s_addc_u32 s101, s101, 0
	global_load_dword v152, v113, s[100:101]
	s_add_u32 s100, s100, 0x4000
	s_addc_u32 s101, s101, 0
	global_load_dword v153, v113, s[100:101]
	s_add_u32 s100, s100, 0x4000
	s_addc_u32 s101, s101, 0
	global_load_dword v154, v113, s[100:101]
	s_add_u32 s100, s100, 0x4000
	s_addc_u32 s101, s101, 0
	global_load_dword v155, v113, s[100:101]
	s_add_u32 s100, s100, 0x4000
	s_addc_u32 s101, s101, 0
	global_load_dword v156, v113, s[100:101]
	s_add_u32 s100, s100, 0x4000
	s_addc_u32 s101, s101, 0
	global_load_dword v157, v113, s[100:101]
	s_add_u32 s100, s100, 0x4000
	s_addc_u32 s101, s101, 0
	global_load_dword v158, v113, s[100:101]
	s_add_u32 s100, s100, 0x4000
	s_addc_u32 s101, s101, 0
	global_load_dword v159, v113, s[100:101]
	s_add_u32 s100, s100, 0x4000
	s_addc_u32 s101, s101, 0
	global_load_dword v160, v113, s[100:101]
	s_add_u32 s100, s100, 0x4000
	s_addc_u32 s101, s101, 0
	global_load_dword v161, v113, s[100:101]
	s_add_u32 s100, s100, 0x4000
	s_addc_u32 s101, s101, 0
	global_load_dword v162, v113, s[100:101]
	s_add_u32 s100, s100, 0x4000
	s_addc_u32 s101, s101, 0
	global_load_dword v163, v113, s[100:101]
	s_waitcnt vmcnt(48)
	v_mov_b32_e32 v102, 0x300
	ds_read_b128 v[86:89], v102
	ds_read_b128 v[90:93], v102 offset:16
	ds_read_b128 v[94:97], v102 offset:32
	ds_read_b128 v[98:101], v102 offset:48
	s_waitcnt lgkmcnt(3)
	v_pk_fma_f32 v[58:59], v[164:165], v[86:87], v[58:59] op_sel_hi:[0,1,1]
	v_pk_fma_f32 v[56:57], v[164:165], v[88:89], v[56:57] op_sel_hi:[0,1,1]
	s_waitcnt lgkmcnt(2)
	v_pk_fma_f32 v[58:59], v[164:165], v[90:91], v[58:59] op_sel:[1,0,0]
	v_pk_fma_f32 v[56:57], v[164:165], v[92:93], v[56:57] op_sel:[1,0,0]
	s_waitcnt lgkmcnt(1)
	v_pk_fma_f32 v[58:59], v[166:167], v[94:95], v[58:59] op_sel_hi:[0,1,1]
	v_mov_b32_e32 v86, v167
	v_pk_fma_f32 v[56:57], v[166:167], v[96:97], v[56:57] op_sel_hi:[0,1,1]
	s_waitcnt lgkmcnt(0)
	v_pk_fma_f32 v[90:91], v[86:87], v[98:99], v[58:59] op_sel_hi:[0,1,1]
	v_pk_fma_f32 v[94:95], v[86:87], v[100:101], v[56:57] op_sel_hi:[0,1,1]
	ds_read_b128 v[56:59], v102 offset:64
	ds_read_b128 v[60:63], v102 offset:80
	ds_read_b128 v[86:89], v102 offset:96
	s_waitcnt lgkmcnt(2)
	v_pk_fma_f32 v[56:57], v[168:169], v[56:57], v[90:91] op_sel_hi:[0,1,1]
	ds_read_b128 v[90:93], v102 offset:112
	s_waitcnt lgkmcnt(2)
	v_pk_fma_f32 v[56:57], v[168:169], v[60:61], v[56:57] op_sel:[1,0,0]
	v_mov_b32_e32 v60, v171
	s_waitcnt lgkmcnt(1)
	v_pk_fma_f32 v[56:57], v[170:171], v[86:87], v[56:57] op_sel_hi:[0,1,1]
	s_waitcnt lgkmcnt(0)
	v_pk_fma_f32 v[86:87], v[60:61], v[90:91], v[56:57] op_sel_hi:[0,1,1]
	v_pk_fma_f32 v[56:57], v[168:169], v[58:59], v[94:95] op_sel_hi:[0,1,1]
	v_pk_fma_f32 v[56:57], v[168:169], v[62:63], v[56:57] op_sel:[1,0,0]
	s_nop 0
	v_pk_fma_f32 v[56:57], v[170:171], v[88:89], v[56:57] op_sel_hi:[0,1,1]
	v_pk_fma_f32 v[90:91], v[60:61], v[92:93], v[56:57] op_sel_hi:[0,1,1]
	ds_read_b128 v[56:59], v102 offset:128
	ds_read_b128 v[60:63], v102 offset:144
	ds_read_b128 v[82:85], v102 offset:160
	s_waitcnt lgkmcnt(2)
	v_pk_fma_f32 v[56:57], v[172:173], v[56:57], v[86:87] op_sel_hi:[0,1,1]
	ds_read_b128 v[86:89], v102 offset:176
	v_pk_fma_f32 v[58:59], v[172:173], v[58:59], v[90:91] op_sel_hi:[0,1,1]
	s_waitcnt lgkmcnt(2)
	v_pk_fma_f32 v[56:57], v[172:173], v[60:61], v[56:57] op_sel:[1,0,0]
	v_pk_fma_f32 v[58:59], v[172:173], v[62:63], v[58:59] op_sel:[1,0,0]
	s_waitcnt lgkmcnt(1)
	v_pk_fma_f32 v[56:57], v[174:175], v[82:83], v[56:57] op_sel_hi:[0,1,1]
	v_mov_b32_e32 v60, v175
	v_pk_fma_f32 v[58:59], v[174:175], v[84:85], v[58:59] op_sel_hi:[0,1,1]
	s_waitcnt lgkmcnt(0)
	v_pk_fma_f32 v[56:57], v[60:61], v[86:87], v[56:57] op_sel_hi:[0,1,1]
	v_pk_fma_f32 v[62:63], v[60:61], v[88:89], v[58:59] op_sel_hi:[0,1,1]
	ds_read_b128 v[58:61], v102 offset:192
	ds_read_b128 v[78:81], v102 offset:208
	ds_read_b128 v[82:85], v102 offset:224
	ds_read_b128 v[86:89], v102 offset:240
	s_waitcnt lgkmcnt(3)
	v_pk_fma_f32 v[56:57], v[176:177], v[58:59], v[56:57] op_sel_hi:[0,1,1]
	s_waitcnt lgkmcnt(2)
	v_pk_fma_f32 v[56:57], v[176:177], v[78:79], v[56:57] op_sel:[1,0,0]
	v_mov_b32_e32 v78, v179
	s_waitcnt lgkmcnt(1)
	v_pk_fma_f32 v[56:57], v[178:179], v[82:83], v[56:57] op_sel_hi:[0,1,1]
	s_waitcnt lgkmcnt(0)
; __device__ void ph_filter_gen(const Params& P, int j, const float* __restrict__ a3, float* __restrict__ kf, float* sl) {
;     ...
;         for (int i = 0; i < 8; ++i) { const int t = tid + NT * i; const float4* ar = (const float4*)(a3 + (size_t)t * 64);
;             float a0 = 0.f, a1 = 0.f, a2 = 0.f, a3v = 0.f;
; #pragma unroll 4
;             for (int jq = 0; jq < 16; ++jq) { const float4 av = ar[jq]; const float ae[4] = {av.x, av.y, av.z, av.w};
; #pragma unroll
;                 for (int e = 0; e < 4; ++e) { const float4 wv = *(const float4*)(sw + (jq * 4 + e) * 4); a0 += ae[e] * wv.x; a1 += ae[e] * wv.y; a2 += ae[e] * wv.z; a3v += ae[e] * wv.w; } }
;             const float dec = expf(-((float)t / (float)(SEQ - 1)) * delta);
;             hv[i][0] = a0 * dec; hv[i][1] = a1 * dec; hv[i][2] = a2 * dec; hv[i][3] = a3v * dec;
;             n0 += fabsf(hv[i][0]) + (t >= 1 ? fabsf(hv[i][1]) : 0.f); n1 += fabsf(hv[i][2]) + (t >= 1 ? fabsf(hv[i][3]) : 0.f); }
	v_pk_fma_f32 v[58:59], v[78:79], v[86:87], v[56:57] op_sel_hi:[0,1,1]
	v_pk_fma_f32 v[56:57], v[176:177], v[60:61], v[62:63] op_sel_hi:[0,1,1]
	v_pk_fma_f32 v[56:57], v[176:177], v[80:81], v[56:57] op_sel:[1,0,0]
	s_nop 0
	v_pk_fma_f32 v[56:57], v[178:179], v[84:85], v[56:57] op_sel_hi:[0,1,1]
	v_pk_fma_f32 v[56:57], v[78:79], v[88:89], v[56:57] op_sel_hi:[0,1,1]
	s_add_u32 s100, s78, 0x1e8c0000
	s_addc_u32 s101, s79, 0
	global_load_dword v164, v113, s[100:101]
	s_add_u32 s100, s100, 0x4000
	s_addc_u32 s101, s101, 0
	global_load_dword v165, v113, s[100:101]
	s_add_u32 s100, s100, 0x4000
	s_addc_u32 s101, s101, 0
	global_load_dword v166, v113, s[100:101]
	s_add_u32 s100, s100, 0x4000
	s_addc_u32 s101, s101, 0
	global_load_dword v167, v113, s[100:101]
	s_add_u32 s100, s100, 0x4000
	s_addc_u32 s101, s101, 0
	global_load_dword v168, v113, s[100:101]
	s_add_u32 s100, s100, 0x4000
	s_addc_u32 s101, s101, 0
	global_load_dword v169, v113, s[100:101]
	s_add_u32 s100, s100, 0x4000
	s_addc_u32 s101, s101, 0
	global_load_dword v170, v113, s[100:101]
	s_add_u32 s100, s100, 0x4000
	s_addc_u32 s101, s101, 0
	global_load_dword v171, v113, s[100:101]
	s_add_u32 s100, s100, 0x4000
	s_addc_u32 s101, s101, 0
	global_load_dword v172, v113, s[100:101]
	s_add_u32 s100, s100, 0x4000
	s_addc_u32 s101, s101, 0
	global_load_dword v173, v113, s[100:101]
	s_add_u32 s100, s100, 0x4000
	s_addc_u32 s101, s101, 0
	global_load_dword v174, v113, s[100:101]
	s_add_u32 s100, s100, 0x4000
	s_addc_u32 s101, s101, 0
	global_load_dword v175, v113, s[100:101]
	s_add_u32 s100, s100, 0x4000
	s_addc_u32 s101, s101, 0
	global_load_dword v176, v113, s[100:101]
	s_add_u32 s100, s100, 0x4000
	s_addc_u32 s101, s101, 0
	global_load_dword v177, v113, s[100:101]
	s_add_u32 s100, s100, 0x4000
	s_addc_u32 s101, s101, 0
	global_load_dword v178, v113, s[100:101]
	s_add_u32 s100, s100, 0x4000
	s_addc_u32 s101, s101, 0
	global_load_dword v179, v113, s[100:101]
	v_mov_b32_e32 v62, 0
	s_mov_b32 s0, 0
	s_mov_b64 s[14:15], 0
	v_mov_b32_e32 v63, v62
	v_mov_b32_e32 v60, v62
	v_mov_b32_e32 v61, v62
.LBB0_233:
	v_add_u32_e32 v113, 0x3800, v68
	s_waitcnt vmcnt(48)
	v_mov_b32_e32 v106, 0
	ds_read_b128 v[90:93], v106
	ds_read_b128 v[94:97], v106 offset:16
	ds_read_b128 v[98:101], v106 offset:32
	ds_read_b128 v[102:105], v106 offset:48
	s_waitcnt lgkmcnt(3)
	v_pk_fma_f32 v[62:63], v[116:117], v[90:91], v[62:63] op_sel_hi:[0,1,1]
	v_pk_fma_f32 v[60:61], v[116:117], v[92:93], v[60:61] op_sel_hi:[0,1,1]
	s_waitcnt lgkmcnt(2)
	v_pk_fma_f32 v[62:63], v[116:117], v[94:95], v[62:63] op_sel:[1,0,0]
	v_pk_fma_f32 v[60:61], v[116:117], v[96:97], v[60:61] op_sel:[1,0,0]
	s_waitcnt lgkmcnt(1)
	v_pk_fma_f32 v[62:63], v[118:119], v[98:99], v[62:63] op_sel_hi:[0,1,1]
	v_mov_b32_e32 v90, v119
	v_pk_fma_f32 v[60:61], v[118:119], v[100:101], v[60:61] op_sel_hi:[0,1,1]
	s_waitcnt lgkmcnt(0)
	v_pk_fma_f32 v[94:95], v[90:91], v[102:103], v[62:63] op_sel_hi:[0,1,1]
	v_pk_fma_f32 v[98:99], v[90:91], v[104:105], v[60:61] op_sel_hi:[0,1,1]
	ds_read_b128 v[60:63], v106 offset:64
	ds_read_b128 v[64:67], v106 offset:80
	ds_read_b128 v[90:93], v106 offset:96
	s_waitcnt lgkmcnt(2)
	v_pk_fma_f32 v[60:61], v[120:121], v[60:61], v[94:95] op_sel_hi:[0,1,1]
	ds_read_b128 v[94:97], v106 offset:112
	s_waitcnt lgkmcnt(2)
	v_pk_fma_f32 v[60:61], v[120:121], v[64:65], v[60:61] op_sel:[1,0,0]
	v_mov_b32_e32 v64, v123
	s_waitcnt lgkmcnt(1)
	v_pk_fma_f32 v[60:61], v[122:123], v[90:91], v[60:61] op_sel_hi:[0,1,1]
	s_waitcnt lgkmcnt(0)
	v_pk_fma_f32 v[90:91], v[64:65], v[94:95], v[60:61] op_sel_hi:[0,1,1]
	v_pk_fma_f32 v[60:61], v[120:121], v[62:63], v[98:99] op_sel_hi:[0,1,1]
	v_pk_fma_f32 v[60:61], v[120:121], v[66:67], v[60:61] op_sel:[1,0,0]
	s_nop 0
	v_pk_fma_f32 v[60:61], v[122:123], v[92:93], v[60:61] op_sel_hi:[0,1,1]
	v_pk_fma_f32 v[94:95], v[64:65], v[96:97], v[60:61] op_sel_hi:[0,1,1]
	ds_read_b128 v[60:63], v106 offset:128
	ds_read_b128 v[64:67], v106 offset:144
	ds_read_b128 v[86:89], v106 offset:160
	s_waitcnt lgkmcnt(2)
	v_pk_fma_f32 v[60:61], v[124:125], v[60:61], v[90:91] op_sel_hi:[0,1,1]
	ds_read_b128 v[90:93], v106 offset:176
	v_pk_fma_f32 v[62:63], v[124:125], v[62:63], v[94:95] op_sel_hi:[0,1,1]
	s_waitcnt lgkmcnt(2)
	v_pk_fma_f32 v[60:61], v[124:125], v[64:65], v[60:61] op_sel:[1,0,0]
	v_pk_fma_f32 v[62:63], v[124:125], v[66:67], v[62:63] op_sel:[1,0,0]
	s_waitcnt lgkmcnt(1)
	v_pk_fma_f32 v[60:61], v[126:127], v[86:87], v[60:61] op_sel_hi:[0,1,1]
	v_mov_b32_e32 v64, v127
	v_pk_fma_f32 v[62:63], v[126:127], v[88:89], v[62:63] op_sel_hi:[0,1,1]
	s_waitcnt lgkmcnt(0)
	v_pk_fma_f32 v[60:61], v[64:65], v[90:91], v[60:61] op_sel_hi:[0,1,1]
	v_pk_fma_f32 v[66:67], v[64:65], v[92:93], v[62:63] op_sel_hi:[0,1,1]
	ds_read_b128 v[62:65], v106 offset:192
	ds_read_b128 v[82:85], v106 offset:208
	ds_read_b128 v[86:89], v106 offset:224
	ds_read_b128 v[90:93], v106 offset:240
	s_waitcnt lgkmcnt(3)
	v_pk_fma_f32 v[60:61], v[128:129], v[62:63], v[60:61] op_sel_hi:[0,1,1]
	s_waitcnt lgkmcnt(2)
	v_pk_fma_f32 v[60:61], v[128:129], v[82:83], v[60:61] op_sel:[1,0,0]
	v_mov_b32_e32 v82, v131
	s_waitcnt lgkmcnt(1)
	v_pk_fma_f32 v[60:61], v[130:131], v[86:87], v[60:61] op_sel_hi:[0,1,1]
	s_waitcnt lgkmcnt(0)
; __device__ void ph_filter_gen(const Params& P, int j, const float* __restrict__ a3, float* __restrict__ kf, float* sl) {
;     ...
;         for (int i = 0; i < 8; ++i) { const int t = tid + NT * i; const float4* ar = (const float4*)(a3 + (size_t)t * 64);
;             float a0 = 0.f, a1 = 0.f, a2 = 0.f, a3v = 0.f;
; #pragma unroll 4
;             for (int jq = 0; jq < 16; ++jq) { const float4 av = ar[jq]; const float ae[4] = {av.x, av.y, av.z, av.w};
; #pragma unroll
;                 for (int e = 0; e < 4; ++e) { const float4 wv = *(const float4*)(sw + (jq * 4 + e) * 4); a0 += ae[e] * wv.x; a1 += ae[e] * wv.y; a2 += ae[e] * wv.z; a3v += ae[e] * wv.w; } }
;             const float dec = expf(-((float)t / (float)(SEQ - 1)) * delta);
;             hv[i][0] = a0 * dec; hv[i][1] = a1 * dec; hv[i][2] = a2 * dec; hv[i][3] = a3v * dec;
;             n0 += fabsf(hv[i][0]) + (t >= 1 ? fabsf(hv[i][1]) : 0.f); n1 += fabsf(hv[i][2]) + (t >= 1 ? fabsf(hv[i][3]) : 0.f); }
	v_pk_fma_f32 v[62:63], v[82:83], v[90:91], v[60:61] op_sel_hi:[0,1,1]
	v_pk_fma_f32 v[60:61], v[128:129], v[64:65], v[66:67] op_sel_hi:[0,1,1]
	v_pk_fma_f32 v[60:61], v[128:129], v[84:85], v[60:61] op_sel:[1,0,0]
	s_nop 0
	v_pk_fma_f32 v[60:61], v[130:131], v[88:89], v[60:61] op_sel_hi:[0,1,1]
	v_pk_fma_f32 v[60:61], v[82:83], v[92:93], v[60:61] op_sel_hi:[0,1,1]
	s_add_u32 s100, s78, 0x1e800000
	s_addc_u32 s101, s79, 0
	global_load_dword v116, v113, s[100:101]
	s_add_u32 s100, s100, 0x4000
	s_addc_u32 s101, s101, 0
	global_load_dword v117, v113, s[100:101]
	s_add_u32 s100, s100, 0x4000
	s_addc_u32 s101, s101, 0
	global_load_dword v118, v113, s[100:101]
	s_add_u32 s100, s100, 0x4000
	s_addc_u32 s101, s101, 0
	global_load_dword v119, v113, s[100:101]
	s_add_u32 s100, s100, 0x4000
	s_addc_u32 s101, s101, 0
	global_load_dword v120, v113, s[100:101]
	s_add_u32 s100, s100, 0x4000
	s_addc_u32 s101, s101, 0
	global_load_dword v121, v113, s[100:101]
	s_add_u32 s100, s100, 0x4000
	s_addc_u32 s101, s101, 0
	global_load_dword v122, v113, s[100:101]
	s_add_u32 s100, s100, 0x4000
	s_addc_u32 s101, s101, 0
	global_load_dword v123, v113, s[100:101]
	s_add_u32 s100, s100, 0x4000
	s_addc_u32 s101, s101, 0
	global_load_dword v124, v113, s[100:101]
	s_add_u32 s100, s100, 0x4000
	s_addc_u32 s101, s101, 0
	global_load_dword v125, v113, s[100:101]
	s_add_u32 s100, s100, 0x4000
	s_addc_u32 s101, s101, 0
	global_load_dword v126, v113, s[100:101]
	s_add_u32 s100, s100, 0x4000
	s_addc_u32 s101, s101, 0
	global_load_dword v127, v113, s[100:101]
	s_add_u32 s100, s100, 0x4000
	s_addc_u32 s101, s101, 0
	global_load_dword v128, v113, s[100:101]
	s_add_u32 s100, s100, 0x4000
	s_addc_u32 s101, s101, 0
	global_load_dword v129, v113, s[100:101]
	s_add_u32 s100, s100, 0x4000
	s_addc_u32 s101, s101, 0
	global_load_dword v130, v113, s[100:101]
	s_add_u32 s100, s100, 0x4000
	s_addc_u32 s101, s101, 0
	global_load_dword v131, v113, s[100:101]
	s_waitcnt vmcnt(48)
	v_mov_b32_e32 v106, 0x100
	ds_read_b128 v[90:93], v106
	ds_read_b128 v[94:97], v106 offset:16
	ds_read_b128 v[98:101], v106 offset:32
	ds_read_b128 v[102:105], v106 offset:48
	s_waitcnt lgkmcnt(3)
	v_pk_fma_f32 v[62:63], v[132:133], v[90:91], v[62:63] op_sel_hi:[0,1,1]
	v_pk_fma_f32 v[60:61], v[132:133], v[92:93], v[60:61] op_sel_hi:[0,1,1]
	s_waitcnt lgkmcnt(2)
	v_pk_fma_f32 v[62:63], v[132:133], v[94:95], v[62:63] op_sel:[1,0,0]
	v_pk_fma_f32 v[60:61], v[132:133], v[96:97], v[60:61] op_sel:[1,0,0]
	s_waitcnt lgkmcnt(1)
	v_pk_fma_f32 v[62:63], v[134:135], v[98:99], v[62:63] op_sel_hi:[0,1,1]
	v_mov_b32_e32 v90, v135
	v_pk_fma_f32 v[60:61], v[134:135], v[100:101], v[60:61] op_sel_hi:[0,1,1]
	s_waitcnt lgkmcnt(0)
	v_pk_fma_f32 v[94:95], v[90:91], v[102:103], v[62:63] op_sel_hi:[0,1,1]
	v_pk_fma_f32 v[98:99], v[90:91], v[104:105], v[60:61] op_sel_hi:[0,1,1]
	ds_read_b128 v[60:63], v106 offset:64
	ds_read_b128 v[64:67], v106 offset:80
	ds_read_b128 v[90:93], v106 offset:96
	s_waitcnt lgkmcnt(2)
	v_pk_fma_f32 v[60:61], v[136:137], v[60:61], v[94:95] op_sel_hi:[0,1,1]
	ds_read_b128 v[94:97], v106 offset:112
	s_waitcnt lgkmcnt(2)
	v_pk_fma_f32 v[60:61], v[136:137], v[64:65], v[60:61] op_sel:[1,0,0]
	v_mov_b32_e32 v64, v139
	s_waitcnt lgkmcnt(1)
	v_pk_fma_f32 v[60:61], v[138:139], v[90:91], v[60:61] op_sel_hi:[0,1,1]
	s_waitcnt lgkmcnt(0)
	v_pk_fma_f32 v[90:91], v[64:65], v[94:95], v[60:61] op_sel_hi:[0,1,1]
	v_pk_fma_f32 v[60:61], v[136:137], v[62:63], v[98:99] op_sel_hi:[0,1,1]
	v_pk_fma_f32 v[60:61], v[136:137], v[66:67], v[60:61] op_sel:[1,0,0]
	s_nop 0
	v_pk_fma_f32 v[60:61], v[138:139], v[92:93], v[60:61] op_sel_hi:[0,1,1]
	v_pk_fma_f32 v[94:95], v[64:65], v[96:97], v[60:61] op_sel_hi:[0,1,1]
	ds_read_b128 v[60:63], v106 offset:128
	ds_read_b128 v[64:67], v106 offset:144
	ds_read_b128 v[86:89], v106 offset:160
	s_waitcnt lgkmcnt(2)
	v_pk_fma_f32 v[60:61], v[140:141], v[60:61], v[90:91] op_sel_hi:[0,1,1]
	ds_read_b128 v[90:93], v106 offset:176
	v_pk_fma_f32 v[62:63], v[140:141], v[62:63], v[94:95] op_sel_hi:[0,1,1]
	s_waitcnt lgkmcnt(2)
	v_pk_fma_f32 v[60:61], v[140:141], v[64:65], v[60:61] op_sel:[1,0,0]
	v_pk_fma_f32 v[62:63], v[140:141], v[66:67], v[62:63] op_sel:[1,0,0]
	s_waitcnt lgkmcnt(1)
	v_pk_fma_f32 v[60:61], v[142:143], v[86:87], v[60:61] op_sel_hi:[0,1,1]
	v_mov_b32_e32 v64, v143
	v_pk_fma_f32 v[62:63], v[142:143], v[88:89], v[62:63] op_sel_hi:[0,1,1]
	s_waitcnt lgkmcnt(0)
	v_pk_fma_f32 v[60:61], v[64:65], v[90:91], v[60:61] op_sel_hi:[0,1,1]
	v_pk_fma_f32 v[66:67], v[64:65], v[92:93], v[62:63] op_sel_hi:[0,1,1]
	ds_read_b128 v[62:65], v106 offset:192
	ds_read_b128 v[82:85], v106 offset:208
	ds_read_b128 v[86:89], v106 offset:224
	ds_read_b128 v[90:93], v106 offset:240
	s_waitcnt lgkmcnt(3)
	v_pk_fma_f32 v[60:61], v[144:145], v[62:63], v[60:61] op_sel_hi:[0,1,1]
	s_waitcnt lgkmcnt(2)
	v_pk_fma_f32 v[60:61], v[144:145], v[82:83], v[60:61] op_sel:[1,0,0]
	v_mov_b32_e32 v82, v147
	s_waitcnt lgkmcnt(1)
	v_pk_fma_f32 v[60:61], v[146:147], v[86:87], v[60:61] op_sel_hi:[0,1,1]
	s_waitcnt lgkmcnt(0)
; __device__ void ph_filter_gen(const Params& P, int j, const float* __restrict__ a3, float* __restrict__ kf, float* sl) {
;     ...
;         for (int i = 0; i < 8; ++i) { const int t = tid + NT * i; const float4* ar = (const float4*)(a3 + (size_t)t * 64);
;             float a0 = 0.f, a1 = 0.f, a2 = 0.f, a3v = 0.f;
; #pragma unroll 4
;             for (int jq = 0; jq < 16; ++jq) { const float4 av = ar[jq]; const float ae[4] = {av.x, av.y, av.z, av.w};
; #pragma unroll
;                 for (int e = 0; e < 4; ++e) { const float4 wv = *(const float4*)(sw + (jq * 4 + e) * 4); a0 += ae[e] * wv.x; a1 += ae[e] * wv.y; a2 += ae[e] * wv.z; a3v += ae[e] * wv.w; } }
;             const float dec = expf(-((float)t / (float)(SEQ - 1)) * delta);
;             hv[i][0] = a0 * dec; hv[i][1] = a1 * dec; hv[i][2] = a2 * dec; hv[i][3] = a3v * dec;
;             n0 += fabsf(hv[i][0]) + (t >= 1 ? fabsf(hv[i][1]) : 0.f); n1 += fabsf(hv[i][2]) + (t >= 1 ? fabsf(hv[i][3]) : 0.f); }
	v_pk_fma_f32 v[62:63], v[82:83], v[90:91], v[60:61] op_sel_hi:[0,1,1]
	v_pk_fma_f32 v[60:61], v[144:145], v[64:65], v[66:67] op_sel_hi:[0,1,1]
	v_pk_fma_f32 v[60:61], v[144:145], v[84:85], v[60:61] op_sel:[1,0,0]
	s_nop 0
	v_pk_fma_f32 v[60:61], v[146:147], v[88:89], v[60:61] op_sel_hi:[0,1,1]
	v_pk_fma_f32 v[60:61], v[82:83], v[92:93], v[60:61] op_sel_hi:[0,1,1]
	s_add_u32 s100, s78, 0x1e840000
	s_addc_u32 s101, s79, 0
	global_load_dword v132, v113, s[100:101]
	s_add_u32 s100, s100, 0x4000
	s_addc_u32 s101, s101, 0
	global_load_dword v133, v113, s[100:101]
	s_add_u32 s100, s100, 0x4000
	s_addc_u32 s101, s101, 0
	global_load_dword v134, v113, s[100:101]
	s_add_u32 s100, s100, 0x4000
	s_addc_u32 s101, s101, 0
	global_load_dword v135, v113, s[100:101]
	s_add_u32 s100, s100, 0x4000
	s_addc_u32 s101, s101, 0
	global_load_dword v136, v113, s[100:101]
	s_add_u32 s100, s100, 0x4000
	s_addc_u32 s101, s101, 0
	global_load_dword v137, v113, s[100:101]
	s_add_u32 s100, s100, 0x4000
	s_addc_u32 s101, s101, 0
	global_load_dword v138, v113, s[100:101]
	s_add_u32 s100, s100, 0x4000
	s_addc_u32 s101, s101, 0
	global_load_dword v139, v113, s[100:101]
	s_add_u32 s100, s100, 0x4000
	s_addc_u32 s101, s101, 0
	global_load_dword v140, v113, s[100:101]
	s_add_u32 s100, s100, 0x4000
	s_addc_u32 s101, s101, 0
	global_load_dword v141, v113, s[100:101]
	s_add_u32 s100, s100, 0x4000
	s_addc_u32 s101, s101, 0
	global_load_dword v142, v113, s[100:101]
	s_add_u32 s100, s100, 0x4000
	s_addc_u32 s101, s101, 0
	global_load_dword v143, v113, s[100:101]
	s_add_u32 s100, s100, 0x4000
	s_addc_u32 s101, s101, 0
	global_load_dword v144, v113, s[100:101]
	s_add_u32 s100, s100, 0x4000
	s_addc_u32 s101, s101, 0
	global_load_dword v145, v113, s[100:101]
	s_add_u32 s100, s100, 0x4000
	s_addc_u32 s101, s101, 0
	global_load_dword v146, v113, s[100:101]
	s_add_u32 s100, s100, 0x4000
	s_addc_u32 s101, s101, 0
	global_load_dword v147, v113, s[100:101]
	s_waitcnt vmcnt(48)
	v_mov_b32_e32 v106, 0x200
	ds_read_b128 v[90:93], v106
	ds_read_b128 v[94:97], v106 offset:16
	ds_read_b128 v[98:101], v106 offset:32
	ds_read_b128 v[102:105], v106 offset:48
	s_waitcnt lgkmcnt(3)
	v_pk_fma_f32 v[62:63], v[148:149], v[90:91], v[62:63] op_sel_hi:[0,1,1]
	v_pk_fma_f32 v[60:61], v[148:149], v[92:93], v[60:61] op_sel_hi:[0,1,1]
	s_waitcnt lgkmcnt(2)
	v_pk_fma_f32 v[62:63], v[148:149], v[94:95], v[62:63] op_sel:[1,0,0]
	v_pk_fma_f32 v[60:61], v[148:149], v[96:97], v[60:61] op_sel:[1,0,0]
	s_waitcnt lgkmcnt(1)
	v_pk_fma_f32 v[62:63], v[150:151], v[98:99], v[62:63] op_sel_hi:[0,1,1]
	v_mov_b32_e32 v90, v151
	v_pk_fma_f32 v[60:61], v[150:151], v[100:101], v[60:61] op_sel_hi:[0,1,1]
	s_waitcnt lgkmcnt(0)
	v_pk_fma_f32 v[94:95], v[90:91], v[102:103], v[62:63] op_sel_hi:[0,1,1]
	v_pk_fma_f32 v[98:99], v[90:91], v[104:105], v[60:61] op_sel_hi:[0,1,1]
	ds_read_b128 v[60:63], v106 offset:64
	ds_read_b128 v[64:67], v106 offset:80
	ds_read_b128 v[90:93], v106 offset:96
	s_waitcnt lgkmcnt(2)
	v_pk_fma_f32 v[60:61], v[152:153], v[60:61], v[94:95] op_sel_hi:[0,1,1]
	ds_read_b128 v[94:97], v106 offset:112
	s_waitcnt lgkmcnt(2)
	v_pk_fma_f32 v[60:61], v[152:153], v[64:65], v[60:61] op_sel:[1,0,0]
	v_mov_b32_e32 v64, v155
	s_waitcnt lgkmcnt(1)
	v_pk_fma_f32 v[60:61], v[154:155], v[90:91], v[60:61] op_sel_hi:[0,1,1]
	s_waitcnt lgkmcnt(0)
	v_pk_fma_f32 v[90:91], v[64:65], v[94:95], v[60:61] op_sel_hi:[0,1,1]
	v_pk_fma_f32 v[60:61], v[152:153], v[62:63], v[98:99] op_sel_hi:[0,1,1]
	v_pk_fma_f32 v[60:61], v[152:153], v[66:67], v[60:61] op_sel:[1,0,0]
	s_nop 0
	v_pk_fma_f32 v[60:61], v[154:155], v[92:93], v[60:61] op_sel_hi:[0,1,1]
	v_pk_fma_f32 v[94:95], v[64:65], v[96:97], v[60:61] op_sel_hi:[0,1,1]
	ds_read_b128 v[60:63], v106 offset:128
	ds_read_b128 v[64:67], v106 offset:144
	ds_read_b128 v[86:89], v106 offset:160
	s_waitcnt lgkmcnt(2)
	v_pk_fma_f32 v[60:61], v[156:157], v[60:61], v[90:91] op_sel_hi:[0,1,1]
	ds_read_b128 v[90:93], v106 offset:176
	v_pk_fma_f32 v[62:63], v[156:157], v[62:63], v[94:95] op_sel_hi:[0,1,1]
	s_waitcnt lgkmcnt(2)
	v_pk_fma_f32 v[60:61], v[156:157], v[64:65], v[60:61] op_sel:[1,0,0]
	v_pk_fma_f32 v[62:63], v[156:157], v[66:67], v[62:63] op_sel:[1,0,0]
	s_waitcnt lgkmcnt(1)
	v_pk_fma_f32 v[60:61], v[158:159], v[86:87], v[60:61] op_sel_hi:[0,1,1]
	v_mov_b32_e32 v64, v159
	v_pk_fma_f32 v[62:63], v[158:159], v[88:89], v[62:63] op_sel_hi:[0,1,1]
	s_waitcnt lgkmcnt(0)
	v_pk_fma_f32 v[60:61], v[64:65], v[90:91], v[60:61] op_sel_hi:[0,1,1]
	v_pk_fma_f32 v[66:67], v[64:65], v[92:93], v[62:63] op_sel_hi:[0,1,1]
	ds_read_b128 v[62:65], v106 offset:192
	ds_read_b128 v[82:85], v106 offset:208
	ds_read_b128 v[86:89], v106 offset:224
	ds_read_b128 v[90:93], v106 offset:240
	s_waitcnt lgkmcnt(3)
	v_pk_fma_f32 v[60:61], v[160:161], v[62:63], v[60:61] op_sel_hi:[0,1,1]
	s_waitcnt lgkmcnt(2)
	v_pk_fma_f32 v[60:61], v[160:161], v[82:83], v[60:61] op_sel:[1,0,0]
	v_mov_b32_e32 v82, v163
	s_waitcnt lgkmcnt(1)
	v_pk_fma_f32 v[60:61], v[162:163], v[86:87], v[60:61] op_sel_hi:[0,1,1]
	s_waitcnt lgkmcnt(0)
; __device__ void ph_filter_gen(const Params& P, int j, const float* __restrict__ a3, float* __restrict__ kf, float* sl) {
;     ...
;         for (int i = 0; i < 8; ++i) { const int t = tid + NT * i; const float4* ar = (const float4*)(a3 + (size_t)t * 64);
;             float a0 = 0.f, a1 = 0.f, a2 = 0.f, a3v = 0.f;
; #pragma unroll 4
;             for (int jq = 0; jq < 16; ++jq) { const float4 av = ar[jq]; const float ae[4] = {av.x, av.y, av.z, av.w};
; #pragma unroll
;                 for (int e = 0; e < 4; ++e) { const float4 wv = *(const float4*)(sw + (jq * 4 + e) * 4); a0 += ae[e] * wv.x; a1 += ae[e] * wv.y; a2 += ae[e] * wv.z; a3v += ae[e] * wv.w; } }
;             const float dec = expf(-((float)t / (float)(SEQ - 1)) * delta);
;             hv[i][0] = a0 * dec; hv[i][1] = a1 * dec; hv[i][2] = a2 * dec; hv[i][3] = a3v * dec;
;             n0 += fabsf(hv[i][0]) + (t >= 1 ? fabsf(hv[i][1]) : 0.f); n1 += fabsf(hv[i][2]) + (t >= 1 ? fabsf(hv[i][3]) : 0.f); }
	v_pk_fma_f32 v[62:63], v[82:83], v[90:91], v[60:61] op_sel_hi:[0,1,1]
	v_pk_fma_f32 v[60:61], v[160:161], v[64:65], v[66:67] op_sel_hi:[0,1,1]
	v_pk_fma_f32 v[60:61], v[160:161], v[84:85], v[60:61] op_sel:[1,0,0]
	s_nop 0
	v_pk_fma_f32 v[60:61], v[162:163], v[88:89], v[60:61] op_sel_hi:[0,1,1]
	v_pk_fma_f32 v[60:61], v[82:83], v[92:93], v[60:61] op_sel_hi:[0,1,1]
	s_add_u32 s100, s78, 0x1e880000
	s_addc_u32 s101, s79, 0
	global_load_dword v148, v113, s[100:101]
	s_add_u32 s100, s100, 0x4000
	s_addc_u32 s101, s101, 0
	global_load_dword v149, v113, s[100:101]
	s_add_u32 s100, s100, 0x4000
	s_addc_u32 s101, s101, 0
	global_load_dword v150, v113, s[100:101]
	s_add_u32 s100, s100, 0x4000
	s_addc_u32 s101, s101, 0
	global_load_dword v151, v113, s[100:101]
	s_add_u32 s100, s100, 0x4000
	s_addc_u32 s101, s101, 0
	global_load_dword v152, v113, s[100:101]
	s_add_u32 s100, s100, 0x4000
	s_addc_u32 s101, s101, 0
	global_load_dword v153, v113, s[100:101]
	s_add_u32 s100, s100, 0x4000
	s_addc_u32 s101, s101, 0
	global_load_dword v154, v113, s[100:101]
	s_add_u32 s100, s100, 0x4000
	s_addc_u32 s101, s101, 0
	global_load_dword v155, v113, s[100:101]
	s_add_u32 s100, s100, 0x4000
	s_addc_u32 s101, s101, 0
	global_load_dword v156, v113, s[100:101]
	s_add_u32 s100, s100, 0x4000
	s_addc_u32 s101, s101, 0
	global_load_dword v157, v113, s[100:101]
	s_add_u32 s100, s100, 0x4000
	s_addc_u32 s101, s101, 0
	global_load_dword v158, v113, s[100:101]
	s_add_u32 s100, s100, 0x4000
	s_addc_u32 s101, s101, 0
	global_load_dword v159, v113, s[100:101]
	s_add_u32 s100, s100, 0x4000
	s_addc_u32 s101, s101, 0
	global_load_dword v160, v113, s[100:101]
	s_add_u32 s100, s100, 0x4000
	s_addc_u32 s101, s101, 0
	global_load_dword v161, v113, s[100:101]
	s_add_u32 s100, s100, 0x4000
	s_addc_u32 s101, s101, 0
	global_load_dword v162, v113, s[100:101]
	s_add_u32 s100, s100, 0x4000
	s_addc_u32 s101, s101, 0
	global_load_dword v163, v113, s[100:101]
	s_waitcnt vmcnt(48)
	v_mov_b32_e32 v106, 0x300
	ds_read_b128 v[90:93], v106
	ds_read_b128 v[94:97], v106 offset:16
	ds_read_b128 v[98:101], v106 offset:32
	ds_read_b128 v[102:105], v106 offset:48
	s_waitcnt lgkmcnt(3)
	v_pk_fma_f32 v[62:63], v[164:165], v[90:91], v[62:63] op_sel_hi:[0,1,1]
	v_pk_fma_f32 v[60:61], v[164:165], v[92:93], v[60:61] op_sel_hi:[0,1,1]
	s_waitcnt lgkmcnt(2)
	v_pk_fma_f32 v[62:63], v[164:165], v[94:95], v[62:63] op_sel:[1,0,0]
	v_pk_fma_f32 v[60:61], v[164:165], v[96:97], v[60:61] op_sel:[1,0,0]
	s_waitcnt lgkmcnt(1)
	v_pk_fma_f32 v[62:63], v[166:167], v[98:99], v[62:63] op_sel_hi:[0,1,1]
	v_mov_b32_e32 v90, v167
	v_pk_fma_f32 v[60:61], v[166:167], v[100:101], v[60:61] op_sel_hi:[0,1,1]
	s_waitcnt lgkmcnt(0)
	v_pk_fma_f32 v[94:95], v[90:91], v[102:103], v[62:63] op_sel_hi:[0,1,1]
	v_pk_fma_f32 v[98:99], v[90:91], v[104:105], v[60:61] op_sel_hi:[0,1,1]
	ds_read_b128 v[60:63], v106 offset:64
	ds_read_b128 v[64:67], v106 offset:80
	ds_read_b128 v[90:93], v106 offset:96
	s_waitcnt lgkmcnt(2)
	v_pk_fma_f32 v[60:61], v[168:169], v[60:61], v[94:95] op_sel_hi:[0,1,1]
	ds_read_b128 v[94:97], v106 offset:112
	s_waitcnt lgkmcnt(2)
	v_pk_fma_f32 v[60:61], v[168:169], v[64:65], v[60:61] op_sel:[1,0,0]
	v_mov_b32_e32 v64, v171
	s_waitcnt lgkmcnt(1)
	v_pk_fma_f32 v[60:61], v[170:171], v[90:91], v[60:61] op_sel_hi:[0,1,1]
	s_waitcnt lgkmcnt(0)
	v_pk_fma_f32 v[90:91], v[64:65], v[94:95], v[60:61] op_sel_hi:[0,1,1]
	v_pk_fma_f32 v[60:61], v[168:169], v[62:63], v[98:99] op_sel_hi:[0,1,1]
	v_pk_fma_f32 v[60:61], v[168:169], v[66:67], v[60:61] op_sel:[1,0,0]
	s_nop 0
	v_pk_fma_f32 v[60:61], v[170:171], v[92:93], v[60:61] op_sel_hi:[0,1,1]
	v_pk_fma_f32 v[94:95], v[64:65], v[96:97], v[60:61] op_sel_hi:[0,1,1]
	ds_read_b128 v[60:63], v106 offset:128
	ds_read_b128 v[64:67], v106 offset:144
	ds_read_b128 v[86:89], v106 offset:160
	s_waitcnt lgkmcnt(2)
	v_pk_fma_f32 v[60:61], v[172:173], v[60:61], v[90:91] op_sel_hi:[0,1,1]
	ds_read_b128 v[90:93], v106 offset:176
	v_pk_fma_f32 v[62:63], v[172:173], v[62:63], v[94:95] op_sel_hi:[0,1,1]
	s_waitcnt lgkmcnt(2)
	v_pk_fma_f32 v[60:61], v[172:173], v[64:65], v[60:61] op_sel:[1,0,0]
	v_pk_fma_f32 v[62:63], v[172:173], v[66:67], v[62:63] op_sel:[1,0,0]
	s_waitcnt lgkmcnt(1)
	v_pk_fma_f32 v[60:61], v[174:175], v[86:87], v[60:61] op_sel_hi:[0,1,1]
	v_mov_b32_e32 v64, v175
	v_pk_fma_f32 v[62:63], v[174:175], v[88:89], v[62:63] op_sel_hi:[0,1,1]
	s_waitcnt lgkmcnt(0)
	v_pk_fma_f32 v[60:61], v[64:65], v[90:91], v[60:61] op_sel_hi:[0,1,1]
	v_pk_fma_f32 v[66:67], v[64:65], v[92:93], v[62:63] op_sel_hi:[0,1,1]
	ds_read_b128 v[62:65], v106 offset:192
	ds_read_b128 v[82:85], v106 offset:208
	ds_read_b128 v[86:89], v106 offset:224
	ds_read_b128 v[90:93], v106 offset:240
	s_waitcnt lgkmcnt(3)
	v_pk_fma_f32 v[60:61], v[176:177], v[62:63], v[60:61] op_sel_hi:[0,1,1]
	s_waitcnt lgkmcnt(2)
	v_pk_fma_f32 v[60:61], v[176:177], v[82:83], v[60:61] op_sel:[1,0,0]
	v_mov_b32_e32 v82, v179
	s_waitcnt lgkmcnt(1)
	v_pk_fma_f32 v[60:61], v[178:179], v[86:87], v[60:61] op_sel_hi:[0,1,1]
	s_waitcnt lgkmcnt(0)
; __device__ void ph_filter_gen(const Params& P, int j, const float* __restrict__ a3, float* __restrict__ kf, float* sl) {
;     ...
;         for (int i = 0; i < 8; ++i) { const int t = tid + NT * i; const float4* ar = (const float4*)(a3 + (size_t)t * 64);
;             float a0 = 0.f, a1 = 0.f, a2 = 0.f, a3v = 0.f;
; #pragma unroll 4
;             for (int jq = 0; jq < 16; ++jq) { const float4 av = ar[jq]; const float ae[4] = {av.x, av.y, av.z, av.w};
; #pragma unroll
;                 for (int e = 0; e < 4; ++e) { const float4 wv = *(const float4*)(sw + (jq * 4 + e) * 4); a0 += ae[e] * wv.x; a1 += ae[e] * wv.y; a2 += ae[e] * wv.z; a3v += ae[e] * wv.w; } }
;             const float dec = expf(-((float)t / (float)(SEQ - 1)) * delta);
;             hv[i][0] = a0 * dec; hv[i][1] = a1 * dec; hv[i][2] = a2 * dec; hv[i][3] = a3v * dec;
;             n0 += fabsf(hv[i][0]) + (t >= 1 ? fabsf(hv[i][1]) : 0.f); n1 += fabsf(hv[i][2]) + (t >= 1 ? fabsf(hv[i][3]) : 0.f); }
	v_pk_fma_f32 v[62:63], v[82:83], v[90:91], v[60:61] op_sel_hi:[0,1,1]
	v_pk_fma_f32 v[60:61], v[176:177], v[64:65], v[66:67] op_sel_hi:[0,1,1]
	v_pk_fma_f32 v[60:61], v[176:177], v[84:85], v[60:61] op_sel:[1,0,0]
	s_nop 0
	v_pk_fma_f32 v[60:61], v[178:179], v[88:89], v[60:61] op_sel_hi:[0,1,1]
	v_pk_fma_f32 v[60:61], v[82:83], v[92:93], v[60:61] op_sel_hi:[0,1,1]
	s_add_u32 s100, s78, 0x1e8c0000
	s_addc_u32 s101, s79, 0
	global_load_dword v164, v113, s[100:101]
	s_add_u32 s100, s100, 0x4000
	s_addc_u32 s101, s101, 0
	global_load_dword v165, v113, s[100:101]
	s_add_u32 s100, s100, 0x4000
	s_addc_u32 s101, s101, 0
	global_load_dword v166, v113, s[100:101]
	s_add_u32 s100, s100, 0x4000
	s_addc_u32 s101, s101, 0
	global_load_dword v167, v113, s[100:101]
	s_add_u32 s100, s100, 0x4000
	s_addc_u32 s101, s101, 0
	global_load_dword v168, v113, s[100:101]
	s_add_u32 s100, s100, 0x4000
	s_addc_u32 s101, s101, 0
	global_load_dword v169, v113, s[100:101]
	s_add_u32 s100, s100, 0x4000
	s_addc_u32 s101, s101, 0
	global_load_dword v170, v113, s[100:101]
	s_add_u32 s100, s100, 0x4000
	s_addc_u32 s101, s101, 0
	global_load_dword v171, v113, s[100:101]
	s_add_u32 s100, s100, 0x4000
	s_addc_u32 s101, s101, 0
	global_load_dword v172, v113, s[100:101]
	s_add_u32 s100, s100, 0x4000
	s_addc_u32 s101, s101, 0
	global_load_dword v173, v113, s[100:101]
	s_add_u32 s100, s100, 0x4000
	s_addc_u32 s101, s101, 0
	global_load_dword v174, v113, s[100:101]
	s_add_u32 s100, s100, 0x4000
	s_addc_u32 s101, s101, 0
	global_load_dword v175, v113, s[100:101]
	s_add_u32 s100, s100, 0x4000
	s_addc_u32 s101, s101, 0
	global_load_dword v176, v113, s[100:101]
	s_add_u32 s100, s100, 0x4000
	s_addc_u32 s101, s101, 0
	global_load_dword v177, v113, s[100:101]
	s_add_u32 s100, s100, 0x4000
	s_addc_u32 s101, s101, 0
	global_load_dword v178, v113, s[100:101]
	s_add_u32 s100, s100, 0x4000
	s_addc_u32 s101, s101, 0
	global_load_dword v179, v113, s[100:101]
	v_mov_b32_e32 v64, 0
	s_mov_b32 s0, 0
	s_mov_b64 s[14:15], 0
	v_mov_b32_e32 v65, v64
	v_mov_b32_e32 v66, v64
	v_mov_b32_e32 v67, v64
.LBB0_235:
	s_waitcnt vmcnt(48)
	v_mov_b32_e32 v112, 0
	ds_read_b128 v[94:97], v112
	ds_read_b128 v[98:101], v112 offset:16
	ds_read_b128 v[102:105], v112 offset:32
	ds_read_b128 v[106:109], v112 offset:48
	s_waitcnt lgkmcnt(3)
	v_mov_b32_e32 v110, v94
	v_mov_b32_e32 v111, v96
	v_mov_b32_e32 v96, v95
	v_pk_fma_f32 v[66:67], v[116:117], v[110:111], v[66:67] op_sel_hi:[0,1,1]
	s_waitcnt lgkmcnt(2)
	v_mov_b32_e32 v110, v98
	v_mov_b32_e32 v111, v100
	v_pk_fma_f32 v[64:65], v[116:117], v[96:97], v[64:65] op_sel_hi:[0,1,1]
	v_mov_b32_e32 v100, v99
	v_pk_fma_f32 v[66:67], v[116:117], v[110:111], v[66:67] op_sel:[1,0,0]
	s_waitcnt lgkmcnt(1)
	v_mov_b32_e32 v110, v102
	v_mov_b32_e32 v111, v104
	v_pk_fma_f32 v[64:65], v[116:117], v[100:101], v[64:65] op_sel:[1,0,0]
	v_mov_b32_e32 v104, v103
	v_pk_fma_f32 v[66:67], v[118:119], v[110:111], v[66:67] op_sel_hi:[0,1,1]
	v_mov_b32_e32 v94, v119
	s_waitcnt lgkmcnt(0)
	v_mov_b32_e32 v110, v106
	v_mov_b32_e32 v111, v108
	v_pk_fma_f32 v[64:65], v[118:119], v[104:105], v[64:65] op_sel_hi:[0,1,1]
	v_mov_b32_e32 v108, v107
	v_pk_fma_f32 v[110:111], v[94:95], v[110:111], v[66:67] op_sel_hi:[0,1,1]
	v_pk_fma_f32 v[102:103], v[94:95], v[108:109], v[64:65] op_sel_hi:[0,1,1]
	ds_read_b128 v[64:67], v112 offset:64
	ds_read_b128 v[78:81], v112 offset:80
	ds_read_b128 v[94:97], v112 offset:96
	s_waitcnt lgkmcnt(2)
	v_mov_b32_e32 v98, v64
	v_mov_b32_e32 v99, v66
	v_pk_fma_f32 v[98:99], v[120:121], v[98:99], v[110:111] op_sel_hi:[0,1,1]
	s_waitcnt lgkmcnt(1)
	v_mov_b32_e32 v100, v78
	v_mov_b32_e32 v101, v80
	v_pk_fma_f32 v[98:99], v[120:121], v[100:101], v[98:99] op_sel:[1,0,0]
	s_waitcnt lgkmcnt(0)
	v_mov_b32_e32 v100, v94
	v_mov_b32_e32 v101, v96
	v_pk_fma_f32 v[104:105], v[122:123], v[100:101], v[98:99] op_sel_hi:[0,1,1]
	ds_read_b128 v[98:101], v112 offset:112
	v_mov_b32_e32 v66, v65
	v_pk_fma_f32 v[66:67], v[120:121], v[66:67], v[102:103] op_sel_hi:[0,1,1]
	v_mov_b32_e32 v80, v79
	v_pk_fma_f32 v[66:67], v[120:121], v[80:81], v[66:67] op_sel:[1,0,0]
	v_mov_b32_e32 v96, v95
	v_mov_b32_e32 v64, v123
	s_waitcnt lgkmcnt(0)
	v_mov_b32_e32 v106, v98
	v_mov_b32_e32 v107, v100
	v_pk_fma_f32 v[66:67], v[122:123], v[96:97], v[66:67] op_sel_hi:[0,1,1]
	v_mov_b32_e32 v100, v99
	v_pk_fma_f32 v[104:105], v[64:65], v[106:107], v[104:105] op_sel_hi:[0,1,1]
	v_pk_fma_f32 v[98:99], v[64:65], v[100:101], v[66:67] op_sel_hi:[0,1,1]
	ds_read_b128 v[64:67], v112 offset:128
	ds_read_b128 v[78:81], v112 offset:144
	ds_read_b128 v[90:93], v112 offset:160
	s_waitcnt lgkmcnt(2)
	v_mov_b32_e32 v94, v64
	v_mov_b32_e32 v95, v66
	v_pk_fma_f32 v[94:95], v[124:125], v[94:95], v[104:105] op_sel_hi:[0,1,1]
	s_waitcnt lgkmcnt(1)
	v_mov_b32_e32 v96, v78
	v_mov_b32_e32 v97, v80
	v_pk_fma_f32 v[94:95], v[124:125], v[96:97], v[94:95] op_sel:[1,0,0]
	s_waitcnt lgkmcnt(0)
	v_mov_b32_e32 v96, v90
	v_mov_b32_e32 v97, v92
	v_pk_fma_f32 v[100:101], v[126:127], v[96:97], v[94:95] op_sel_hi:[0,1,1]
	ds_read_b128 v[94:97], v112 offset:176
	v_mov_b32_e32 v66, v65
	v_pk_fma_f32 v[66:67], v[124:125], v[66:67], v[98:99] op_sel_hi:[0,1,1]
	v_mov_b32_e32 v80, v79
	v_pk_fma_f32 v[66:67], v[124:125], v[80:81], v[66:67] op_sel:[1,0,0]
	v_mov_b32_e32 v92, v91
	v_mov_b32_e32 v64, v127
	v_pk_fma_f32 v[66:67], v[126:127], v[92:93], v[66:67] op_sel_hi:[0,1,1]
	ds_read_b128 v[78:81], v112 offset:192
	ds_read_b128 v[86:89], v112 offset:208
	ds_read_b128 v[90:93], v112 offset:224
	s_waitcnt lgkmcnt(3)
	v_mov_b32_e32 v102, v94
	v_mov_b32_e32 v103, v96
	v_mov_b32_e32 v96, v95
	v_pk_fma_f32 v[100:101], v[64:65], v[102:103], v[100:101] op_sel_hi:[0,1,1]
	v_pk_fma_f32 v[64:65], v[64:65], v[96:97], v[66:67] op_sel_hi:[0,1,1]
	s_waitcnt lgkmcnt(2)
; __device__ void ph_filter_gen(const Params& P, int j, const float* __restrict__ a3, float* __restrict__ kf, float* sl) {
;     ...
;         for (int i = 0; i < 8; ++i) { const int t = tid + NT * i; const float4* ar = (const float4*)(a3 + (size_t)t * 64);
;             float a0 = 0.f, a1 = 0.f, a2 = 0.f, a3v = 0.f;
; #pragma unroll 4
;             for (int jq = 0; jq < 16; ++jq) { const float4 av = ar[jq]; const float ae[4] = {av.x, av.y, av.z, av.w};
; #pragma unroll
;                 for (int e = 0; e < 4; ++e) { const float4 wv = *(const float4*)(sw + (jq * 4 + e) * 4); a0 += ae[e] * wv.x; a1 += ae[e] * wv.y; a2 += ae[e] * wv.z; a3v += ae[e] * wv.w; } }
;             const float dec = expf(-((float)t / (float)(SEQ - 1)) * delta);
;             hv[i][0] = a0 * dec; hv[i][1] = a1 * dec; hv[i][2] = a2 * dec; hv[i][3] = a3v * dec;
;             n0 += fabsf(hv[i][0]) + (t >= 1 ? fabsf(hv[i][1]) : 0.f); n1 += fabsf(hv[i][2]) + (t >= 1 ? fabsf(hv[i][3]) : 0.f); }
	v_mov_b32_e32 v66, v78
	v_mov_b32_e32 v67, v80
	v_pk_fma_f32 v[66:67], v[128:129], v[66:67], v[100:101] op_sel_hi:[0,1,1]
	s_waitcnt lgkmcnt(1)
	v_mov_b32_e32 v94, v86
	v_mov_b32_e32 v95, v88
	v_pk_fma_f32 v[66:67], v[128:129], v[94:95], v[66:67] op_sel:[1,0,0]
	s_waitcnt lgkmcnt(0)
	v_mov_b32_e32 v94, v90
	v_mov_b32_e32 v95, v92
	v_pk_fma_f32 v[66:67], v[130:131], v[94:95], v[66:67] op_sel_hi:[0,1,1]
	ds_read_b128 v[94:97], v112 offset:240
	v_mov_b32_e32 v80, v79
	v_pk_fma_f32 v[64:65], v[128:129], v[80:81], v[64:65] op_sel_hi:[0,1,1]
	v_mov_b32_e32 v88, v87
	v_pk_fma_f32 v[64:65], v[128:129], v[88:89], v[64:65] op_sel:[1,0,0]
	v_mov_b32_e32 v92, v91
	v_mov_b32_e32 v78, v131
	s_waitcnt lgkmcnt(0)
	v_mov_b32_e32 v98, v94
	v_mov_b32_e32 v99, v96
	v_pk_fma_f32 v[64:65], v[130:131], v[92:93], v[64:65] op_sel_hi:[0,1,1]
	v_mov_b32_e32 v96, v95
	v_pk_fma_f32 v[66:67], v[78:79], v[98:99], v[66:67] op_sel_hi:[0,1,1]
	v_pk_fma_f32 v[64:65], v[78:79], v[96:97], v[64:65] op_sel_hi:[0,1,1]
	s_waitcnt vmcnt(32)
	v_mov_b32_e32 v112, 0x100
	ds_read_b128 v[94:97], v112
	ds_read_b128 v[98:101], v112 offset:16
	ds_read_b128 v[102:105], v112 offset:32
	ds_read_b128 v[106:109], v112 offset:48
	s_waitcnt lgkmcnt(3)
	v_mov_b32_e32 v110, v94
	v_mov_b32_e32 v111, v96
	v_mov_b32_e32 v96, v95
	v_pk_fma_f32 v[66:67], v[132:133], v[110:111], v[66:67] op_sel_hi:[0,1,1]
	s_waitcnt lgkmcnt(2)
	v_mov_b32_e32 v110, v98
	v_mov_b32_e32 v111, v100
	v_pk_fma_f32 v[64:65], v[132:133], v[96:97], v[64:65] op_sel_hi:[0,1,1]
	v_mov_b32_e32 v100, v99
	v_pk_fma_f32 v[66:67], v[132:133], v[110:111], v[66:67] op_sel:[1,0,0]
	s_waitcnt lgkmcnt(1)
	v_mov_b32_e32 v110, v102
	v_mov_b32_e32 v111, v104
	v_pk_fma_f32 v[64:65], v[132:133], v[100:101], v[64:65] op_sel:[1,0,0]
	v_mov_b32_e32 v104, v103
	v_pk_fma_f32 v[66:67], v[134:135], v[110:111], v[66:67] op_sel_hi:[0,1,1]
	v_mov_b32_e32 v94, v135
	s_waitcnt lgkmcnt(0)
	v_mov_b32_e32 v110, v106
	v_mov_b32_e32 v111, v108
	v_pk_fma_f32 v[64:65], v[134:135], v[104:105], v[64:65] op_sel_hi:[0,1,1]
	v_mov_b32_e32 v108, v107
	v_pk_fma_f32 v[110:111], v[94:95], v[110:111], v[66:67] op_sel_hi:[0,1,1]
	v_pk_fma_f32 v[102:103], v[94:95], v[108:109], v[64:65] op_sel_hi:[0,1,1]
	ds_read_b128 v[64:67], v112 offset:64
	ds_read_b128 v[78:81], v112 offset:80
	ds_read_b128 v[94:97], v112 offset:96
	s_waitcnt lgkmcnt(2)
	v_mov_b32_e32 v98, v64
	v_mov_b32_e32 v99, v66
	v_pk_fma_f32 v[98:99], v[136:137], v[98:99], v[110:111] op_sel_hi:[0,1,1]
	s_waitcnt lgkmcnt(1)
	v_mov_b32_e32 v100, v78
	v_mov_b32_e32 v101, v80
	v_pk_fma_f32 v[98:99], v[136:137], v[100:101], v[98:99] op_sel:[1,0,0]
	s_waitcnt lgkmcnt(0)
	v_mov_b32_e32 v100, v94
	v_mov_b32_e32 v101, v96
	v_pk_fma_f32 v[104:105], v[138:139], v[100:101], v[98:99] op_sel_hi:[0,1,1]
	ds_read_b128 v[98:101], v112 offset:112
	v_mov_b32_e32 v66, v65
	v_pk_fma_f32 v[66:67], v[136:137], v[66:67], v[102:103] op_sel_hi:[0,1,1]
	v_mov_b32_e32 v80, v79
	v_pk_fma_f32 v[66:67], v[136:137], v[80:81], v[66:67] op_sel:[1,0,0]
	v_mov_b32_e32 v96, v95
	v_mov_b32_e32 v64, v139
	s_waitcnt lgkmcnt(0)
	v_mov_b32_e32 v106, v98
	v_mov_b32_e32 v107, v100
	v_pk_fma_f32 v[66:67], v[138:139], v[96:97], v[66:67] op_sel_hi:[0,1,1]
	v_mov_b32_e32 v100, v99
	v_pk_fma_f32 v[104:105], v[64:65], v[106:107], v[104:105] op_sel_hi:[0,1,1]
	v_pk_fma_f32 v[98:99], v[64:65], v[100:101], v[66:67] op_sel_hi:[0,1,1]
	ds_read_b128 v[64:67], v112 offset:128
	ds_read_b128 v[78:81], v112 offset:144
	ds_read_b128 v[90:93], v112 offset:160
	s_waitcnt lgkmcnt(2)
	v_mov_b32_e32 v94, v64
	v_mov_b32_e32 v95, v66
	v_pk_fma_f32 v[94:95], v[140:141], v[94:95], v[104:105] op_sel_hi:[0,1,1]
	s_waitcnt lgkmcnt(1)
	v_mov_b32_e32 v96, v78
	v_mov_b32_e32 v97, v80
	v_pk_fma_f32 v[94:95], v[140:141], v[96:97], v[94:95] op_sel:[1,0,0]
	s_waitcnt lgkmcnt(0)
	v_mov_b32_e32 v96, v90
	v_mov_b32_e32 v97, v92
	v_pk_fma_f32 v[100:101], v[142:143], v[96:97], v[94:95] op_sel_hi:[0,1,1]
	ds_read_b128 v[94:97], v112 offset:176
	v_mov_b32_e32 v66, v65
	v_pk_fma_f32 v[66:67], v[140:141], v[66:67], v[98:99] op_sel_hi:[0,1,1]
	v_mov_b32_e32 v80, v79
	v_pk_fma_f32 v[66:67], v[140:141], v[80:81], v[66:67] op_sel:[1,0,0]
	v_mov_b32_e32 v92, v91
	v_mov_b32_e32 v64, v143
	v_pk_fma_f32 v[66:67], v[142:143], v[92:93], v[66:67] op_sel_hi:[0,1,1]
	ds_read_b128 v[78:81], v112 offset:192
	ds_read_b128 v[86:89], v112 offset:208
	ds_read_b128 v[90:93], v112 offset:224
	s_waitcnt lgkmcnt(3)
	v_mov_b32_e32 v102, v94
	v_mov_b32_e32 v103, v96
	v_mov_b32_e32 v96, v95
	v_pk_fma_f32 v[100:101], v[64:65], v[102:103], v[100:101] op_sel_hi:[0,1,1]
	v_pk_fma_f32 v[64:65], v[64:65], v[96:97], v[66:67] op_sel_hi:[0,1,1]
	s_waitcnt lgkmcnt(2)
	v_mov_b32_e32 v66, v78
	v_mov_b32_e32 v67, v80
	v_pk_fma_f32 v[66:67], v[144:145], v[66:67], v[100:101] op_sel_hi:[0,1,1]
	s_waitcnt lgkmcnt(1)
	v_mov_b32_e32 v94, v86
	v_mov_b32_e32 v95, v88
	v_pk_fma_f32 v[66:67], v[144:145], v[94:95], v[66:67] op_sel:[1,0,0]
	s_waitcnt lgkmcnt(0)
	v_mov_b32_e32 v94, v90
	v_mov_b32_e32 v95, v92
	v_pk_fma_f32 v[66:67], v[146:147], v[94:95], v[66:67] op_sel_hi:[0,1,1]
	ds_read_b128 v[94:97], v112 offset:240
	v_mov_b32_e32 v80, v79
	v_pk_fma_f32 v[64:65], v[144:145], v[80:81], v[64:65] op_sel_hi:[0,1,1]
	v_mov_b32_e32 v88, v87
	v_pk_fma_f32 v[64:65], v[144:145], v[88:89], v[64:65] op_sel:[1,0,0]
	v_mov_b32_e32 v92, v91
	v_mov_b32_e32 v78, v147
	s_waitcnt lgkmcnt(0)
	v_mov_b32_e32 v98, v94
	v_mov_b32_e32 v99, v96
	v_pk_fma_f32 v[64:65], v[146:147], v[92:93], v[64:65] op_sel_hi:[0,1,1]
	v_mov_b32_e32 v96, v95
	v_pk_fma_f32 v[66:67], v[78:79], v[98:99], v[66:67] op_sel_hi:[0,1,1]
	v_pk_fma_f32 v[64:65], v[78:79], v[96:97], v[64:65] op_sel_hi:[0,1,1]
	s_waitcnt vmcnt(16)
; __device__ void ph_filter_gen(const Params& P, int j, const float* __restrict__ a3, float* __restrict__ kf, float* sl) {
;     ...
;         for (int i = 0; i < 8; ++i) { const int t = tid + NT * i; const float4* ar = (const float4*)(a3 + (size_t)t * 64);
;             float a0 = 0.f, a1 = 0.f, a2 = 0.f, a3v = 0.f;
; #pragma unroll 4
;             for (int jq = 0; jq < 16; ++jq) { const float4 av = ar[jq]; const float ae[4] = {av.x, av.y, av.z, av.w};
; #pragma unroll
;                 for (int e = 0; e < 4; ++e) { const float4 wv = *(const float4*)(sw + (jq * 4 + e) * 4); a0 += ae[e] * wv.x; a1 += ae[e] * wv.y; a2 += ae[e] * wv.z; a3v += ae[e] * wv.w; } }
;             const float dec = expf(-((float)t / (float)(SEQ - 1)) * delta);
;             hv[i][0] = a0 * dec; hv[i][1] = a1 * dec; hv[i][2] = a2 * dec; hv[i][3] = a3v * dec;
;             n0 += fabsf(hv[i][0]) + (t >= 1 ? fabsf(hv[i][1]) : 0.f); n1 += fabsf(hv[i][2]) + (t >= 1 ? fabsf(hv[i][3]) : 0.f); }
	v_mov_b32_e32 v112, 0x200
	ds_read_b128 v[94:97], v112
	ds_read_b128 v[98:101], v112 offset:16
	ds_read_b128 v[102:105], v112 offset:32
	ds_read_b128 v[106:109], v112 offset:48
	s_waitcnt lgkmcnt(3)
	v_mov_b32_e32 v110, v94
	v_mov_b32_e32 v111, v96
	v_mov_b32_e32 v96, v95
	v_pk_fma_f32 v[66:67], v[148:149], v[110:111], v[66:67] op_sel_hi:[0,1,1]
	s_waitcnt lgkmcnt(2)
	v_mov_b32_e32 v110, v98
	v_mov_b32_e32 v111, v100
	v_pk_fma_f32 v[64:65], v[148:149], v[96:97], v[64:65] op_sel_hi:[0,1,1]
	v_mov_b32_e32 v100, v99
	v_pk_fma_f32 v[66:67], v[148:149], v[110:111], v[66:67] op_sel:[1,0,0]
	s_waitcnt lgkmcnt(1)
	v_mov_b32_e32 v110, v102
	v_mov_b32_e32 v111, v104
	v_pk_fma_f32 v[64:65], v[148:149], v[100:101], v[64:65] op_sel:[1,0,0]
	v_mov_b32_e32 v104, v103
	v_pk_fma_f32 v[66:67], v[150:151], v[110:111], v[66:67] op_sel_hi:[0,1,1]
	v_mov_b32_e32 v94, v151
	s_waitcnt lgkmcnt(0)
	v_mov_b32_e32 v110, v106
	v_mov_b32_e32 v111, v108
	v_pk_fma_f32 v[64:65], v[150:151], v[104:105], v[64:65] op_sel_hi:[0,1,1]
	v_mov_b32_e32 v108, v107
	v_pk_fma_f32 v[110:111], v[94:95], v[110:111], v[66:67] op_sel_hi:[0,1,1]
	v_pk_fma_f32 v[102:103], v[94:95], v[108:109], v[64:65] op_sel_hi:[0,1,1]
	ds_read_b128 v[64:67], v112 offset:64
	ds_read_b128 v[78:81], v112 offset:80
	ds_read_b128 v[94:97], v112 offset:96
	s_waitcnt lgkmcnt(2)
	v_mov_b32_e32 v98, v64
	v_mov_b32_e32 v99, v66
	v_pk_fma_f32 v[98:99], v[152:153], v[98:99], v[110:111] op_sel_hi:[0,1,1]
	s_waitcnt lgkmcnt(1)
	v_mov_b32_e32 v100, v78
	v_mov_b32_e32 v101, v80
	v_pk_fma_f32 v[98:99], v[152:153], v[100:101], v[98:99] op_sel:[1,0,0]
	s_waitcnt lgkmcnt(0)
	v_mov_b32_e32 v100, v94
	v_mov_b32_e32 v101, v96
	v_pk_fma_f32 v[104:105], v[154:155], v[100:101], v[98:99] op_sel_hi:[0,1,1]
	ds_read_b128 v[98:101], v112 offset:112
	v_mov_b32_e32 v66, v65
	v_pk_fma_f32 v[66:67], v[152:153], v[66:67], v[102:103] op_sel_hi:[0,1,1]
	v_mov_b32_e32 v80, v79
	v_pk_fma_f32 v[66:67], v[152:153], v[80:81], v[66:67] op_sel:[1,0,0]
	v_mov_b32_e32 v96, v95
	v_mov_b32_e32 v64, v155
	s_waitcnt lgkmcnt(0)
	v_mov_b32_e32 v106, v98
	v_mov_b32_e32 v107, v100
	v_pk_fma_f32 v[66:67], v[154:155], v[96:97], v[66:67] op_sel_hi:[0,1,1]
	v_mov_b32_e32 v100, v99
	v_pk_fma_f32 v[104:105], v[64:65], v[106:107], v[104:105] op_sel_hi:[0,1,1]
	v_pk_fma_f32 v[98:99], v[64:65], v[100:101], v[66:67] op_sel_hi:[0,1,1]
	ds_read_b128 v[64:67], v112 offset:128
	ds_read_b128 v[78:81], v112 offset:144
	ds_read_b128 v[90:93], v112 offset:160
	s_waitcnt lgkmcnt(2)
	v_mov_b32_e32 v94, v64
	v_mov_b32_e32 v95, v66
	v_pk_fma_f32 v[94:95], v[156:157], v[94:95], v[104:105] op_sel_hi:[0,1,1]
	s_waitcnt lgkmcnt(1)
	v_mov_b32_e32 v96, v78
	v_mov_b32_e32 v97, v80
	v_pk_fma_f32 v[94:95], v[156:157], v[96:97], v[94:95] op_sel:[1,0,0]
	s_waitcnt lgkmcnt(0)
	v_mov_b32_e32 v96, v90
	v_mov_b32_e32 v97, v92
	v_pk_fma_f32 v[100:101], v[158:159], v[96:97], v[94:95] op_sel_hi:[0,1,1]
	ds_read_b128 v[94:97], v112 offset:176
	v_mov_b32_e32 v66, v65
	v_pk_fma_f32 v[66:67], v[156:157], v[66:67], v[98:99] op_sel_hi:[0,1,1]
	v_mov_b32_e32 v80, v79
	v_pk_fma_f32 v[66:67], v[156:157], v[80:81], v[66:67] op_sel:[1,0,0]
	v_mov_b32_e32 v92, v91
	v_mov_b32_e32 v64, v159
	v_pk_fma_f32 v[66:67], v[158:159], v[92:93], v[66:67] op_sel_hi:[0,1,1]
	ds_read_b128 v[78:81], v112 offset:192
	ds_read_b128 v[86:89], v112 offset:208
	ds_read_b128 v[90:93], v112 offset:224
	s_waitcnt lgkmcnt(3)
	v_mov_b32_e32 v102, v94
	v_mov_b32_e32 v103, v96
	v_mov_b32_e32 v96, v95
	v_pk_fma_f32 v[100:101], v[64:65], v[102:103], v[100:101] op_sel_hi:[0,1,1]
	v_pk_fma_f32 v[64:65], v[64:65], v[96:97], v[66:67] op_sel_hi:[0,1,1]
	s_waitcnt lgkmcnt(2)
	v_mov_b32_e32 v66, v78
	v_mov_b32_e32 v67, v80
	v_pk_fma_f32 v[66:67], v[160:161], v[66:67], v[100:101] op_sel_hi:[0,1,1]
	s_waitcnt lgkmcnt(1)
	v_mov_b32_e32 v94, v86
	v_mov_b32_e32 v95, v88
	v_pk_fma_f32 v[66:67], v[160:161], v[94:95], v[66:67] op_sel:[1,0,0]
	s_waitcnt lgkmcnt(0)
	v_mov_b32_e32 v94, v90
	v_mov_b32_e32 v95, v92
	v_pk_fma_f32 v[66:67], v[162:163], v[94:95], v[66:67] op_sel_hi:[0,1,1]
	ds_read_b128 v[94:97], v112 offset:240
	v_mov_b32_e32 v80, v79
	v_pk_fma_f32 v[64:65], v[160:161], v[80:81], v[64:65] op_sel_hi:[0,1,1]
	v_mov_b32_e32 v88, v87
	v_pk_fma_f32 v[64:65], v[160:161], v[88:89], v[64:65] op_sel:[1,0,0]
	v_mov_b32_e32 v92, v91
	v_mov_b32_e32 v78, v163
	s_waitcnt lgkmcnt(0)
	v_mov_b32_e32 v98, v94
	v_mov_b32_e32 v99, v96
	v_pk_fma_f32 v[64:65], v[162:163], v[92:93], v[64:65] op_sel_hi:[0,1,1]
	v_mov_b32_e32 v96, v95
	v_pk_fma_f32 v[66:67], v[78:79], v[98:99], v[66:67] op_sel_hi:[0,1,1]
	v_pk_fma_f32 v[64:65], v[78:79], v[96:97], v[64:65] op_sel_hi:[0,1,1]
	s_waitcnt vmcnt(0)
	v_mov_b32_e32 v112, 0x300
	ds_read_b128 v[94:97], v112
	ds_read_b128 v[98:101], v112 offset:16
	ds_read_b128 v[102:105], v112 offset:32
	ds_read_b128 v[106:109], v112 offset:48
	s_waitcnt lgkmcnt(3)
	v_mov_b32_e32 v110, v94
	v_mov_b32_e32 v111, v96
	v_mov_b32_e32 v96, v95
	v_pk_fma_f32 v[66:67], v[164:165], v[110:111], v[66:67] op_sel_hi:[0,1,1]
	s_waitcnt lgkmcnt(2)
	v_mov_b32_e32 v110, v98
	v_mov_b32_e32 v111, v100
	v_pk_fma_f32 v[64:65], v[164:165], v[96:97], v[64:65] op_sel_hi:[0,1,1]
	v_mov_b32_e32 v100, v99
	v_pk_fma_f32 v[66:67], v[164:165], v[110:111], v[66:67] op_sel:[1,0,0]
	s_waitcnt lgkmcnt(1)
	v_mov_b32_e32 v110, v102
	v_mov_b32_e32 v111, v104
	v_pk_fma_f32 v[64:65], v[164:165], v[100:101], v[64:65] op_sel:[1,0,0]
	v_mov_b32_e32 v104, v103
	v_pk_fma_f32 v[66:67], v[166:167], v[110:111], v[66:67] op_sel_hi:[0,1,1]
	v_mov_b32_e32 v94, v167
	s_waitcnt lgkmcnt(0)
; __device__ void ph_filter_gen(const Params& P, int j, const float* __restrict__ a3, float* __restrict__ kf, float* sl) {
;     ...
;             for (int jq = 0; jq < 16; ++jq) { const float4 av = ar[jq]; const float ae[4] = {av.x, av.y, av.z, av.w};
; #pragma unroll
;                 for (int e = 0; e < 4; ++e) { const float4 wv = *(const float4*)(sw + (jq * 4 + e) * 4); a0 += ae[e] * wv.x; a1 += ae[e] * wv.y; a2 += ae[e] * wv.z; a3v += ae[e] * wv.w; } }
;             const float dec = expf(-((float)t / (float)(SEQ - 1)) * delta);
;             hv[i][0] = a0 * dec; hv[i][1] = a1 * dec; hv[i][2] = a2 * dec; hv[i][3] = a3v * dec;
;             n0 += fabsf(hv[i][0]) + (t >= 1 ? fabsf(hv[i][1]) : 0.f); n1 += fabsf(hv[i][2]) + (t >= 1 ? fabsf(hv[i][3]) : 0.f); }
	v_mov_b32_e32 v110, v106
	v_mov_b32_e32 v111, v108
	v_pk_fma_f32 v[64:65], v[166:167], v[104:105], v[64:65] op_sel_hi:[0,1,1]
	v_mov_b32_e32 v108, v107
	v_pk_fma_f32 v[110:111], v[94:95], v[110:111], v[66:67] op_sel_hi:[0,1,1]
	v_pk_fma_f32 v[102:103], v[94:95], v[108:109], v[64:65] op_sel_hi:[0,1,1]
	ds_read_b128 v[64:67], v112 offset:64
	ds_read_b128 v[78:81], v112 offset:80
	ds_read_b128 v[94:97], v112 offset:96
	s_waitcnt lgkmcnt(2)
	v_mov_b32_e32 v98, v64
	v_mov_b32_e32 v99, v66
	v_pk_fma_f32 v[98:99], v[168:169], v[98:99], v[110:111] op_sel_hi:[0,1,1]
	s_waitcnt lgkmcnt(1)
	v_mov_b32_e32 v100, v78
	v_mov_b32_e32 v101, v80
	v_pk_fma_f32 v[98:99], v[168:169], v[100:101], v[98:99] op_sel:[1,0,0]
	s_waitcnt lgkmcnt(0)
	v_mov_b32_e32 v100, v94
	v_mov_b32_e32 v101, v96
	v_pk_fma_f32 v[104:105], v[170:171], v[100:101], v[98:99] op_sel_hi:[0,1,1]
	ds_read_b128 v[98:101], v112 offset:112
	v_mov_b32_e32 v66, v65
	v_pk_fma_f32 v[66:67], v[168:169], v[66:67], v[102:103] op_sel_hi:[0,1,1]
	v_mov_b32_e32 v80, v79
	v_pk_fma_f32 v[66:67], v[168:169], v[80:81], v[66:67] op_sel:[1,0,0]
	v_mov_b32_e32 v96, v95
	v_mov_b32_e32 v64, v171
	s_waitcnt lgkmcnt(0)
	v_mov_b32_e32 v106, v98
	v_mov_b32_e32 v107, v100
	v_pk_fma_f32 v[66:67], v[170:171], v[96:97], v[66:67] op_sel_hi:[0,1,1]
	v_mov_b32_e32 v100, v99
	v_pk_fma_f32 v[104:105], v[64:65], v[106:107], v[104:105] op_sel_hi:[0,1,1]
	v_pk_fma_f32 v[98:99], v[64:65], v[100:101], v[66:67] op_sel_hi:[0,1,1]
	ds_read_b128 v[64:67], v112 offset:128
	ds_read_b128 v[78:81], v112 offset:144
	ds_read_b128 v[90:93], v112 offset:160
	s_waitcnt lgkmcnt(2)
	v_mov_b32_e32 v94, v64
	v_mov_b32_e32 v95, v66
	v_pk_fma_f32 v[94:95], v[172:173], v[94:95], v[104:105] op_sel_hi:[0,1,1]
	s_waitcnt lgkmcnt(1)
	v_mov_b32_e32 v96, v78
	v_mov_b32_e32 v97, v80
	v_pk_fma_f32 v[94:95], v[172:173], v[96:97], v[94:95] op_sel:[1,0,0]
	s_waitcnt lgkmcnt(0)
	v_mov_b32_e32 v96, v90
	v_mov_b32_e32 v97, v92
	v_pk_fma_f32 v[100:101], v[174:175], v[96:97], v[94:95] op_sel_hi:[0,1,1]
	ds_read_b128 v[94:97], v112 offset:176
	v_mov_b32_e32 v66, v65
	v_pk_fma_f32 v[66:67], v[172:173], v[66:67], v[98:99] op_sel_hi:[0,1,1]
	v_mov_b32_e32 v80, v79
	v_pk_fma_f32 v[66:67], v[172:173], v[80:81], v[66:67] op_sel:[1,0,0]
	v_mov_b32_e32 v92, v91
	v_mov_b32_e32 v64, v175
	v_pk_fma_f32 v[66:67], v[174:175], v[92:93], v[66:67] op_sel_hi:[0,1,1]
	ds_read_b128 v[78:81], v112 offset:192
	ds_read_b128 v[86:89], v112 offset:208
	ds_read_b128 v[90:93], v112 offset:224
	s_waitcnt lgkmcnt(3)
	v_mov_b32_e32 v102, v94
	v_mov_b32_e32 v103, v96
	v_mov_b32_e32 v96, v95
	v_pk_fma_f32 v[100:101], v[64:65], v[102:103], v[100:101] op_sel_hi:[0,1,1]
	v_pk_fma_f32 v[64:65], v[64:65], v[96:97], v[66:67] op_sel_hi:[0,1,1]
	s_waitcnt lgkmcnt(2)
	v_mov_b32_e32 v66, v78
	v_mov_b32_e32 v67, v80
	v_pk_fma_f32 v[66:67], v[176:177], v[66:67], v[100:101] op_sel_hi:[0,1,1]
	s_waitcnt lgkmcnt(1)
	v_mov_b32_e32 v94, v86
	v_mov_b32_e32 v95, v88
	v_pk_fma_f32 v[66:67], v[176:177], v[94:95], v[66:67] op_sel:[1,0,0]
	s_waitcnt lgkmcnt(0)
	v_mov_b32_e32 v94, v90
	v_mov_b32_e32 v95, v92
	v_pk_fma_f32 v[66:67], v[178:179], v[94:95], v[66:67] op_sel_hi:[0,1,1]
	ds_read_b128 v[94:97], v112 offset:240
	v_mov_b32_e32 v80, v79
	v_pk_fma_f32 v[64:65], v[176:177], v[80:81], v[64:65] op_sel_hi:[0,1,1]
	v_mov_b32_e32 v88, v87
	v_pk_fma_f32 v[64:65], v[176:177], v[88:89], v[64:65] op_sel:[1,0,0]
	v_mov_b32_e32 v92, v91
	v_mov_b32_e32 v78, v179
	s_waitcnt lgkmcnt(0)
	v_mov_b32_e32 v98, v94
	v_mov_b32_e32 v99, v96
	v_pk_fma_f32 v[64:65], v[178:179], v[92:93], v[64:65] op_sel_hi:[0,1,1]
	v_mov_b32_e32 v96, v95
	v_pk_fma_f32 v[66:67], v[78:79], v[98:99], v[66:67] op_sel_hi:[0,1,1]
	v_pk_fma_f32 v[64:65], v[78:79], v[96:97], v[64:65] op_sel_hi:[0,1,1]
	v_cvt_f32_i32_e32 v78, s38
	v_mov_b32_e32 v79, 0xc0447cbd
	s_mov_b32 s0, 0xc2ce8ed0
	s_mov_b32 s1, 0x42b17218
	v_fmamk_f32 v91, v78, 0xbc44ade8, v79
	v_mul_f32_e64 v78, v69, |v91|
	v_mul_f32_e32 v79, 0x3fb8aa3b, v78
	v_fma_f32 v80, v78, s92, -v79
	v_rndne_f32_e32 v81, v79
	v_fmac_f32_e32 v80, 0x32a5705f, v78
	v_sub_f32_e32 v79, v79, v81
	v_add_f32_e32 v79, v79, v80
	v_cvt_i32_f32_e32 v81, v81
	v_exp_f32_e32 v79, v79
	v_cmp_ngt_f32_e32 vcc, s0, v78
	v_mul_f32_e64 v80, v70, |v91|
	v_ldexp_f32 v79, v79, v81
	v_cndmask_b32_e32 v79, 0, v79, vcc
	v_cmp_nlt_f32_e32 vcc, s1, v78
	s_nop 1
	v_cndmask_b32_e32 v82, v244, v79, vcc
	v_mul_f32_e32 v79, v82, v39
	v_mul_f32_e32 v39, 0x3fb8aa3b, v80
	v_fma_f32 v78, v80, s92, -v39
	v_rndne_f32_e32 v81, v39
	v_fmac_f32_e32 v78, 0x32a5705f, v80
	v_sub_f32_e32 v39, v39, v81
	v_add_f32_e32 v39, v39, v78
	v_exp_f32_e32 v39, v39
	v_cvt_i32_f32_e32 v78, v81
	v_cmp_ngt_f32_e32 vcc, s0, v80
	v_cndmask_b32_e64 v81, 0, |v79|, s[46:47]
	v_mul_f32_e32 v85, v82, v38
	v_ldexp_f32 v39, v39, v78
	v_cndmask_b32_e32 v39, 0, v39, vcc
	v_cmp_nlt_f32_e32 vcc, s1, v80
	v_add_f32_e64 v38, |v85|, v81
	v_mul_f32_e32 v86, v82, v37
	v_cndmask_b32_e32 v39, v244, v39, vcc
	v_mul_f32_e32 v83, v39, v42
	v_mul_f32_e64 v42, v71, |v91|
	v_mul_f32_e32 v80, v39, v43
	v_mul_f32_e32 v43, 0x3fb8aa3b, v42
	v_fma_f32 v78, v42, s92, -v43
	v_rndne_f32_e32 v81, v43
	v_fmac_f32_e32 v78, 0x32a5705f, v42
	v_sub_f32_e32 v43, v43, v81
	v_add_f32_e32 v43, v43, v78
	v_exp_f32_e32 v43, v43
	v_cvt_i32_f32_e32 v78, v81
	v_cmp_ngt_f32_e32 vcc, s0, v42
	v_cndmask_b32_e64 v81, 0, |v80|, s[48:49]
	v_add_f32_e64 v81, |v83|, v81
	v_ldexp_f32 v43, v43, v78
	v_cndmask_b32_e32 v43, 0, v43, vcc
	v_cmp_nlt_f32_e32 vcc, s1, v42
	v_add_f32_e32 v38, v38, v81
	v_cndmask_b32_e64 v37, 0, |v86|, s[46:47]
	v_cndmask_b32_e32 v42, v244, v43, vcc
	v_mul_f32_e64 v43, v72, |v91|
	v_mul_f32_e32 v84, v42, v46
; __device__ __forceinline__ int olane() { int l = __builtin_amdgcn_mbcnt_hi(-1, __builtin_amdgcn_mbcnt_lo(-1, 0)); asm volatile("" : "+v"(l)); return l; }
; __device__ __forceinline__ float bperm_f(int addr, float v) { return __uint_as_float((unsigned)__builtin_amdgcn_ds_bpermute(addr, (int)__float_as_uint(v))); }
; __device__ __forceinline__ float wave_sum(float v) { const int l = olane();
; #pragma unroll
;     for (int o = 32; o >= 1; o >>= 1) v += bperm_f((l ^ o) << 2, v);
;     return v; }
; __device__ void ph_filter_gen(const Params& P, int j, const float* __restrict__ a3, float* __restrict__ kf, float* sl) {
;     ...
;             const float dec = expf(-((float)t / (float)(SEQ - 1)) * delta);
;             hv[i][0] = a0 * dec; hv[i][1] = a1 * dec; hv[i][2] = a2 * dec; hv[i][3] = a3v * dec;
;             n0 += fabsf(hv[i][0]) + (t >= 1 ? fabsf(hv[i][1]) : 0.f); n1 += fabsf(hv[i][2]) + (t >= 1 ? fabsf(hv[i][3]) : 0.f); }
;         n0 = wave_sum(n0); n1 = wave_sum(n1);
;         if (lane == 0) { red[wid * 2] = n0; red[wid * 2 + 1] = n1; }
	v_mul_f32_e32 v46, 0x3fb8aa3b, v43
	v_mul_f32_e32 v78, v42, v47
	v_fma_f32 v47, v43, s92, -v46
	v_rndne_f32_e32 v81, v46
	v_fmac_f32_e32 v47, 0x32a5705f, v43
	v_sub_f32_e32 v46, v46, v81
	v_add_f32_e32 v46, v46, v47
	v_exp_f32_e32 v46, v46
	v_cvt_i32_f32_e32 v47, v81
	v_cmp_ngt_f32_e32 vcc, s0, v43
	v_cndmask_b32_e64 v81, 0, |v78|, s[50:51]
	v_add_f32_e64 v81, |v84|, v81
	v_ldexp_f32 v46, v46, v47
	v_cndmask_b32_e32 v46, 0, v46, vcc
	v_cmp_nlt_f32_e32 vcc, s1, v43
	v_mul_f32_e64 v47, v73, |v91|
	v_add_f32_e32 v38, v38, v81
	v_cndmask_b32_e32 v43, v244, v46, vcc
	v_mul_f32_e32 v81, v43, v50
	v_mul_f32_e32 v50, v43, v51
	v_mul_f32_e32 v51, 0x3fb8aa3b, v47
	v_fma_f32 v87, v47, s92, -v51
	v_rndne_f32_e32 v88, v51
	v_fmac_f32_e32 v87, 0x32a5705f, v47
	v_sub_f32_e32 v51, v51, v88
	v_add_f32_e32 v51, v51, v87
	v_exp_f32_e32 v51, v51
	v_cvt_i32_f32_e32 v87, v88
	v_cndmask_b32_e64 v46, 0, |v50|, s[52:53]
	v_add_f32_e64 v46, |v81|, v46
	v_mul_f32_e32 v90, v82, v36
	v_add_f32_e64 v36, |v90|, v37
	v_add_f32_e32 v37, v38, v46
	v_ldexp_f32 v38, v51, v87
	v_cmp_ngt_f32_e32 vcc, s0, v47
	v_mul_f32_e32 v88, v39, v40
	v_mul_f32_e64 v40, v74, |v91|
	v_cndmask_b32_e32 v38, 0, v38, vcc
	v_cmp_nlt_f32_e32 vcc, s1, v47
	v_mul_f32_e32 v87, v39, v41
	v_mul_f32_e32 v41, 0x3fb8aa3b, v40
	v_cndmask_b32_e32 v38, v244, v38, vcc
	v_mul_f32_e32 v47, v38, v55
	v_fma_f32 v51, v40, s92, -v41
	v_rndne_f32_e32 v55, v41
	v_fmac_f32_e32 v51, 0x32a5705f, v40
	v_sub_f32_e32 v41, v41, v55
	v_add_f32_e32 v41, v41, v51
	v_exp_f32_e32 v41, v41
	v_cvt_i32_f32_e32 v51, v55
	v_cndmask_b32_e64 v39, 0, |v87|, s[48:49]
	v_add_f32_e64 v39, |v88|, v39
	v_add_f32_e32 v36, v36, v39
	v_ldexp_f32 v39, v41, v51
	v_cmp_ngt_f32_e32 vcc, s0, v40
	v_mul_f32_e32 v82, v38, v52
	v_mul_f32_e32 v89, v42, v44
	v_cndmask_b32_e32 v39, 0, v39, vcc
	v_cmp_nlt_f32_e32 vcc, s1, v40
	v_mul_f32_e32 v54, v38, v54
	v_cndmask_b32_e64 v46, 0, |v47|, s[54:55]
	v_cndmask_b32_e32 v39, v244, v39, vcc
	v_mul_f32_e32 v52, v39, v58
	v_mul_f32_e32 v58, v42, v45
	v_cndmask_b32_e64 v41, 0, |v58|, s[50:51]
	v_add_f32_e64 v41, |v89|, v41
	v_mul_f32_e64 v42, v75, |v91|
	v_add_f32_e32 v41, v36, v41
	v_mul_f32_e32 v36, 0x3fb8aa3b, v42
	v_fma_f32 v44, v42, s92, -v36
	v_rndne_f32_e32 v45, v36
	v_fmac_f32_e32 v44, 0x32a5705f, v42
	v_sub_f32_e32 v36, v36, v45
	v_add_f32_e32 v36, v36, v44
	v_add_f32_e64 v46, |v54|, v46
	v_exp_f32_e32 v44, v36
	v_cvt_i32_f32_e32 v45, v45
	v_add_f32_e32 v37, v37, v46
	v_mul_f32_e32 v46, v39, v59
	v_cndmask_b32_e64 v40, 0, |v46|, s[56:57]
	v_mul_f32_e32 v55, v38, v53
	v_add_f32_e64 v40, |v52|, v40
	v_cndmask_b32_e64 v38, 0, |v55|, s[54:55]
	v_add_f32_e64 v36, |v82|, v38
	v_add_f32_e32 v38, v37, v40
	v_ldexp_f32 v37, v44, v45
	v_cmp_ngt_f32_e32 vcc, s0, v42
	v_mul_f32_e32 v53, v39, v56
	v_mul_f32_e32 v56, v43, v49
	v_cndmask_b32_e32 v37, 0, v37, vcc
	v_cmp_nlt_f32_e32 vcc, s1, v42
	v_mul_f32_e32 v59, v43, v48
	v_mul_f32_e32 v48, v39, v57
	v_cndmask_b32_e32 v92, v244, v37, vcc
	v_mul_f32_e32 v44, v92, v63
	v_mul_f32_e32 v51, v92, v62
	v_cndmask_b32_e64 v37, 0, |v44|, s[58:59]
	v_add_f32_e64 v40, |v51|, v37
	v_cndmask_b32_e64 v37, 0, |v56|, s[52:53]
	v_add_f32_e64 v42, |v59|, v37
	v_mul_f32_e64 v39, v76, |v91|
	v_cndmask_b32_e64 v37, 0, |v48|, s[56:57]
	v_add_f32_e32 v42, v41, v42
	v_and_b32_e32 v43, 0x7fffffff, v53
	v_mul_f32_e32 v41, 0x3fb8aa3b, v39
	v_pk_add_f32 v[36:37], v[42:43], v[36:37]
	v_fma_f32 v42, v39, s92, -v41
	v_rndne_f32_e32 v43, v41
	v_fmac_f32_e32 v42, 0x32a5705f, v39
	v_sub_f32_e32 v41, v41, v43
	v_add_f32_e32 v41, v41, v42
	v_exp_f32_e32 v42, v41
	v_cvt_i32_f32_e32 v43, v43
	v_pk_add_f32 v[36:37], v[36:37], v[36:37] op_sel_hi:[0,1]
	v_cmp_ngt_f32_e32 vcc, s0, v39
	v_mul_f32_e32 v45, v92, v61
	v_ldexp_f32 v36, v42, v43
	v_cndmask_b32_e32 v36, 0, v36, vcc
	v_cmp_nlt_f32_e32 vcc, s1, v39
	v_mov_b32_e32 v39, v239
	v_cndmask_b32_e64 v61, 0, |v45|, s[58:59]
	v_lshlrev_b32_e32 v57, 2, v39
	v_mov_b32_e32 v39, v239
	v_mul_f32_e32 v49, v92, v60
	v_add_f32_e64 v41, |v49|, v61
	v_cndmask_b32_e32 v36, v244, v36, vcc
	v_lshlrev_b32_e32 v63, 2, v39
	v_mov_b32_e32 v39, v37
	v_pk_add_f32 v[40:41], v[38:39], v[40:41]
	v_pk_mul_f32 v[38:39], v[36:37], v[66:67] op_sel_hi:[0,1]
	v_pk_mul_f32 v[36:37], v[36:37], v[64:65] op_sel_hi:[0,1]
	v_and_b32_e32 v43, 0x7fffffff, v39
	v_and_b32_e32 v42, 0x7fffffff, v38
	v_cndmask_b32_e64 v61, 0, |v37|, s[60:61]
	v_cndmask_b32_e64 v60, 0, |v36|, s[60:61]
	v_pk_add_f32 v[42:43], v[42:43], v[60:61]
	v_xor_b32_e32 v62, 0x80, v57
	v_xor_b32_e32 v91, 0x80, v63
	v_pk_add_f32 v[40:41], v[40:41], v[42:43]
	ds_bpermute_b32 v42, v62, v40
	ds_bpermute_b32 v43, v91, v41
	v_xor_b32_e32 v60, 64, v57
	v_xor_b32_e32 v61, 64, v63
	s_waitcnt lgkmcnt(0)
	v_pk_add_f32 v[40:41], v[40:41], v[42:43]
	ds_bpermute_b32 v42, v60, v40
	ds_bpermute_b32 v43, v61, v41
	v_xor_b32_e32 v60, 32, v57
	v_xor_b32_e32 v61, 32, v63
	s_waitcnt lgkmcnt(0)
	v_pk_add_f32 v[40:41], v[40:41], v[42:43]
	ds_bpermute_b32 v42, v60, v40
	ds_bpermute_b32 v43, v61, v41
	v_xor_b32_e32 v60, 16, v57
	v_xor_b32_e32 v61, 16, v63
	s_waitcnt lgkmcnt(0)
	v_pk_add_f32 v[40:41], v[40:41], v[42:43]
	ds_bpermute_b32 v42, v60, v40
	ds_bpermute_b32 v43, v61, v41
	v_xor_b32_e32 v60, 8, v57
	v_xor_b32_e32 v61, 8, v63
	v_xor_b32_e32 v57, 4, v57
	s_waitcnt lgkmcnt(0)
	v_pk_add_f32 v[40:41], v[40:41], v[42:43]
	ds_bpermute_b32 v42, v60, v40
	ds_bpermute_b32 v43, v61, v41
	s_waitcnt lgkmcnt(0)
	v_pk_add_f32 v[40:41], v[40:41], v[42:43]
	v_xor_b32_e32 v43, 4, v63
	ds_bpermute_b32 v42, v57, v40
	ds_bpermute_b32 v43, v43, v41
	s_and_saveexec_b64 s[10:11], s[42:43]
	s_cbranch_execz .LBB0_238
	s_waitcnt lgkmcnt(0)
	v_pk_add_f32 v[40:41], v[40:41], v[42:43]
	ds_write2_b32 v77, v40, v41 offset1:1

; #define LAS __attribute__((address_space(3)))
;     __device__ __forceinline__ int qtok(int n) const { return (r0 + (n >> 4)) * 64 + c0 + (n & 15); }
;     __device__ __forceinline__ void init(int n, int hh) { rq = r0 + (n >> 4); const int cq = c0 + (n & 15); rsq = rq - 4; rsq = rsq < 0 ? 0 : (rsq > 56 ? 56 : rsq); int csq = cq - 8; csq = csq < 0 ? 0 : (csq > 48 ? 48 : csq);
;         cbase = cw0 + 4 * hh - cq + 15; int m = 0;
; #pragma unroll
;         for (int i = 0; i < 16; ++i) { const int ck = cw0 + 4 * hh + CI32(i); m |= (ck >= csq && ck < csq + 16) ? (1 << i) : 0; }
;         colmask = m; }
; __device__ __forceinline__ void natten_wave_task2(const bf16_t* __restrict__ proj, int b, int h, NatPol pA, NatPol pB, bf16_t* __restrict__ yout, int lane, LAS unsigned char* wl) {
;     const int r = lane & 31, hh = lane >> 5, xaddr = (lane ^ 32) << 2;
;     pA.init(r, hh); pB.init(r, hh);
;     const int qtA = pA.qtok(r), qtB = pB.qtok(r);
;     const bf16_t* qbase = proj + (size_t)(b * 16 + h) * (4096 * 64); const bf16_t* kbase = qbase + (size_t)T_TOK * 1024; const bf16_t* vbase = kbase + (size_t)T_TOK * 1024; const bf16_t* gbase = vbase + (size_t)T_TOK * 1024;
;     ...
;         { const LAS unsigned short* rp = (const LAS unsigned short*)(wl + (4 * hh) * 144 + r * 2);
.LBB0_372:
	v_readlane_b32 s0, v255, 47
	v_readlane_b32 s1, v255, 48
	s_andn2_b64 vcc, exec, s[0:1]
	s_cbranch_vccnz .LBB0_390
	v_readlane_b32 s0, v254, 25
	v_readlane_b32 s1, v254, 26
	v_mov_b32_e32 v160, v195
	s_andn2_b64 vcc, exec, s[0:1]
	s_cbranch_vccnz .LBB0_390
	v_readlane_b32 s0, v255, 50
	v_ashrrev_i32_e32 v176, 6, v160
	s_mul_i32 s0, s0, 0xe880
	s_add_u32 s12, s68, s0
	s_movk_i32 s0, 0x1200
	v_lshlrev_b32_e32 v2, 4, v176
	v_mul_lo_u32 v0, v176, s0
	v_and_b32_e32 v2, 48, v2
	v_add_u32_e32 v1, 0, v0
	v_and_b32_e32 v0, 63, v160
	v_med3_u32 v3, v2, 8, 40
	v_bfe_u32 v7, v160, 5, 1
	v_and_or_b32 v178, v160, 15, v2
	v_add_u32_e32 v5, -8, v3
	v_lshlrev_b32_e32 v4, 2, v0
	v_med3_u32 v2, v178, 8, 56
	v_lshlrev_b32_e32 v0, 2, v7
	v_add_u32_e32 v8, -8, v2
	v_or_b32_e32 v9, v5, v0
	v_add_u32_e32 v10, 8, v2
	v_readlane_b32 s1, v255, 51
	s_movk_i32 s0, 0x1d1
	v_cmp_ge_u32_e32 vcc, v9, v8
	v_cmp_lt_u32_e64 s[44:45], v9, v10
	v_or_b32_e32 v11, 1, v9
	s_addc_u32 s17, s69, 0
	v_cmp_gt_i32_e64 s[42:43], s0, v160
	s_and_b64 s[0:1], vcc, s[44:45]
	v_cmp_ge_u32_e32 vcc, v11, v8
	v_cmp_lt_u32_e64 s[44:45], v11, v10
	v_or_b32_e32 v12, 2, v9
	s_and_b64 s[6:7], vcc, s[44:45]
	v_cmp_ge_u32_e32 vcc, v12, v8
	v_cmp_lt_u32_e64 s[44:45], v12, v10
	v_or_b32_e32 v13, 3, v9
	v_cndmask_b32_e64 v11, 0, 2, s[6:7]
	s_and_b64 s[6:7], vcc, s[44:45]
	v_cmp_ge_u32_e32 vcc, v13, v8
	v_cmp_lt_u32_e64 s[44:45], v13, v10
	v_add_u32_e32 v14, 8, v9
	v_cndmask_b32_e64 v12, 0, 4, s[6:7]
	s_and_b64 s[6:7], vcc, s[44:45]
	v_cmp_ge_u32_e32 vcc, v14, v8
	v_cmp_lt_u32_e64 s[44:45], v9, v2
	v_add_u32_e32 v2, 9, v9
	v_cndmask_b32_e64 v13, 0, 8, s[6:7]
	s_and_b64 s[6:7], s[44:45], vcc
	v_cmp_ge_u32_e32 vcc, v2, v8
	v_cmp_lt_u32_e64 s[44:45], v2, v10
	v_add_u32_e32 v2, 10, v9
	v_cndmask_b32_e64 v14, 0, 16, s[6:7]
	s_and_b64 s[6:7], vcc, s[44:45]
	v_cmp_ge_u32_e32 vcc, v2, v8
	v_cmp_lt_u32_e64 s[44:45], v2, v10
	v_add_u32_e32 v2, 11, v9
	v_cndmask_b32_e64 v15, 0, 32, s[6:7]
	s_and_b64 s[6:7], vcc, s[44:45]
	v_cmp_ge_u32_e32 vcc, v2, v8
	v_cmp_lt_u32_e64 s[44:45], v2, v10
	s_and_b64 vcc, vcc, s[44:45]
	v_mov_b32_e32 v2, 0x80
	v_cndmask_b32_e32 v17, 0, v2, vcc
	v_add_u32_e32 v2, 16, v9
	v_cmp_ge_u32_e32 vcc, v2, v8
	v_cmp_lt_u32_e64 s[44:45], v2, v10
	s_and_b64 vcc, vcc, s[44:45]
	v_mov_b32_e32 v2, 0x100
	v_cndmask_b32_e32 v18, 0, v2, vcc
	v_add_u32_e32 v2, 17, v9
	v_cmp_ge_u32_e32 vcc, v2, v8
	v_cmp_lt_u32_e64 s[44:45], v2, v10
	s_and_b64 vcc, vcc, s[44:45]
	v_mov_b32_e32 v2, 0x200
	v_cndmask_b32_e32 v19, 0, v2, vcc
	v_add_u32_e32 v2, 18, v9
	v_cmp_ge_u32_e32 vcc, v2, v8
	v_cmp_lt_u32_e64 s[44:45], v2, v10
	s_and_b64 vcc, vcc, s[44:45]
	v_mov_b32_e32 v2, 0x400
	v_cndmask_b32_e32 v20, 0, v2, vcc
	v_add_u32_e32 v2, 19, v9
	v_cmp_ge_u32_e32 vcc, v2, v8
	v_cmp_lt_u32_e64 s[44:45], v2, v10
	s_and_b64 vcc, vcc, s[44:45]
	v_mov_b32_e32 v2, 0x800
	v_cndmask_b32_e32 v21, 0, v2, vcc
	v_add_u32_e32 v2, 24, v9
	v_cmp_ge_u32_e32 vcc, v2, v8
	v_cmp_lt_u32_e64 s[44:45], v2, v10
	s_and_b64 vcc, vcc, s[44:45]
	v_add_u32_e32 v2, 25, v9
	v_cndmask_b32_e32 v22, 0, v231, vcc
	v_cmp_ge_u32_e32 vcc, v2, v8
	v_cmp_lt_u32_e64 s[44:45], v2, v10
	s_and_b64 vcc, vcc, s[44:45]
	v_add_u32_e32 v2, 26, v9
	v_cndmask_b32_e32 v23, 0, v238, vcc
	v_cmp_ge_u32_e32 vcc, v2, v8
	v_cmp_lt_u32_e64 s[44:45], v2, v10
	v_add_u32_e32 v2, 27, v9
	v_cndmask_b32_e64 v9, 0, 1, s[0:1]
	v_or_b32_e32 v9, v11, v9
	v_or3_b32 v9, v9, v12, v13
	v_cndmask_b32_e64 v16, 0, 64, s[6:7]
	v_or3_b32 v9, v9, v14, v15
	s_and_b64 vcc, vcc, s[44:45]
	v_or3_b32 v9, v9, v16, v17
	v_cndmask_b32_e32 v24, 0, v230, vcc
	v_cmp_ge_u32_e32 vcc, v2, v8
	v_cmp_lt_u32_e64 s[44:45], v2, v10
	v_or3_b32 v9, v9, v18, v19
	s_and_b64 vcc, vcc, s[44:45]
	v_mov_b32_e32 v2, 0x8000
	v_or3_b32 v9, v9, v20, v21
	v_cndmask_b32_e32 v8, 0, v2, vcc
	v_or3_b32 v9, v9, v22, v23
	v_and_b32_e32 v6, 31, v160
	v_or3_b32 v179, v9, v24, v8
	v_bfe_u32 v8, v160, 3, 3
	v_add_lshl_u32 v181, v5, v6, 6
	v_or_b32_e32 v5, v5, v8
	v_lshlrev_b32_e32 v182, 6, v5
	v_or_b32_e32 v5, v3, v8
	v_lshlrev_b32_e32 v183, 6, v5
	v_lshlrev_b32_e32 v5, 4, v160
	v_and_b32_e32 v5, 0x70, v5
	s_movk_i32 s0, 0x240
	v_lshlrev_b32_e32 v2, 3, v7
	v_add_u32_e32 v5, v1, v5
	v_mad_u32_u24 v1, v7, s0, v1
	v_mul_u32_u24_e32 v7, 0x90, v8
	v_max_i32_e32 v8, 0xffffffd1, v160
	v_sub_u32_e32 v8, v8, v160
	v_add_u32_e32 v8, 0x1ff, v8
	v_lshrrev_b32_e32 v9, 9, v8
	v_xor_b32_e32 v180, 0x80, v4
	v_lshlrev_b32_e32 v4, 3, v160
	v_add_u32_e32 v9, 1, v9
	v_or_b32_e32 v3, v3, v0
	s_add_i32 s35, 0, 0x100
	v_readlane_b32 s0, v255, 56
	v_and_b32_e32 v4, 56, v4
	v_lshlrev_b32_e32 v6, 1, v6
	v_and_b32_e32 v186, 0xfffffe, v9
	v_sub_u32_e32 v3, v3, v178
	s_add_u32 s38, s68, s0
	v_bfe_u32 v177, v160, 4, 1
	v_add_u32_e32 v184, 0x200, v183
	v_add_u32_e32 v185, 0x400, v183
	v_cmp_lt_u32_e64 s[44:45], s82, v8
	v_lshl_add_u32 v187, v186, 9, v160
	v_add_u32_e32 v161, 0x200, v160
	v_cmp_ne_u32_e64 s[46:47], v9, v186
	v_lshl_add_u32 v188, v3, 2, 0
	v_lshlrev_b32_e32 v189, 2, v160
	s_addc_u32 s39, s69, s93
	v_lshlrev_b32_e32 v192, 1, v2
	v_lshlrev_b32_e32 v162, 1, v4
	v_add_u32_e32 v190, v5, v7
	v_add_u32_e32 v191, v1, v6
	v_lshlrev_b32_e32 v164, 1, v0
	v_readlane_b32 s52, v254, 29
	v_lshrrev_b32_e32 v191, 6, v195
	v_mul_u32_u24_e32 v191, 0x1200, v191
	v_bfe_u32 v198, v195, 5, 1
	v_mul_u32_u24_e32 v198, 0x240, v198
	v_add_u32_e32 v191, v191, v198
	v_bfe_u32 v198, v195, 2, 2
	v_mul_u32_u24_e32 v198, 0x90, v198
	v_add_u32_e32 v191, v191, v198
	v_bfe_u32 v198, v195, 4, 1
	v_lshl_add_u32 v191, v198, 5, v191
	v_and_b32_e32 v198, 3, v195
	v_lshl_add_u32 v191, v198, 3, v191
	s_branch .LBB0_376

;     __device__ __forceinline__ int qtok(int n) const { return (r0 + (n >> 4)) * 64 + c0 + (n & 15); }
; __device__ __forceinline__ void natten_wave_task2(const bf16_t* __restrict__ proj, int b, int h, NatPol pA, NatPol pB, bf16_t* __restrict__ yout, int lane, LAS unsigned char* wl) {
;     ...
;     pA.init(r, hh); pB.init(r, hh);
;     const int qtA = pA.qtok(r), qtB = pB.qtok(r);
;     const bf16_t* qbase = proj + (size_t)(b * 16 + h) * (4096 * 64); const bf16_t* kbase = qbase + (size_t)T_TOK * 1024; const bf16_t* vbase = kbase + (size_t)T_TOK * 1024; const bf16_t* gbase = vbase + (size_t)T_TOK * 1024;
;     bf16x8s qA[4], qB[4];
; #pragma unroll
;     for (int s = 0; s < 4; ++s) { qA[s] = *(const bf16x8s*)(qbase + qtA * 64 + 16 * s + 8 * hh); qB[s] = *(const bf16x8s*)(qbase + qtB * 64 + 16 * s + 8 * hh); }
;     f32x16 oA0, oA1, oB0, oB1;
; #pragma unroll
;     for (int i = 0; i < 16; ++i) { oA0[i] = 0.f; oA1[i] = 0.f; oB0[i] = 0.f; oB1[i] = 0.f; }
;     float mA = -40.0f, lA = 0.f, mB = -40.0f, lB = 0.f;
;     constexpr int NB = 11;
;     bf16x8s kf[4]; u32x4a vg[4];
;     attn_loadk<NatPol>(kbase, pA, 0, r, hh, kf);
;     attn_loadv<NatPol>(vbase, pA, 0, r, hh, vg);
; __device__ void ph_natten_mfma(const Params& P, int j, int half, const bf16_t* __restrict__ proj, bf16_t* __restrict__ yout, unsigned char* lds_raw) {
;     ...
;     for (int id0 = vb * 8; id0 < 8192; id0 += G * 8) {
;         const int p = id0 >> 6, b = p >> 4, h = p & 15, wt = (id0 & 63) + wid;
;         __syncthreads();
;         for (int x = tid; x < 465; x += NT) tbl[64 + x] = rpb[(size_t)(half * 16 + h) * 465 + x] * 1.44269504088896341f;
;         __syncthreads();
;         const int r0 = (wt >> 2) * 4, c0 = (wt & 3) * 16;
;         int rs0 = r0 - 4; rs0 = rs0 < 0 ? 0 : (rs0 > 56 ? 56 : rs0); int cw0 = c0 - 8; cw0 = cw0 < 0 ? 0 : (cw0 > 32 ? 32 : cw0);
;         NatPol polA{r0, c0, rs0, cw0, tbl + 64, 0, 0, 0, 0}, polB{r0 + 2, c0, rs0, cw0, tbl + 64, 0, 0, 0, 0};
.LBB0_386:
	s_or_b64 exec, exec, s[6:7]
	s_and_b32 s1, s52, 56
	v_add_u32_e32 v0, s1, v176
	s_ashr_i32 s1, s52, 10
	s_lshl_b32 s6, s1, 4
	v_and_b32_e32 v0, -4, v0
	s_or_b32 s6, s6, s0
	v_med3_i32 v1, v0, 4, 60
	v_sub_u32_e32 v2, 0, v177
	v_or_b32_e32 v4, v0, v177
	s_ashr_i32 s7, s6, 31
	v_add_u32_e32 v2, v2, v1
	v_or_b32_e32 v6, 2, v4
	v_lshl_or_b32 v205, v4, 6, v178
	s_lshl_b64 s[6:7], s[6:7], 19
	v_readlane_b32 s14, v252, 36
	v_sub_u32_e32 v206, v2, v0
	v_min_i32_e32 v0, 60, v4
	v_lshl_or_b32 v204, v6, 6, v178
	v_readlane_b32 s15, v252, 37
	s_add_u32 s6, s14, s6
	v_lshlrev_b32_e32 v168, 6, v205
	v_add_u32_e32 v5, -4, v0
	v_min_i32_e32 v0, 60, v6
	s_addc_u32 s7, s15, s7
	v_ashrrev_i32_e32 v169, 31, v168
	v_lshlrev_b32_e32 v166, 6, v204
	v_add_u32_e32 v165, -4, v1
	v_add_u32_e32 v207, -4, v1
	v_add_u32_e32 v7, -4, v0
	v_lshl_add_u64 v[0:1], v[168:169], 1, s[6:7]
	v_ashrrev_i32_e32 v167, 31, v166
	v_lshl_add_u64 v[0:1], v[0:1], 0, v[192:193]
	v_lshl_add_u64 v[2:3], v[166:167], 1, s[6:7]
	s_waitcnt lgkmcnt(0)
	s_barrier
	s_add_u32 s14, s6, 0x4000000
	v_lshl_add_u64 v[2:3], v[2:3], 0, v[192:193]
	global_load_dwordx4 v[96:99], v[0:1], off
	global_load_dwordx4 v[100:103], v[0:1], off offset:32
	global_load_dwordx4 v[104:107], v[2:3], off
	global_load_dwordx4 v[108:111], v[2:3], off offset:32
	global_load_dwordx4 v[112:115], v[0:1], off offset:64
	global_load_dwordx4 v[116:119], v[0:1], off offset:96
	global_load_dwordx4 v[120:123], v[2:3], off offset:64
	global_load_dwordx4 v[124:127], v[2:3], off offset:96
	v_lshlrev_b32_e32 v211, 12, v207
	s_addc_u32 s15, s7, 0
	v_add_lshl_u32 v0, v211, v181, 1
	v_mov_b32_e32 v1, v193
	v_lshl_add_u64 v[0:1], s[14:15], 0, v[0:1]
	v_lshl_add_u64 v[0:1], v[0:1], 0, v[192:193]
	v_cmp_lt_i32_e32 vcc, 3, v4
	v_mov_b32_e32 v163, v193
	v_lshl_add_u64 v[0:1], s[6:7], 0, v[162:163]
	v_cndmask_b32_e32 v208, 0, v5, vcc
	v_cmp_lt_i32_e32 vcc, 3, v6
	s_mov_b64 s[18:19], 0x8000000
	v_lshl_add_u64 v[170:171], v[0:1], 0, s[18:19]
	s_mov_b32 s100, 0xfc000000
	s_mov_b32 s101, -1
	v_lshl_add_u64 v[240:241], v[170:171], 0, s[100:101]
	v_lshrrev_b32_e32 v242, 6, v195
	v_mul_u32_u24_e32 v242, 0x1200, v242
	v_and_b32_e32 v243, 31, v195
	v_mul_u32_u24_e32 v243, 0x90, v243
	v_add_u32_e32 v242, v242, v243
	v_bfe_u32 v243, v195, 5, 1
	v_lshl_add_u32 v242, v243, 4, v242
	v_add_u32_e32 v242, 0x9000, v242
	v_add_u32_e32 v243, 0x9000, v190
	v_add_u32_e32 v200, v211, v182
	v_or_b32_e32 v202, v211, v183
	v_ashrrev_i32_e32 v201, 31, v200
	v_ashrrev_i32_e32 v203, 31, v202
	v_lshl_add_u64 v[200:201], v[200:201], 1, v[240:241]
	v_lshl_add_u64 v[202:203], v[202:203], 1, v[240:241]
	global_load_dwordx4 v[140:143], v[200:201], off
	global_load_dwordx4 v[136:139], v[202:203], off
	v_add_u32_e32 v200, v211, v184
	v_add_u32_e32 v202, v211, v185
	v_ashrrev_i32_e32 v201, 31, v200
	v_ashrrev_i32_e32 v203, 31, v202
	v_lshl_add_u64 v[200:201], v[200:201], 1, v[240:241]
	v_lshl_add_u64 v[202:203], v[202:203], 1, v[240:241]
	global_load_dwordx4 v[132:135], v[200:201], off
	global_load_dwordx4 v[128:131], v[202:203], off
	v_add_u32_e32 v200, v211, v182
	v_or_b32_e32 v202, v211, v183
	v_ashrrev_i32_e32 v201, 31, v200
	v_ashrrev_i32_e32 v203, 31, v202
	v_lshl_add_u64 v[200:201], v[200:201], 1, v[170:171]
	v_lshl_add_u64 v[202:203], v[202:203], 1, v[170:171]
	global_load_dwordx4 v[144:147], v[200:201], off
	global_load_dwordx4 v[148:151], v[202:203], off
	v_add_u32_e32 v200, v211, v184
	v_add_u32_e32 v202, v211, v185
	v_ashrrev_i32_e32 v201, 31, v200
	v_ashrrev_i32_e32 v203, 31, v202
	v_lshl_add_u64 v[200:201], v[200:201], 1, v[170:171]
	v_lshl_add_u64 v[202:203], v[202:203], 1, v[170:171]
	global_load_dwordx4 v[152:155], v[200:201], off
	global_load_dwordx4 v[156:159], v[202:203], off
	v_cndmask_b32_e32 v209, 0, v7, vcc
	v_mov_b32_e32 v0, 0
	s_mov_b32 s10, -4
	s_mov_b32 s11, 0
	v_lshl_add_u64 v[172:173], s[14:15], 0, v[192:193]
	v_add_u32_e32 v163, 8, v208
	v_add_u32_e32 v210, 8, v209
	v_mov_b32_e32 v212, 0xc2200000
	v_mov_b32_e32 v213, 0xc2200000
	v_mov_b32_e32 v1, v0
	v_mov_b32_e32 v2, v0
	v_mov_b32_e32 v3, v0
	v_mov_b32_e32 v4, v0
	v_mov_b32_e32 v5, v0
	v_mov_b32_e32 v6, v0
	v_mov_b32_e32 v7, v0
	v_mov_b32_e32 v8, v0
	v_mov_b32_e32 v9, v0
	v_mov_b32_e32 v10, v0
	v_mov_b32_e32 v11, v0
	v_mov_b32_e32 v12, v0
	v_mov_b32_e32 v13, v0
	v_mov_b32_e32 v14, v0
	v_mov_b32_e32 v15, v0
	v_mov_b32_e32 v16, v0
	v_mov_b32_e32 v17, v0
	v_mov_b32_e32 v18, v0
	v_mov_b32_e32 v19, v0
	v_mov_b32_e32 v20, v0
	v_mov_b32_e32 v21, v0
	v_mov_b32_e32 v22, v0
	v_mov_b32_e32 v23, v0
	v_mov_b32_e32 v24, v0
	v_mov_b32_e32 v25, v0
	v_mov_b32_e32 v26, v0
	v_mov_b32_e32 v27, v0
	v_mov_b32_e32 v28, v0
	v_mov_b32_e32 v29, v0
	v_mov_b32_e32 v30, v0
	v_mov_b32_e32 v31, v0
	v_mov_b32_e32 v32, v0
	v_mov_b32_e32 v33, v0
	v_mov_b32_e32 v34, v0
	v_mov_b32_e32 v35, v0
	v_mov_b32_e32 v36, v0
	v_mov_b32_e32 v37, v0
	v_mov_b32_e32 v38, v0
	v_mov_b32_e32 v39, v0
	v_mov_b32_e32 v40, v0
	v_mov_b32_e32 v41, v0
	v_mov_b32_e32 v42, v0
	v_mov_b32_e32 v43, v0
	v_mov_b32_e32 v44, v0
	v_mov_b32_e32 v45, v0
	v_mov_b32_e32 v46, v0
	v_mov_b32_e32 v47, v0
	v_mov_b32_e32 v48, v0
	v_mov_b32_e32 v49, v0
	v_mov_b32_e32 v50, v0
	v_mov_b32_e32 v51, v0
	v_mov_b32_e32 v52, v0
	v_mov_b32_e32 v53, v0
	v_mov_b32_e32 v54, v0
	v_mov_b32_e32 v55, v0
	v_mov_b32_e32 v56, v0
	v_mov_b32_e32 v57, v0
	v_mov_b32_e32 v58, v0
	v_mov_b32_e32 v59, v0
	v_mov_b32_e32 v60, v0
	v_mov_b32_e32 v61, v0
	v_mov_b32_e32 v62, v0
	v_mov_b32_e32 v63, v0
	v_mov_b32_e32 v174, v0
	v_mov_b32_e32 v175, v0
	s_branch .LBB0_388
; #define LAS __attribute__((address_space(3)))
; __device__ __forceinline__ void natten_wave_task2(const bf16_t* __restrict__ proj, int b, int h, NatPol pA, NatPol pB, bf16_t* __restrict__ yout, int lane, LAS unsigned char* wl) {
;     ...
;         float psA = 0.f, psB = 0.f;
; #pragma unroll
;         for (int i = 0; i < 16; ++i) { const float pa = __builtin_amdgcn_exp2f(scA[i] - mA); scA[i] = pa; psA += pa; const float pb = __builtin_amdgcn_exp2f(scB[i] - mB); scB[i] = pb; psB += pb; }
;         lA += psA; lB += psB;
;         { asm volatile("" ::: "memory");
; #pragma unroll
;           for (int j = 0; j < 4; ++j) *(LAS u32x4a*)(wl + (8 * j + (lane >> 3)) * 144 + (lane & 7) * 16) = vg[j];
;           asm volatile("" ::: "memory"); }
;         attn_loadv<NatPol>(vbase, pA, fbn, r, hh, vg);
;         u32x4a va[2], vb[2];
;         { const LAS unsigned short* rp = (const LAS unsigned short*)(wl + (4 * hh) * 144 + r * 2);
; #pragma unroll
;           for (int s = 0; s < 2; ++s)
; #pragma unroll
;             for (int jx = 0; jx < 4; ++jx) { const int k0 = 16 * s + 8 * ((2 * jx) >> 2) + ((2 * jx) & 3), k1 = k0 + 1;
;                 va[s][jx] = (unsigned)rp[k0 * 72] | ((unsigned)rp[k1 * 72] << 16); vb[s][jx] = (unsigned)rp[k0 * 72 + 32] | ((unsigned)rp[k1 * 72 + 32] << 16); } }
; #pragma unroll
;         for (int s = 0; s < 2; ++s) { f32x8v ta, tb;
; #pragma unroll
;             for (int jx = 0; jx < 8; ++jx) { ta[jx] = scA[8 * s + jx]; tb[jx] = scB[8 * s + jx]; }
;             const bf16x8s pfa = __builtin_bit_cast(bf16x8s, __builtin_convertvector(ta, bf16x8n)), pfb = __builtin_bit_cast(bf16x8s, __builtin_convertvector(tb, bf16x8n));
;             oA0 = __builtin_amdgcn_mfma_f32_32x32x16_bf16(__builtin_bit_cast(bf16x8s, va[s]), pfa, oA0, 0, 0, 0);
;             oA1 = __builtin_amdgcn_mfma_f32_32x32x16_bf16(__builtin_bit_cast(bf16x8s, vb[s]), pfa, oA1, 0, 0, 0);
;             oB0 = __builtin_amdgcn_mfma_f32_32x32x16_bf16(__builtin_bit_cast(bf16x8s, va[s]), pfb, oB0, 0, 0, 0);
;             oB1 = __builtin_amdgcn_mfma_f32_32x32x16_bf16(__builtin_bit_cast(bf16x8s, vb[s]), pfb, oB1, 0, 0, 0); }
.Lhop_lbb8:
	s_branch .LBB0_8
.LBB0_387:
	v_sub_f32_e32 v76, v218, v212
	v_exp_f32_e32 v79, v76
	v_sub_f32_e32 v76, v219, v212
	v_exp_f32_e32 v218, v76
	v_sub_f32_e32 v76, v92, v213
	v_add_f32_e32 v77, 0, v79
	v_sub_f32_e32 v66, v66, v213
	v_exp_f32_e32 v219, v76
	v_add_f32_e32 v76, v218, v77
	v_sub_f32_e32 v77, v93, v213
	v_exp_f32_e32 v225, v66
	v_sub_f32_e32 v66, v67, v213
	v_exp_f32_e32 v220, v77
	v_sub_f32_e32 v77, v216, v212
	v_exp_f32_e32 v226, v66
	v_sub_f32_e32 v66, v82, v212
	v_exp_f32_e32 v216, v77
	v_sub_f32_e32 v77, v90, v213
	v_exp_f32_e32 v90, v66
	v_sub_f32_e32 v66, v68, v213
	v_exp_f32_e32 v221, v77
	v_sub_f32_e32 v77, v91, v213
	v_exp_f32_e32 v91, v66
	v_sub_f32_e32 v66, v83, v212
	v_exp_f32_e32 v82, v66
	v_sub_f32_e32 v66, v69, v213
	v_exp_f32_e32 v83, v66
	v_sub_f32_e32 v66, v84, v212
	v_exp_f32_e32 v92, v66
	v_sub_f32_e32 v66, v70, v213
	v_exp_f32_e32 v93, v66
	v_sub_f32_e32 v66, v85, v212
	v_exp_f32_e32 v84, v66
	v_sub_f32_e32 v66, v71, v213
	v_exp_f32_e32 v85, v66
	v_sub_f32_e32 v66, v86, v212
	v_exp_f32_e32 v94, v66
	v_sub_f32_e32 v66, v72, v213
	v_exp_f32_e32 v95, v66
	v_sub_f32_e32 v198, v87, v212
	s_waitcnt vmcnt(7)
	ds_write_b128 v190, v[144:147] offset:32768
	s_waitcnt vmcnt(6)
	ds_write_b128 v190, v[148:151] offset:33920
	s_waitcnt vmcnt(5)
	ds_write_b128 v190, v[152:155] offset:35072
	s_waitcnt vmcnt(4)
	ds_write_b128 v190, v[156:159] offset:36224
	s_cmp_eq_u32 s11, 11
	s_cbranch_scc1 .Lnat0_skipv
	v_add_u32_e32 v200, v211, v182
	v_or_b32_e32 v202, v211, v183
	v_ashrrev_i32_e32 v201, 31, v200
	v_ashrrev_i32_e32 v203, 31, v202
	v_lshl_add_u64 v[200:201], v[200:201], 1, v[170:171]
	v_lshl_add_u64 v[202:203], v[202:203], 1, v[170:171]
	global_load_dwordx4 v[144:147], v[200:201], off
	global_load_dwordx4 v[148:151], v[202:203], off
	v_add_u32_e32 v200, v211, v184
	v_add_u32_e32 v202, v211, v185
	v_ashrrev_i32_e32 v201, 31, v200
	v_ashrrev_i32_e32 v203, 31, v202
	v_lshl_add_u64 v[200:201], v[200:201], 1, v[170:171]
	v_lshl_add_u64 v[202:203], v[202:203], 1, v[170:171]
	global_load_dwordx4 v[152:155], v[200:201], off
	global_load_dwordx4 v[156:159], v[202:203], off
.Lnat0_skipv:
	ds_read_b64_tr_b16 v[66:67], v191 offset:32768
	ds_read_b64_tr_b16 v[68:69], v191 offset:33920
	ds_read_b64_tr_b16 v[70:71], v191 offset:32832
	v_exp_f32_e32 v86, v198
	v_sub_f32_e32 v198, v73, v213
	ds_read_b64_tr_b16 v[72:73], v191 offset:33984
	v_exp_f32_e32 v87, v198
	v_sub_f32_e32 v198, v88, v212
	v_sub_f32_e32 v78, v217, v212
	v_exp_f32_e32 v223, v77
	v_sub_f32_e32 v77, v214, v212
	v_exp_f32_e32 v214, v198
	v_sub_f32_e32 v198, v74, v213
	v_exp_f32_e32 v217, v78
	v_sub_f32_e32 v78, v215, v212
	v_exp_f32_e32 v215, v198
	v_sub_f32_e32 v198, v89, v212
	v_exp_f32_e32 v88, v198
	v_sub_f32_e32 v198, v75, v213
	v_exp_f32_e32 v89, v198
	v_sub_f32_e32 v198, v81, v212
	v_exp_f32_e32 v196, v198
	v_exp_f32_e32 v222, v78
	v_exp_f32_e32 v224, v77
	v_add_f32_e32 v76, v217, v76
	v_add_f32_e32 v76, v216, v76
	v_add_f32_e32 v76, v222, v76
	v_add_f32_e32 v78, v224, v76
	v_cvt_pk_bf16_f32 v77, v90, v82
	v_cvt_pk_bf16_f32 v76, v222, v224
	v_cvt_pk_bf16_f32 v75, v217, v216
	v_cvt_pk_bf16_f32 v74, v79, v218
	v_sub_f32_e32 v64, v64, v213
	v_exp_f32_e32 v197, v64
	s_waitcnt lgkmcnt(0)
	v_mfma_f32_32x32x16_bf16 v[48:63], v[66:69], v[74:77], v[48:63]
	v_sub_f32_e32 v64, v80, v212
	v_exp_f32_e32 v80, v64
	v_sub_f32_e32 v64, v65, v213
	v_exp_f32_e32 v81, v64
	v_add_f32_e32 v64, 0, v219
	v_add_f32_e32 v64, v220, v64
	v_add_f32_e32 v64, v221, v64
	v_mfma_f32_32x32x16_bf16 v[32:47], v[70:73], v[74:77], v[32:47]
	v_cvt_pk_bf16_f32 v77, v91, v83
	v_cvt_pk_bf16_f32 v76, v225, v226
	v_cvt_pk_bf16_f32 v75, v221, v223
	v_cvt_pk_bf16_f32 v74, v219, v220
	v_add_f32_e32 v244, v223, v64
	s_add_i32 s10, s10, 1
	v_mfma_f32_32x32x16_bf16 v[16:31], v[66:69], v[74:77], v[16:31]
	ds_read_b64_tr_b16 v[64:65], v191 offset:35072
	ds_read_b64_tr_b16 v[66:67], v191 offset:36224
	ds_read_b64_tr_b16 v[68:69], v191 offset:35136
	s_cmp_lg_u32 s11, 11
	v_add_u32_e32 v165, 1, v165
	v_mfma_f32_32x32x16_bf16 v[0:15], v[70:73], v[74:77], v[0:15]
	ds_read_b64_tr_b16 v[70:71], v191 offset:36288
	v_add_f32_e32 v76, v225, v244
	v_add_f32_e32 v79, v226, v76
	v_pk_add_f32 v[76:77], v[90:91], v[78:79]
	v_cvt_pk_bf16_f32 v75, v196, v80
	v_cvt_pk_bf16_f32 v74, v214, v88
	v_cvt_pk_bf16_f32 v73, v94, v86
	v_cvt_pk_bf16_f32 v72, v92, v84
	v_pk_add_f32 v[76:77], v[82:83], v[76:77]
	s_waitcnt lgkmcnt(0)
	s_nop 0
	v_mfma_f32_32x32x16_bf16 v[48:63], v[64:67], v[72:75], v[48:63]
	v_mfma_f32_32x32x16_bf16 v[32:47], v[68:71], v[72:75], v[32:47]
	v_add_f32_e64 v72, v92, v76
	v_add_f32_e64 v73, v93, v77
	v_cvt_pk_bf16_f32 v75, v197, v81
	v_add_f32_e64 v72, v84, v72
	v_add_f32_e64 v73, v85, v73
	v_cvt_pk_bf16_f32 v74, v215, v89
	v_pk_add_f32 v[76:77], v[94:95], v[72:73]
	v_cvt_pk_bf16_f32 v73, v95, v87
	v_cvt_pk_bf16_f32 v72, v93, v85
	s_nop 1
	v_mfma_f32_32x32x16_bf16 v[16:31], v[64:67], v[72:75], v[16:31]
	v_add_f32_e64 v64, v86, v76
	v_add_f32_e64 v65, v87, v77
	v_add_f32_e64 v64, v214, v64
	v_add_f32_e64 v65, v215, v65
	v_add_f32_e64 v64, v88, v64
	v_add_f32_e64 v65, v89, v65
	v_pk_add_f32 v[64:65], v[196:197], v[64:65]
	v_mfma_f32_32x32x16_bf16 v[0:15], v[68:71], v[72:75], v[0:15]
	v_add_f32_e64 v64, v80, v64
	v_add_f32_e64 v65, v81, v65
	v_add_f32_e64 v174, v174, v64
	v_add_f32_e64 v175, v175, v65
	s_cbranch_scc0 .LBB0_375

; #define LAS __attribute__((address_space(3)))
;     __device__ __forceinline__ int qtok(int n) const { return (r0 + (n >> 4)) * 64 + c0 + (n & 15); }
;     __device__ __forceinline__ void init(int n, int hh) { rq = r0 + (n >> 4); const int cq = c0 + (n & 15); rsq = rq - 4; rsq = rsq < 0 ? 0 : (rsq > 56 ? 56 : rsq); int csq = cq - 8; csq = csq < 0 ? 0 : (csq > 48 ? 48 : csq);
;         cbase = cw0 + 4 * hh - cq + 15; int m = 0;
; #pragma unroll
;         for (int i = 0; i < 16; ++i) { const int ck = cw0 + 4 * hh + CI32(i); m |= (ck >= csq && ck < csq + 16) ? (1 << i) : 0; }
;         colmask = m; }
; __device__ __forceinline__ void natten_wave_task2(const bf16_t* __restrict__ proj, int b, int h, NatPol pA, NatPol pB, bf16_t* __restrict__ yout, int lane, LAS unsigned char* wl) {
;     const int r = lane & 31, hh = lane >> 5, xaddr = (lane ^ 32) << 2;
;     pA.init(r, hh); pB.init(r, hh);
;     const int qtA = pA.qtok(r), qtB = pB.qtok(r);
;     const bf16_t* qbase = proj + (size_t)(b * 16 + h) * (4096 * 64); const bf16_t* kbase = qbase + (size_t)T_TOK * 1024; const bf16_t* vbase = kbase + (size_t)T_TOK * 1024; const bf16_t* gbase = vbase + (size_t)T_TOK * 1024;
;     ...
;         { const LAS unsigned short* rp = (const LAS unsigned short*)(wl + (4 * hh) * 144 + r * 2);
.LBB0_557:
	s_andn2_b64 vcc, exec, s[6:7]
	s_cbranch_vccnz .LBB0_671
	v_readlane_b32 s0, v255, 47
	v_readlane_b32 s1, v255, 48
	s_and_b64 vcc, exec, s[0:1]
	v_readlane_b32 s0, v254, 25
	v_readlane_b32 s1, v254, 26
	s_mov_b64 s[6:7], -1
	s_waitcnt vmcnt(0)
	v_cndmask_b32_e64 v0, 0, 1, s[0:1]
	v_cmp_ne_u32_e64 s[38:39], 1, v0
	s_cbranch_vccz .LBB0_577
	v_mov_b32_e32 v160, v195
	s_and_b64 vcc, exec, s[38:39]
	s_cbranch_vccnz .LBB0_576
	v_readlane_b32 s0, v255, 50
	v_ashrrev_i32_e32 v176, 6, v160
	s_mul_i32 s0, s0, 0xe880
	s_add_u32 s12, s68, s0
	s_movk_i32 s0, 0x1200
	v_lshlrev_b32_e32 v2, 4, v176
	v_mul_lo_u32 v0, v176, s0
	v_and_b32_e32 v2, 48, v2
	v_add_u32_e32 v1, 0, v0
	v_and_b32_e32 v0, 63, v160
	v_med3_u32 v3, v2, 8, 40
	v_bfe_u32 v7, v160, 5, 1
	v_and_or_b32 v178, v160, 15, v2
	v_add_u32_e32 v5, -8, v3
	v_lshlrev_b32_e32 v4, 2, v0
	v_med3_u32 v2, v178, 8, 56
	v_lshlrev_b32_e32 v0, 2, v7
	v_add_u32_e32 v8, -8, v2
	v_or_b32_e32 v9, v5, v0
	v_add_u32_e32 v10, 8, v2
	v_readlane_b32 s1, v255, 51
	s_movk_i32 s0, 0x1d1
	v_cmp_ge_u32_e32 vcc, v9, v8
	v_cmp_lt_u32_e64 s[42:43], v9, v10
	v_or_b32_e32 v11, 1, v9
	s_addc_u32 s17, s69, 0
	v_cmp_gt_i32_e64 s[40:41], s0, v160
	s_and_b64 s[0:1], vcc, s[42:43]
	v_cmp_ge_u32_e32 vcc, v11, v8
	v_cmp_lt_u32_e64 s[42:43], v11, v10
	v_or_b32_e32 v12, 2, v9
	s_and_b64 s[6:7], vcc, s[42:43]
	v_cmp_ge_u32_e32 vcc, v12, v8
	v_cmp_lt_u32_e64 s[42:43], v12, v10
	v_or_b32_e32 v13, 3, v9
	v_cndmask_b32_e64 v11, 0, 2, s[6:7]
	s_and_b64 s[6:7], vcc, s[42:43]
	v_cmp_ge_u32_e32 vcc, v13, v8
	v_cmp_lt_u32_e64 s[42:43], v13, v10
	v_add_u32_e32 v14, 8, v9
	v_cndmask_b32_e64 v12, 0, 4, s[6:7]
	s_and_b64 s[6:7], vcc, s[42:43]
	v_cmp_ge_u32_e32 vcc, v14, v8
	v_cmp_lt_u32_e64 s[42:43], v9, v2
	v_add_u32_e32 v2, 9, v9
	v_cndmask_b32_e64 v13, 0, 8, s[6:7]
	s_and_b64 s[6:7], s[42:43], vcc
	v_cmp_ge_u32_e32 vcc, v2, v8
	v_cmp_lt_u32_e64 s[42:43], v2, v10
	v_add_u32_e32 v2, 10, v9
	v_cndmask_b32_e64 v14, 0, 16, s[6:7]
	s_and_b64 s[6:7], vcc, s[42:43]
	v_cmp_ge_u32_e32 vcc, v2, v8
	v_cmp_lt_u32_e64 s[42:43], v2, v10
	v_add_u32_e32 v2, 11, v9
	v_cndmask_b32_e64 v15, 0, 32, s[6:7]
	s_and_b64 s[6:7], vcc, s[42:43]
	v_cmp_ge_u32_e32 vcc, v2, v8
	v_cmp_lt_u32_e64 s[42:43], v2, v10
	s_and_b64 vcc, vcc, s[42:43]
	v_mov_b32_e32 v2, 0x80
	v_cndmask_b32_e32 v17, 0, v2, vcc
	v_add_u32_e32 v2, 16, v9
	v_cmp_ge_u32_e32 vcc, v2, v8
	v_cmp_lt_u32_e64 s[42:43], v2, v10
	s_and_b64 vcc, vcc, s[42:43]
	v_mov_b32_e32 v2, 0x100
	v_cndmask_b32_e32 v18, 0, v2, vcc
	v_add_u32_e32 v2, 17, v9
	v_cmp_ge_u32_e32 vcc, v2, v8
	v_cmp_lt_u32_e64 s[42:43], v2, v10
	s_and_b64 vcc, vcc, s[42:43]
	v_mov_b32_e32 v2, 0x200
	v_cndmask_b32_e32 v19, 0, v2, vcc
	v_add_u32_e32 v2, 18, v9
	v_cmp_ge_u32_e32 vcc, v2, v8
	v_cmp_lt_u32_e64 s[42:43], v2, v10
	s_and_b64 vcc, vcc, s[42:43]
	v_mov_b32_e32 v2, 0x400
	v_cndmask_b32_e32 v20, 0, v2, vcc
	v_add_u32_e32 v2, 19, v9
	v_cmp_ge_u32_e32 vcc, v2, v8
	v_cmp_lt_u32_e64 s[42:43], v2, v10
	s_and_b64 vcc, vcc, s[42:43]
	v_mov_b32_e32 v2, 0x800
	v_cndmask_b32_e32 v21, 0, v2, vcc
	v_add_u32_e32 v2, 24, v9
	v_cmp_ge_u32_e32 vcc, v2, v8
	v_cmp_lt_u32_e64 s[42:43], v2, v10
	s_and_b64 vcc, vcc, s[42:43]
	v_add_u32_e32 v2, 25, v9
	v_cndmask_b32_e32 v22, 0, v231, vcc
	v_cmp_ge_u32_e32 vcc, v2, v8
	v_cmp_lt_u32_e64 s[42:43], v2, v10
	s_and_b64 vcc, vcc, s[42:43]
	v_add_u32_e32 v2, 26, v9
	v_cndmask_b32_e32 v23, 0, v238, vcc
	v_cmp_ge_u32_e32 vcc, v2, v8
	v_cmp_lt_u32_e64 s[42:43], v2, v10
	v_add_u32_e32 v2, 27, v9
	v_cndmask_b32_e64 v9, 0, 1, s[0:1]
	v_or_b32_e32 v9, v11, v9
	v_or3_b32 v9, v9, v12, v13
	v_cndmask_b32_e64 v16, 0, 64, s[6:7]
	v_or3_b32 v9, v9, v14, v15
	s_and_b64 vcc, vcc, s[42:43]
	v_or3_b32 v9, v9, v16, v17
	v_cndmask_b32_e32 v24, 0, v230, vcc
	v_cmp_ge_u32_e32 vcc, v2, v8
	v_cmp_lt_u32_e64 s[42:43], v2, v10
	v_or3_b32 v9, v9, v18, v19
	s_and_b64 vcc, vcc, s[42:43]
	v_mov_b32_e32 v2, 0x8000
	v_or3_b32 v9, v9, v20, v21
	v_cndmask_b32_e32 v8, 0, v2, vcc
	v_or3_b32 v9, v9, v22, v23
	v_and_b32_e32 v6, 31, v160
	v_or3_b32 v179, v9, v24, v8
	v_bfe_u32 v8, v160, 3, 3
	v_add_lshl_u32 v181, v5, v6, 6
	v_or_b32_e32 v5, v5, v8
	v_lshlrev_b32_e32 v182, 6, v5
	v_or_b32_e32 v5, v3, v8
	v_lshlrev_b32_e32 v183, 6, v5
	v_lshlrev_b32_e32 v5, 4, v160
	v_and_b32_e32 v5, 0x70, v5
	s_movk_i32 s0, 0x240
	v_lshlrev_b32_e32 v2, 3, v7
	v_add_u32_e32 v5, v1, v5
	v_mad_u32_u24 v1, v7, s0, v1
	v_mul_u32_u24_e32 v7, 0x90, v8
	v_max_i32_e32 v8, 0xffffffd1, v160
	v_sub_u32_e32 v8, v8, v160
	v_add_u32_e32 v8, 0x1ff, v8
	v_lshrrev_b32_e32 v9, 9, v8
	v_xor_b32_e32 v180, 0x80, v4
	v_lshlrev_b32_e32 v4, 3, v160
	v_add_u32_e32 v9, 1, v9
	v_or_b32_e32 v3, v3, v0
	s_add_i32 s35, 0, 0x100
	v_readlane_b32 s0, v255, 16
	v_readlane_b32 s1, v255, 56
	v_and_b32_e32 v4, 56, v4
	v_lshlrev_b32_e32 v6, 1, v6
	v_and_b32_e32 v186, 0xfffffe, v9
	v_sub_u32_e32 v3, v3, v178
	s_add_u32 s50, s0, s1
	v_readlane_b32 s0, v255, 17
	v_bfe_u32 v177, v160, 4, 1
	v_add_u32_e32 v184, 0x200, v183
	v_add_u32_e32 v185, 0x400, v183
	v_cmp_lt_u32_e64 s[42:43], s82, v8
	v_lshl_add_u32 v187, v186, 9, v160
	v_add_u32_e32 v161, 0x200, v160
	v_cmp_ne_u32_e64 s[44:45], v9, v186
	v_lshl_add_u32 v188, v3, 2, 0
	v_lshlrev_b32_e32 v189, 2, v160
	s_addc_u32 s51, s0, s93
	v_lshlrev_b32_e32 v192, 1, v2
	v_lshlrev_b32_e32 v162, 1, v4
	v_add_u32_e32 v190, v5, v7
	v_add_u32_e32 v191, v1, v6
	v_lshlrev_b32_e32 v164, 1, v0
	v_readlane_b32 s52, v254, 29
	v_lshrrev_b32_e32 v191, 6, v195
	v_mul_u32_u24_e32 v191, 0x1200, v191
	v_bfe_u32 v198, v195, 5, 1
	v_mul_u32_u24_e32 v198, 0x240, v198
	v_add_u32_e32 v191, v191, v198
	v_bfe_u32 v198, v195, 2, 2
	v_mul_u32_u24_e32 v198, 0x90, v198
	v_add_u32_e32 v191, v191, v198
	v_bfe_u32 v198, v195, 4, 1
	v_lshl_add_u32 v191, v198, 5, v191
	v_and_b32_e32 v198, 3, v195
	v_lshl_add_u32 v191, v198, 3, v191
	s_branch .LBB0_562
